# planZ
# speedup vs baseline: 1.0036x; 1.0036x over previous
; #define PG8_STAGE(bufoff, gbase, voff) do { _Pragma("unroll") for (int _i = 0; _i < 2; ++_i) \
;         __builtin_amdgcn_global_load_lds((const unsigned*)((const char*)(gbase) + (voff)[_i]), (PG8_LAS unsigned*)(lds + (bufoff) + ldsw + _i * 8192), 16, 0, 0); } while (0)
; #define PG8_WAIT_V(n) asm volatile("s_waitcnt vmcnt(" #n ")" ::: "memory")
; #define PG8_BAR __builtin_amdgcn_s_barrier()
; template <class Epi, class Sched, bool ALIGN_EPI = false, bool SP2 = false, bool DUAL = false>
; __device__ __forceinline__ void gemm_phase(PG8_LAS unsigned char* lds, const Gemm g, const Sched& S, const Epi& E) {
;     const int tid = threadIdx.x, wid = __builtin_amdgcn_readfirstlane(tid >> 6), lane = tid & 63, wr = wid >> 2, wc = wid & 3, fr = lane & 15, fq = lane >> 4;
;     const int K = g.K, nt = K / BK;
;     unsigned voffA[2], voffB[2];
; #pragma unroll
;     for (int i = 0; i < 2; ++i) { int R, C; stage_rc(tid * 16 + i * 8192, R, C); const int Rb = Epi::PERM ? ((R & ~31) + perm32(R & 31)) : R;
;         voffA[i] = (unsigned)(R * K + C) * 2u; voffB[i] = (unsigned)(Rb * K + C) * 2u; }
;     const size_t kstep = (size_t)(BK * 2);
;     const size_t hstep = (size_t)HALF * K * 2;
;     const size_t tstep = 2 * hstep;
;     const unsigned ldsw = (unsigned)wid * 1024u;
;     const int aoff = lds_byte(wr * 64 + fr, fq * 8), boff = lds_byte(wc * 32 + fr, fq * 8);
;     ...
;     if constexpr (SP2) {
;         PG8_STAGE(PG8_SB(0, 0), cB, voffB); PG8_STAGE(PG8_SB(0, 1), cB + hstep, voffB); PG8_STAGE(PG8_SA(0, 0), cA, voffA); PG8_STAGE(PG8_SA(0, 1), cA + hstep, voffA);
;         if (wr == 1) PG8_BAR;
;         PG8_WAIT_V(2); PG8_BAR;
;         PG8_STAGE(PG8_SB(1, 0), cB + kstep, voffB); PG8_STAGE(PG8_SA(1, 0), cA + kstep, voffA); PG8_STAGE(PG8_SB(1, 1), cB + hstep + kstep, voffB);
;         PG8_WAIT_V(6); PG8_BAR;
.LBB0_242:
	v_and_b32_e32 v161, 15, v200
	v_lshlrev_b32_e32 v172, 1, v162
	v_lshlrev_b32_e32 v12, 6, v200
	s_movk_i32 s5, 0x3c0
	v_and_or_b32 v12, v12, s5, v172
	v_and_b32_e32 v13, 32, v78
	s_and_b32 s5, s1, 3
	s_lshl_b32 s23, s0, 6
	v_lshl_or_b32 v14, v161, 6, v172
	s_lshl_b32 s0, s0, 13
	v_bitop3_b32 v16, v14, s0, v13 bitop3:0xde
	s_lshl_b32 s0, s5, 12
	s_add_u32 s84, s58, 0x8100000
	s_addc_u32 s85, s59, 0
	v_bitop3_b32 v196, s0, v12, v13 bitop3:0xf6
	s_add_u32 s0, s58, 0x10200000
	s_addc_u32 s1, s59, 0
	v_writelane_b32 v254, s0, 58
	s_mov_b64 s[76:77], 0x80
	v_lshl_add_u64 v[6:7], v[6:7], 0, s[76:77]
	v_writelane_b32 v254, s1, 59
	s_add_u32 s0, s58, 0x18300000
	s_addc_u32 s1, s59, 0
	v_writelane_b32 v254, s0, 60
	s_waitcnt vmcnt(2)
	s_barrier
	v_lshl_add_u64 v[4:5], v[4:5], 0, s[76:77]
	v_writelane_b32 v254, s1, 61
	s_add_u32 s0, s58, 0x20400000
	s_addc_u32 s1, s59, 0
	v_writelane_b32 v254, s0, 62
	v_lshl_add_u64 v[0:1], v[0:1], 0, s[76:77]
	v_lshl_add_u64 v[12:13], s[58:59], 0, v[172:173]
	v_writelane_b32 v254, s1, 63
	s_add_u32 s0, s58, 0x28500000
	s_addc_u32 s1, s59, 0
	s_add_u32 s36, s56, 0x10200000
	s_addc_u32 s37, s57, 0
	s_add_u32 s96, s56, 0x10400000
	s_addc_u32 s97, s57, 0
	s_add_u32 s80, s56, 0x10640000
	s_addc_u32 s81, s57, 0
	s_add_u32 s94, s56, 0x10680000
	v_writelane_b32 v255, s0, 0
	s_addc_u32 s95, s57, 0
	v_lshlrev_b32_e32 v172, 2, v162
	v_writelane_b32 v255, s1, 1
	s_add_u32 s0, s56, 0x106c0000
	s_addc_u32 s1, s57, 0
	v_writelane_b32 v255, s0, 2
	s_add_i32 m0, s19, 0x18000
	s_ashr_i32 s26, s2, 31
	v_writelane_b32 v255, s1, 3
	v_cmp_lt_u32_e64 s[0:1], 13, v161
	global_load_lds_dwordx4 v[6:7], off
	s_nop 0
	v_writelane_b32 v255, s0, 4
	s_add_i32 m0, s19, 0x1a000
	s_add_i32 s27, s19, 0x8000
	v_writelane_b32 v255, s1, 5
	v_readlane_b32 s0, v254, 56
	s_ashr_i32 s24, s0, 31
	s_add_i32 s28, s19, 0xa000
	v_readlane_b32 s1, v254, 57
	s_mov_b32 s25, s0
	global_load_lds_dwordx4 v[4:5], off
	s_mov_b32 m0, s27
	s_add_u32 s0, s14, 0x80080
	global_load_lds_dwordx4 v[0:1], off
	v_lshl_add_u64 v[0:1], v[2:3], 0, s[76:77]
	s_mov_b32 m0, s28
	s_addc_u32 s1, s15, 0
	global_load_lds_dwordx4 v[0:1], off
	s_add_i32 m0, s19, 0x1c000
	v_lshl_add_u64 v[0:1], s[0:1], 0, v[166:167]
	global_load_lds_dwordx4 v[0:1], off
	v_lshl_add_u64 v[0:1], s[0:1], 0, v[170:171]
	s_add_i32 m0, s19, 0x1e000
	v_lshl_add_u64 v[14:15], s[58:59], 0, v[172:173]
	global_load_lds_dwordx4 v[0:1], off
	s_mov_b64 s[0:1], 0x3b668400
	v_lshl_add_u64 v[174:175], v[14:15], 0, s[0:1]
	s_mov_b64 s[0:1], 0x3b6a8400
	s_cmpk_lt_u32 s4, 0x100
	v_lshl_add_u64 v[176:177], v[14:15], 0, s[0:1]
	s_cselect_b64 s[38:39], -1, 0
	s_lshl_b32 s0, s5, 6
	s_lshl_b32 s78, s5, 7
	s_mov_b32 s3, s0
	v_or_b32_e32 v180, s0, v162
	v_lshl_add_u64 v[0:1], v[12:13], 0, s[78:79]
	s_mov_b64 s[0:1], 0x30600000
	s_cmp_lg_u64 s[56:57], 0
	v_lshl_or_b32 v178, s5, 5, v162
	v_lshl_add_u64 v[182:183], v[0:1], 0, s[0:1]
	s_cselect_b64 s[0:1], -1, 0
	v_writelane_b32 v255, s0, 6
	v_lshlrev_b32_e32 v172, 1, v178
	v_lshl_add_u64 v[0:1], s[58:59], 0, v[172:173]
	v_writelane_b32 v255, s1, 7
	s_mov_b64 s[0:1], 0x31620000
	v_lshl_add_u64 v[184:185], v[0:1], 0, s[0:1]
	v_lshlrev_b32_e32 v0, 9, v200
	v_and_b32_e32 v0, 0x70000, v0
	v_lshlrev_b32_e32 v1, 12, v10
	v_or3_b32 v0, v8, v0, v1
	v_add_u32_e32 v186, v0, v9
	v_lshlrev_b32_e32 v0, 5, v11
	v_and_b32_e32 v0, 0xf0000, v0
	s_waitcnt vmcnt(6)
	v_or3_b32 v0, v8, v0, v1
	v_add_u32_e32 v188, v0, v9
	s_add_i32 s31, 0, 0x10000
	s_add_i32 s34, 0, 0x14000
	v_mbcnt_lo_u32_b32 v0, -1, 0
	v_add_u32_e32 v197, -14, v161
	v_or_b32_e32 v198, 0x400, v161
	s_mov_b32 s29, 0x8000
	v_mov_b32_e32 v187, v173
	v_mov_b32_e32 v189, v173
	v_mov_b64_e32 v[190:191], 0x1931
	v_add_u32_e32 v199, s31, v196
	v_add_u32_e32 v202, s34, v196
	v_add_u32_e32 v203, 0, v16
	s_movk_i32 s35, 0x7fff
	s_movk_i32 s33, 0x77f
	v_mov_b32_e32 v204, 0x358637bd
	s_mov_b32 s30, 0x800000
	s_mov_b32 s78, 0x3e38aa3b
	v_mbcnt_hi_u32_b32 v205, -1, v0
	v_mov_b32_e32 v206, 0x400
	s_barrier
	s_branch .LBB0_245

;     __device__ bool next(int i, Unit& u) const { if (!base.next(i >> 1, u)) return false; u.sub = i & 1; return true; }
; #define PG8_STAGE(bufoff, gbase, voff) do { _Pragma("unroll") for (int _i = 0; _i < 2; ++_i) \
;         __builtin_amdgcn_global_load_lds((const unsigned*)((const char*)(gbase) + (voff)[_i]), (PG8_LAS unsigned*)(lds + (bufoff) + ldsw + _i * 8192), 16, 0, 0); } while (0)
; #define PG8_LDA(dst, b, h) do { _Pragma("unroll") for (int m = 0; m < 4; ++m) _Pragma("unroll") for (int k = 0; k < 2; ++k) dst[m][k] = *(const PG8_LAS bf16x8*)(lds + PG8_SA(b, h) + aoff + m * 2048 + k * 1024); } while (0)
; #define PG8_LDB(dst, b, h) do { _Pragma("unroll") for (int n = 0; n < 2; ++n) _Pragma("unroll") for (int k = 0; k < 2; ++k) dst[n][k] = *(const PG8_LAS bf16x8*)(lds + PG8_SB(b, h) + boff + n * 2048 + k * 1024); } while (0)
; #define PG8_WAIT_V(n) asm volatile("s_waitcnt vmcnt(" #n ")" ::: "memory")
; template <class Epi, class Sched, bool ALIGN_EPI = false, bool SP2 = false, bool DUAL = false>
; __device__ __forceinline__ void gemm_phase(PG8_LAS unsigned char* lds, const Gemm g, const Sched& S, const Epi& E) {
;     ...
;         const bool has_next = S.next(ui + 1, nxt);
;         const char* nA = has_next ? (const char*)((DUAL && nxt.sub) ? g.A2 : g.A) + (size_t)nxt.pm * tstep : cA; const char* nB = has_next ? (const char*)((DUAL && nxt.sub) ? g.Bt2 : g.Bt) + (size_t)nxt.pn * tstep : cB;
;         for (int t = 0; t < nt; t += 2) {
;             const bool last = (t == nt - 2);
;             const char* a1 = cA + (size_t)(t + 1) * kstep;
;             const char* a2 = last ? nA : cA + (size_t)(t + 2) * kstep; const char* b2 = last ? nB : cB + (size_t)(t + 2) * kstep;
;             const char* a3 = a2 + kstep; const char* b3 = b2 + kstep;
;             if (last && has_next) S.a_ready(nxt);
;             if constexpr (SP2) {
;             PG8_LDB(B0, 0, 0); PG8_LDB(B1, 0, 1); PG8_SCHED; PG8_LDA(At, 0, 0); PG8_STAGE(PG8_SA(1, 1), a1 + hstep, voffA);
;             PG8_WAIT_V(8); PG8_WAIT_L(0); PG8_BAR; PG8_MMA(0, 0, At, B0); PG8_MMA(0, 1, At, B1); PG8_BAR; PG8_SCHED;
;             PG8_LDA(At, 0, 1); PG8_STAGE(PG8_SB(0, 0), b2, voffB); PG8_STAGE(PG8_SB(0, 1), b2 + hstep, voffB); PG8_STAGE(PG8_SA(0, 0), a2, voffA);
;             PG8_WAIT_V(8); PG8_WAIT_L(0); PG8_BAR; PG8_MMA(1, 0, At, B0); PG8_MMA(1, 1, At, B1); PG8_BAR; PG8_SCHED;
.LBB0_251:
	s_ashr_i32 s87, s86, 31
	s_lshl_b64 s[16:17], s[86:87], 20
	s_add_u32 s92, s58, s16
	s_addc_u32 s93, s59, s17
	s_and_b64 s[16:17], s[4:5], exec
	s_cselect_b32 s7, s93, s11
	s_cselect_b32 s9, s92, s10
	s_ashr_i32 s1, s0, 31
	s_lshl_b64 s[16:17], s[0:1], 20
	s_add_u32 s88, s90, s16
	s_addc_u32 s89, s91, s17
	s_and_b64 s[16:17], s[4:5], exec
	s_cselect_b32 s1, s89, s15
	s_cselect_b32 s45, s88, s14
	s_add_u32 s10, s10, 0x80080
	s_addc_u32 s11, s11, 0
	s_add_u32 s46, s14, 0x100
	s_addc_u32 s47, s15, 0
	s_mov_b32 s48, -2
	ds_read_b128 v[80:83], v199
	ds_read_b128 v[84:87], v199 offset:1024
	ds_read_b128 v[88:91], v199 offset:2048
	ds_read_b128 v[92:95], v199 offset:3072
	ds_read_b128 v[144:147], v202
	ds_read_b128 v[148:151], v202 offset:1024
	ds_read_b128 v[152:155], v202 offset:2048
	ds_read_b128 v[156:159], v202 offset:3072
	s_add_u32 s14, s10, 0xfff80080
	s_addc_u32 s15, s11, -1
	s_cmp_eq_u32 s48, 28
	s_cselect_b32 s17, s7, s15
	s_cselect_b32 s16, s9, s14
	s_cselect_b32 s15, s1, s47
	s_cselect_b32 s14, s45, s46
	v_lshl_add_u64 v[192:193], s[10:11], 0, v[186:187]
	s_add_i32 m0, s19, 0xc000
	ds_read_b128 v[208:211], v203
	ds_read_b128 v[212:215], v203 offset:1024
	ds_read_b128 v[216:219], v203 offset:2048
	ds_read_b128 v[220:223], v203 offset:3072
	ds_read_b128 v[232:235], v203 offset:4096
	ds_read_b128 v[236:239], v203 offset:5120
	ds_read_b128 v[240:243], v203 offset:6144
	ds_read_b128 v[244:247], v203 offset:7168
	global_load_lds_dwordx4 v[192:193], off
	v_lshl_add_u64 v[192:193], s[10:11], 0, v[188:189]
	s_add_i32 m0, s19, 0xe000
	s_nop 0
	global_load_lds_dwordx4 v[192:193], off
	s_waitcnt vmcnt(8)
	s_waitcnt lgkmcnt(0)
	s_barrier
	s_setprio 1
	s_waitcnt lgkmcnt(0)
	v_mfma_f32_16x16x32_bf16 v[140:143], v[80:83], v[208:211], 0
	v_mfma_f32_16x16x32_bf16 v[132:135], v[88:91], v[208:211], 0
	v_mfma_f32_16x16x32_bf16 v[124:127], v[80:83], v[216:219], 0
	v_mfma_f32_16x16x32_bf16 v[120:123], v[88:91], v[216:219], 0
	v_mfma_f32_16x16x32_bf16 v[108:111], v[80:83], v[232:235], 0
	v_mfma_f32_16x16x32_bf16 v[104:107], v[88:91], v[232:235], 0
	v_mfma_f32_16x16x32_bf16 v[76:79], v[80:83], v[240:243], 0
	v_mfma_f32_16x16x32_bf16 v[72:75], v[88:91], v[240:243], 0
	v_mfma_f32_16x16x32_bf16 v[140:143], v[84:87], v[212:215], v[140:143]
	v_mfma_f32_16x16x32_bf16 v[132:135], v[92:95], v[212:215], v[132:135]
	v_mfma_f32_16x16x32_bf16 v[124:127], v[84:87], v[220:223], v[124:127]
	v_mfma_f32_16x16x32_bf16 v[120:123], v[92:95], v[220:223], v[120:123]
	v_mfma_f32_16x16x32_bf16 v[108:111], v[84:87], v[236:239], v[108:111]
	v_mfma_f32_16x16x32_bf16 v[104:107], v[92:95], v[236:239], v[104:107]
	v_mfma_f32_16x16x32_bf16 v[76:79], v[84:87], v[244:247], v[76:79]
	v_mfma_f32_16x16x32_bf16 v[72:75], v[92:95], v[244:247], v[72:75]
	s_setprio 0
	s_setprio 1
	v_mfma_f32_16x16x32_bf16 v[136:139], v[144:147], v[208:211], 0
	v_mfma_f32_16x16x32_bf16 v[128:131], v[152:155], v[208:211], 0
	v_mfma_f32_16x16x32_bf16 v[116:119], v[144:147], v[216:219], 0
	v_mfma_f32_16x16x32_bf16 v[112:115], v[152:155], v[216:219], 0
	v_mfma_f32_16x16x32_bf16 v[100:103], v[144:147], v[232:235], 0
	v_mfma_f32_16x16x32_bf16 v[96:99], v[152:155], v[232:235], 0
	v_mfma_f32_16x16x32_bf16 v[68:71], v[144:147], v[240:243], 0
	v_mfma_f32_16x16x32_bf16 v[64:67], v[152:155], v[240:243], 0
	v_mfma_f32_16x16x32_bf16 v[136:139], v[148:151], v[212:215], v[136:139]
	v_mfma_f32_16x16x32_bf16 v[128:131], v[156:159], v[212:215], v[128:131]
	v_mfma_f32_16x16x32_bf16 v[116:119], v[148:151], v[220:223], v[116:119]
	v_mfma_f32_16x16x32_bf16 v[112:115], v[156:159], v[220:223], v[112:115]
	v_mfma_f32_16x16x32_bf16 v[100:103], v[148:151], v[236:239], v[100:103]
	v_mfma_f32_16x16x32_bf16 v[96:99], v[156:159], v[236:239], v[96:99]
	v_mfma_f32_16x16x32_bf16 v[68:71], v[148:151], v[244:247], v[68:71]
	v_mfma_f32_16x16x32_bf16 v[64:67], v[156:159], v[244:247], v[64:67]
	s_setprio 0
	s_barrier
	s_add_i32 s49, s31, s18
	v_lshl_add_u64 v[192:193], s[14:15], 0, v[166:167]
	s_mov_b32 m0, s49
	ds_read_b128 v[208:211], v203 offset:16384
	ds_read_b128 v[212:215], v203 offset:17408
	ds_read_b128 v[216:219], v203 offset:18432
	ds_read_b128 v[220:223], v203 offset:19456
	ds_read_b128 v[232:235], v203 offset:20480
	ds_read_b128 v[236:239], v203 offset:21504
	ds_read_b128 v[240:243], v203 offset:22528
	ds_read_b128 v[244:247], v203 offset:23552
	global_load_lds_dwordx4 v[192:193], off
	s_add_i32 m0, s49, 0x2000
	s_add_u32 s50, s14, 0x80000
	v_lshl_add_u64 v[248:249], s[14:15], 0, v[170:171]
	s_addc_u32 s51, s15, 0
	s_add_i32 s49, s34, s18
	global_load_lds_dwordx4 v[248:249], off
	v_lshl_add_u64 v[250:251], s[50:51], 0, v[166:167]
	s_mov_b32 m0, s49
	v_lshl_add_u64 v[252:253], s[16:17], 0, v[168:169]
	global_load_lds_dwordx4 v[250:251], off
	v_lshl_add_u64 v[250:251], s[50:51], 0, v[170:171]
	s_add_i32 m0, s49, 0x2000
	s_nop 0
	global_load_lds_dwordx4 v[250:251], off
	v_lshl_add_u64 v[250:251], s[16:17], 0, v[164:165]
	s_mov_b32 m0, s19
	s_nop 0
	global_load_lds_dwordx4 v[250:251], off
	s_mov_b32 m0, s20
	s_nop 0
	global_load_lds_dwordx4 v[252:253], off
	s_waitcnt vmcnt(8)
	s_waitcnt lgkmcnt(0)
	s_barrier
; #define PG8_STAGE(bufoff, gbase, voff) do { _Pragma("unroll") for (int _i = 0; _i < 2; ++_i) \
;         __builtin_amdgcn_global_load_lds((const unsigned*)((const char*)(gbase) + (voff)[_i]), (PG8_LAS unsigned*)(lds + (bufoff) + ldsw + _i * 8192), 16, 0, 0); } while (0)
; #define PG8_LDA(dst, b, h) do { _Pragma("unroll") for (int m = 0; m < 4; ++m) _Pragma("unroll") for (int k = 0; k < 2; ++k) dst[m][k] = *(const PG8_LAS bf16x8*)(lds + PG8_SA(b, h) + aoff + m * 2048 + k * 1024); } while (0)
; #define PG8_LDB(dst, b, h) do { _Pragma("unroll") for (int n = 0; n < 2; ++n) _Pragma("unroll") for (int k = 0; k < 2; ++k) dst[n][k] = *(const PG8_LAS bf16x8*)(lds + PG8_SB(b, h) + boff + n * 2048 + k * 1024); } while (0)
; #define PG8_MMA(ai, bj, At, Bt) do { __builtin_amdgcn_s_setprio(1); _Pragma("unroll") for (int m = 0; m < 4; ++m) _Pragma("unroll") for (int n = 0; n < 2; ++n) _Pragma("unroll") for (int k = 0; k < 2; ++k) \
;         acc[ai][bj][m][n] = __builtin_amdgcn_mfma_f32_16x16x32_bf16(Bt[n][k], At[m][k], acc[ai][bj][m][n], 0, 0, 0); __builtin_amdgcn_s_setprio(0); } while (0)
; #define PG8_WAIT_V(n) asm volatile("s_waitcnt vmcnt(" #n ")" ::: "memory")
; #define PG8_WAIT_L(n) asm volatile("s_waitcnt lgkmcnt(" #n ")" ::: "memory")
; #define PG8_BAR __builtin_amdgcn_s_barrier()
; #define PG8_SCHED __builtin_amdgcn_sched_barrier(0)
; template <class Epi, class Sched, bool ALIGN_EPI = false, bool SP2 = false, bool DUAL = false>
; __device__ __forceinline__ void gemm_phase(PG8_LAS unsigned char* lds, const Gemm g, const Sched& S, const Epi& E) {
;     ...
;             PG8_WAIT_V(8); PG8_WAIT_L(0); PG8_BAR; PG8_MMA(1, 0, At, B0); PG8_MMA(1, 1, At, B1); PG8_BAR; PG8_SCHED;
;             PG8_LDB(B0, 1, 0); PG8_LDB(B1, 1, 1); PG8_SCHED; PG8_LDA(At, 1, 0); PG8_STAGE(PG8_SA(0, 1), a2 + hstep, voffA);
;             PG8_WAIT_V(8); PG8_WAIT_L(0); PG8_BAR; PG8_MMA(0, 0, At, B0); PG8_MMA(0, 1, At, B1); PG8_BAR; PG8_SCHED;
	s_setprio 1
	s_waitcnt lgkmcnt(0)
	v_mfma_f32_16x16x32_bf16 v[60:63], v[80:83], v[208:211], 0
	v_mfma_f32_16x16x32_bf16 v[56:59], v[88:91], v[208:211], 0
	v_mfma_f32_16x16x32_bf16 v[44:47], v[80:83], v[216:219], 0
	v_mfma_f32_16x16x32_bf16 v[40:43], v[88:91], v[216:219], 0
	v_mfma_f32_16x16x32_bf16 v[28:31], v[80:83], v[232:235], 0
	v_mfma_f32_16x16x32_bf16 v[24:27], v[88:91], v[232:235], 0
	v_mfma_f32_16x16x32_bf16 v[12:15], v[80:83], v[240:243], 0
	v_mfma_f32_16x16x32_bf16 v[8:11], v[88:91], v[240:243], 0
	v_mfma_f32_16x16x32_bf16 v[60:63], v[84:87], v[212:215], v[60:63]
	v_mfma_f32_16x16x32_bf16 v[56:59], v[92:95], v[212:215], v[56:59]
	v_mfma_f32_16x16x32_bf16 v[44:47], v[84:87], v[220:223], v[44:47]
	v_mfma_f32_16x16x32_bf16 v[40:43], v[92:95], v[220:223], v[40:43]
	v_mfma_f32_16x16x32_bf16 v[28:31], v[84:87], v[236:239], v[28:31]
	v_mfma_f32_16x16x32_bf16 v[24:27], v[92:95], v[236:239], v[24:27]
	v_mfma_f32_16x16x32_bf16 v[12:15], v[84:87], v[244:247], v[12:15]
	v_mfma_f32_16x16x32_bf16 v[8:11], v[92:95], v[244:247], v[8:11]
	s_setprio 0
	s_setprio 1
	v_mfma_f32_16x16x32_bf16 v[52:55], v[144:147], v[208:211], 0
	v_mfma_f32_16x16x32_bf16 v[48:51], v[152:155], v[208:211], 0
	v_mfma_f32_16x16x32_bf16 v[36:39], v[144:147], v[216:219], 0
	v_mfma_f32_16x16x32_bf16 v[32:35], v[152:155], v[216:219], 0
	v_mfma_f32_16x16x32_bf16 v[20:23], v[144:147], v[232:235], 0
	v_mfma_f32_16x16x32_bf16 v[16:19], v[152:155], v[232:235], 0
	v_mfma_f32_16x16x32_bf16 v[4:7], v[144:147], v[240:243], 0
	v_mfma_f32_16x16x32_bf16 v[0:3], v[152:155], v[240:243], 0
	v_mfma_f32_16x16x32_bf16 v[52:55], v[148:151], v[212:215], v[52:55]
	v_mfma_f32_16x16x32_bf16 v[48:51], v[156:159], v[212:215], v[48:51]
	v_mfma_f32_16x16x32_bf16 v[36:39], v[148:151], v[220:223], v[36:39]
	v_mfma_f32_16x16x32_bf16 v[32:35], v[156:159], v[220:223], v[32:35]
	v_mfma_f32_16x16x32_bf16 v[20:23], v[148:151], v[236:239], v[20:23]
	v_mfma_f32_16x16x32_bf16 v[16:19], v[156:159], v[236:239], v[16:19]
	v_mfma_f32_16x16x32_bf16 v[4:7], v[148:151], v[244:247], v[4:7]
	v_mfma_f32_16x16x32_bf16 v[0:3], v[156:159], v[244:247], v[0:3]
	s_setprio 0
	s_barrier
	s_add_i32 s49, 0, 0x18000
	s_add_i32 s50, 0, 0x1c000
	v_add_u32_e32 v92, s49, v196
	v_add_u32_e32 v156, s50, v196
	ds_read_b128 v[80:83], v92
	ds_read_b128 v[84:87], v92 offset:1024
	ds_read_b128 v[88:91], v92 offset:2048
	ds_read_b128 v[92:95], v92 offset:3072
	ds_read_b128 v[144:147], v156
	ds_read_b128 v[148:151], v156 offset:1024
	ds_read_b128 v[152:155], v156 offset:2048
	ds_read_b128 v[156:159], v156 offset:3072
	s_add_u32 s16, s16, 0x80000
	s_addc_u32 s17, s17, 0
	s_mov_b32 m0, s21
	v_lshl_add_u64 v[228:229], s[16:17], 0, v[164:165]
	ds_read_b128 v[208:211], v203 offset:32768
	ds_read_b128 v[212:215], v203 offset:33792
	ds_read_b128 v[216:219], v203 offset:34816
	ds_read_b128 v[220:223], v203 offset:35840
	ds_read_b128 v[232:235], v203 offset:36864
	ds_read_b128 v[236:239], v203 offset:37888
	ds_read_b128 v[240:243], v203 offset:38912
	ds_read_b128 v[244:247], v203 offset:39936
	global_load_lds_dwordx4 v[228:229], off
	v_lshl_add_u64 v[228:229], s[16:17], 0, v[168:169]
	s_mov_b32 m0, s22
	s_nop 0
	global_load_lds_dwordx4 v[228:229], off
	s_waitcnt vmcnt(8)
	s_waitcnt lgkmcnt(0)
	s_barrier
	s_setprio 1
	s_waitcnt lgkmcnt(0)
	v_mfma_f32_16x16x32_bf16 v[140:143], v[80:83], v[208:211], v[140:143]
	v_mfma_f32_16x16x32_bf16 v[132:135], v[88:91], v[208:211], v[132:135]
	v_mfma_f32_16x16x32_bf16 v[124:127], v[80:83], v[216:219], v[124:127]
	v_mfma_f32_16x16x32_bf16 v[120:123], v[88:91], v[216:219], v[120:123]
	v_mfma_f32_16x16x32_bf16 v[108:111], v[80:83], v[232:235], v[108:111]
	v_mfma_f32_16x16x32_bf16 v[104:107], v[88:91], v[232:235], v[104:107]
	v_mfma_f32_16x16x32_bf16 v[76:79], v[80:83], v[240:243], v[76:79]
	v_mfma_f32_16x16x32_bf16 v[72:75], v[88:91], v[240:243], v[72:75]
	v_mfma_f32_16x16x32_bf16 v[140:143], v[84:87], v[212:215], v[140:143]
	v_mfma_f32_16x16x32_bf16 v[132:135], v[92:95], v[212:215], v[132:135]
	v_mfma_f32_16x16x32_bf16 v[124:127], v[84:87], v[220:223], v[124:127]
	v_mfma_f32_16x16x32_bf16 v[120:123], v[92:95], v[220:223], v[120:123]
	v_mfma_f32_16x16x32_bf16 v[108:111], v[84:87], v[236:239], v[108:111]
	v_mfma_f32_16x16x32_bf16 v[104:107], v[92:95], v[236:239], v[104:107]
	v_mfma_f32_16x16x32_bf16 v[76:79], v[84:87], v[244:247], v[76:79]
	v_mfma_f32_16x16x32_bf16 v[72:75], v[92:95], v[244:247], v[72:75]
	s_setprio 0
	s_setprio 1
	v_mfma_f32_16x16x32_bf16 v[136:139], v[144:147], v[208:211], v[136:139]
	v_mfma_f32_16x16x32_bf16 v[128:131], v[152:155], v[208:211], v[128:131]
	v_mfma_f32_16x16x32_bf16 v[116:119], v[144:147], v[216:219], v[116:119]
	v_mfma_f32_16x16x32_bf16 v[112:115], v[152:155], v[216:219], v[112:115]
	v_mfma_f32_16x16x32_bf16 v[100:103], v[144:147], v[232:235], v[100:103]
	v_mfma_f32_16x16x32_bf16 v[96:99], v[152:155], v[232:235], v[96:99]
	v_mfma_f32_16x16x32_bf16 v[68:71], v[144:147], v[240:243], v[68:71]
	v_mfma_f32_16x16x32_bf16 v[64:67], v[152:155], v[240:243], v[64:67]
	v_mfma_f32_16x16x32_bf16 v[136:139], v[148:151], v[212:215], v[136:139]
	v_mfma_f32_16x16x32_bf16 v[128:131], v[156:159], v[212:215], v[128:131]
	v_mfma_f32_16x16x32_bf16 v[116:119], v[148:151], v[220:223], v[116:119]
	v_mfma_f32_16x16x32_bf16 v[112:115], v[156:159], v[220:223], v[112:115]
	v_mfma_f32_16x16x32_bf16 v[100:103], v[148:151], v[236:239], v[100:103]
	v_mfma_f32_16x16x32_bf16 v[96:99], v[156:159], v[236:239], v[96:99]
	v_mfma_f32_16x16x32_bf16 v[68:71], v[148:151], v[244:247], v[68:71]
	v_mfma_f32_16x16x32_bf16 v[64:67], v[156:159], v[244:247], v[64:67]
	s_setprio 0
	s_barrier
; #define PG8_STAGE(bufoff, gbase, voff) do { _Pragma("unroll") for (int _i = 0; _i < 2; ++_i) \
;         __builtin_amdgcn_global_load_lds((const unsigned*)((const char*)(gbase) + (voff)[_i]), (PG8_LAS unsigned*)(lds + (bufoff) + ldsw + _i * 8192), 16, 0, 0); } while (0)
; #define PG8_LDA(dst, b, h) do { _Pragma("unroll") for (int m = 0; m < 4; ++m) _Pragma("unroll") for (int k = 0; k < 2; ++k) dst[m][k] = *(const PG8_LAS bf16x8*)(lds + PG8_SA(b, h) + aoff + m * 2048 + k * 1024); } while (0)
; #define PG8_LDB(dst, b, h) do { _Pragma("unroll") for (int n = 0; n < 2; ++n) _Pragma("unroll") for (int k = 0; k < 2; ++k) dst[n][k] = *(const PG8_LAS bf16x8*)(lds + PG8_SB(b, h) + boff + n * 2048 + k * 1024); } while (0)
; #define PG8_MMA(ai, bj, At, Bt) do { __builtin_amdgcn_s_setprio(1); _Pragma("unroll") for (int m = 0; m < 4; ++m) _Pragma("unroll") for (int n = 0; n < 2; ++n) _Pragma("unroll") for (int k = 0; k < 2; ++k) \
;         acc[ai][bj][m][n] = __builtin_amdgcn_mfma_f32_16x16x32_bf16(Bt[n][k], At[m][k], acc[ai][bj][m][n], 0, 0, 0); __builtin_amdgcn_s_setprio(0); } while (0)
; #define PG8_BAR __builtin_amdgcn_s_barrier()
; template <class Epi, class Sched, bool ALIGN_EPI = false, bool SP2 = false, bool DUAL = false>
; __device__ __forceinline__ void gemm_phase(PG8_LAS unsigned char* lds, const Gemm g, const Sched& S, const Epi& E) {
;     ...
;             PG8_LDB(B0, 0, 0); PG8_LDB(B1, 0, 1); PG8_SCHED; PG8_LDA(At, 0, 0); PG8_STAGE(PG8_SA(1, 1), a1 + hstep, voffA);
;             PG8_WAIT_V(8); PG8_WAIT_L(0); PG8_BAR; PG8_MMA(0, 0, At, B0); PG8_MMA(0, 1, At, B1); PG8_BAR; PG8_SCHED;
;             PG8_LDA(At, 0, 1); PG8_STAGE(PG8_SB(0, 0), b2, voffB); PG8_STAGE(PG8_SB(0, 1), b2 + hstep, voffB); PG8_STAGE(PG8_SA(0, 0), a2, voffA);
;             PG8_WAIT_V(8); PG8_WAIT_L(0); PG8_BAR; PG8_MMA(1, 0, At, B0); PG8_MMA(1, 1, At, B1); PG8_BAR; PG8_SCHED;
;             PG8_LDB(B0, 1, 0); PG8_LDB(B1, 1, 1); PG8_SCHED; PG8_LDA(At, 1, 0); PG8_STAGE(PG8_SA(0, 1), a2 + hstep, voffA);
;             PG8_WAIT_V(8); PG8_WAIT_L(0); PG8_BAR; PG8_MMA(0, 0, At, B0); PG8_MMA(0, 1, At, B1); PG8_BAR; PG8_SCHED;
;             PG8_LDA(At, 1, 1); PG8_STAGE(PG8_SB(1, 0), b3, voffB); PG8_STAGE(PG8_SB(1, 1), b3 + hstep, voffB); PG8_STAGE(PG8_SA(1, 0), a3, voffA);
;             PG8_WAIT_V(8); PG8_WAIT_L(0); PG8_BAR; PG8_MMA(1, 0, At, B0); PG8_MMA(1, 1, At, B1); PG8_BAR; PG8_SCHED;
	s_add_i32 s16, s49, s18
	v_lshl_add_u64 v[192:193], v[192:193], 0, s[76:77]
	s_mov_b32 m0, s16
	ds_read_b128 v[208:211], v203 offset:49152
	ds_read_b128 v[212:215], v203 offset:50176
	ds_read_b128 v[216:219], v203 offset:51200
	ds_read_b128 v[220:223], v203 offset:52224
	ds_read_b128 v[232:235], v203 offset:53248
	ds_read_b128 v[236:239], v203 offset:54272
	ds_read_b128 v[240:243], v203 offset:55296
	ds_read_b128 v[244:247], v203 offset:56320
	global_load_lds_dwordx4 v[192:193], off
	s_add_i32 m0, s16, 0x2000
	s_add_u32 s14, s14, 0x80080
	v_lshl_add_u64 v[192:193], v[248:249], 0, s[76:77]
	s_addc_u32 s15, s15, 0
	s_add_i32 s16, s50, s18
	global_load_lds_dwordx4 v[192:193], off
	v_lshl_add_u64 v[192:193], s[14:15], 0, v[166:167]
	s_mov_b32 m0, s16
	s_nop 0
	global_load_lds_dwordx4 v[192:193], off
	v_lshl_add_u64 v[192:193], s[14:15], 0, v[170:171]
	s_add_i32 m0, s16, 0x2000
	s_nop 0
	global_load_lds_dwordx4 v[192:193], off
	v_lshl_add_u64 v[192:193], v[250:251], 0, s[76:77]
	s_mov_b32 m0, s27
	s_nop 0
	global_load_lds_dwordx4 v[192:193], off
	v_lshl_add_u64 v[192:193], v[252:253], 0, s[76:77]
	s_mov_b32 m0, s28
	s_nop 0
	global_load_lds_dwordx4 v[192:193], off
	s_waitcnt vmcnt(8)
	s_waitcnt lgkmcnt(0)
	s_barrier
	s_setprio 1
	s_waitcnt lgkmcnt(0)
	v_mfma_f32_16x16x32_bf16 v[60:63], v[80:83], v[208:211], v[60:63]
	v_mfma_f32_16x16x32_bf16 v[56:59], v[88:91], v[208:211], v[56:59]
	v_mfma_f32_16x16x32_bf16 v[44:47], v[80:83], v[216:219], v[44:47]
	v_mfma_f32_16x16x32_bf16 v[40:43], v[88:91], v[216:219], v[40:43]
	v_mfma_f32_16x16x32_bf16 v[28:31], v[80:83], v[232:235], v[28:31]
	v_mfma_f32_16x16x32_bf16 v[24:27], v[88:91], v[232:235], v[24:27]
	v_mfma_f32_16x16x32_bf16 v[12:15], v[80:83], v[240:243], v[12:15]
	v_mfma_f32_16x16x32_bf16 v[8:11], v[88:91], v[240:243], v[8:11]
	v_mfma_f32_16x16x32_bf16 v[60:63], v[84:87], v[212:215], v[60:63]
	v_mfma_f32_16x16x32_bf16 v[56:59], v[92:95], v[212:215], v[56:59]
	v_mfma_f32_16x16x32_bf16 v[44:47], v[84:87], v[220:223], v[44:47]
	v_mfma_f32_16x16x32_bf16 v[40:43], v[92:95], v[220:223], v[40:43]
	v_mfma_f32_16x16x32_bf16 v[28:31], v[84:87], v[236:239], v[28:31]
	v_mfma_f32_16x16x32_bf16 v[24:27], v[92:95], v[236:239], v[24:27]
	v_mfma_f32_16x16x32_bf16 v[12:15], v[84:87], v[244:247], v[12:15]
	v_mfma_f32_16x16x32_bf16 v[8:11], v[92:95], v[244:247], v[8:11]
	s_setprio 0
	s_setprio 1
	v_mfma_f32_16x16x32_bf16 v[52:55], v[144:147], v[208:211], v[52:55]
	v_mfma_f32_16x16x32_bf16 v[48:51], v[152:155], v[208:211], v[48:51]
	v_mfma_f32_16x16x32_bf16 v[36:39], v[144:147], v[216:219], v[36:39]
	v_mfma_f32_16x16x32_bf16 v[32:35], v[152:155], v[216:219], v[32:35]
	v_mfma_f32_16x16x32_bf16 v[20:23], v[144:147], v[232:235], v[20:23]
	v_mfma_f32_16x16x32_bf16 v[16:19], v[152:155], v[232:235], v[16:19]
	v_mfma_f32_16x16x32_bf16 v[4:7], v[144:147], v[240:243], v[4:7]
	v_mfma_f32_16x16x32_bf16 v[0:3], v[152:155], v[240:243], v[0:3]
	v_mfma_f32_16x16x32_bf16 v[52:55], v[148:151], v[212:215], v[52:55]
	v_mfma_f32_16x16x32_bf16 v[48:51], v[156:159], v[212:215], v[48:51]
	v_mfma_f32_16x16x32_bf16 v[36:39], v[148:151], v[220:223], v[36:39]
	v_mfma_f32_16x16x32_bf16 v[32:35], v[156:159], v[220:223], v[32:35]
	v_mfma_f32_16x16x32_bf16 v[20:23], v[148:151], v[236:239], v[20:23]
	v_mfma_f32_16x16x32_bf16 v[16:19], v[156:159], v[236:239], v[16:19]
	v_mfma_f32_16x16x32_bf16 v[4:7], v[148:151], v[244:247], v[4:7]
	v_mfma_f32_16x16x32_bf16 v[0:3], v[156:159], v[244:247], v[0:3]
	s_setprio 0
	s_barrier
	s_add_i32 s48, s48, 2
	s_add_u32 s10, s10, 0x100
	s_addc_u32 s11, s11, 0
	s_add_u32 s46, s46, 0x100
	s_addc_u32 s47, s47, 0
.LBB0_252:
	ds_read_b128 v[80:83], v199
	ds_read_b128 v[84:87], v199 offset:1024
	ds_read_b128 v[88:91], v199 offset:2048
	ds_read_b128 v[92:95], v199 offset:3072
	ds_read_b128 v[144:147], v202
	ds_read_b128 v[148:151], v202 offset:1024
	ds_read_b128 v[152:155], v202 offset:2048
	ds_read_b128 v[156:159], v202 offset:3072
	s_add_u32 s14, s10, 0xfff80080
	s_addc_u32 s15, s11, -1
	s_cmp_eq_u32 s48, 28
	s_cselect_b32 s17, s7, s15
	s_cselect_b32 s16, s9, s14
	s_cselect_b32 s15, s1, s47
	s_cselect_b32 s14, s45, s46
	v_lshl_add_u64 v[192:193], s[10:11], 0, v[186:187]
	s_add_i32 m0, s19, 0xc000
	ds_read_b128 v[208:211], v203
	ds_read_b128 v[212:215], v203 offset:1024
	ds_read_b128 v[216:219], v203 offset:2048
	ds_read_b128 v[220:223], v203 offset:3072
	ds_read_b128 v[232:235], v203 offset:4096
	ds_read_b128 v[236:239], v203 offset:5120
	ds_read_b128 v[240:243], v203 offset:6144
	ds_read_b128 v[244:247], v203 offset:7168
	global_load_lds_dwordx4 v[192:193], off
	v_lshl_add_u64 v[192:193], s[10:11], 0, v[188:189]
	s_add_i32 m0, s19, 0xe000
	s_nop 0
	global_load_lds_dwordx4 v[192:193], off
	s_waitcnt vmcnt(8)
	s_waitcnt lgkmcnt(0)
	s_barrier
; #define PG8_STAGE(bufoff, gbase, voff) do { _Pragma("unroll") for (int _i = 0; _i < 2; ++_i) \
;         __builtin_amdgcn_global_load_lds((const unsigned*)((const char*)(gbase) + (voff)[_i]), (PG8_LAS unsigned*)(lds + (bufoff) + ldsw + _i * 8192), 16, 0, 0); } while (0)
; #define PG8_LDA(dst, b, h) do { _Pragma("unroll") for (int m = 0; m < 4; ++m) _Pragma("unroll") for (int k = 0; k < 2; ++k) dst[m][k] = *(const PG8_LAS bf16x8*)(lds + PG8_SA(b, h) + aoff + m * 2048 + k * 1024); } while (0)
; #define PG8_MMA(ai, bj, At, Bt) do { __builtin_amdgcn_s_setprio(1); _Pragma("unroll") for (int m = 0; m < 4; ++m) _Pragma("unroll") for (int n = 0; n < 2; ++n) _Pragma("unroll") for (int k = 0; k < 2; ++k) \
;         acc[ai][bj][m][n] = __builtin_amdgcn_mfma_f32_16x16x32_bf16(Bt[n][k], At[m][k], acc[ai][bj][m][n], 0, 0, 0); __builtin_amdgcn_s_setprio(0); } while (0)
; #define PG8_WAIT_V(n) asm volatile("s_waitcnt vmcnt(" #n ")" ::: "memory")
; #define PG8_WAIT_L(n) asm volatile("s_waitcnt lgkmcnt(" #n ")" ::: "memory")
; #define PG8_BAR __builtin_amdgcn_s_barrier()
; #define PG8_SCHED __builtin_amdgcn_sched_barrier(0)
; template <class Epi, class Sched, bool ALIGN_EPI = false, bool SP2 = false, bool DUAL = false>
; __device__ __forceinline__ void gemm_phase(PG8_LAS unsigned char* lds, const Gemm g, const Sched& S, const Epi& E) {
;     ...
;             PG8_WAIT_V(8); PG8_WAIT_L(0); PG8_BAR; PG8_MMA(0, 0, At, B0); PG8_MMA(0, 1, At, B1); PG8_BAR; PG8_SCHED;
;             PG8_LDA(At, 0, 1); PG8_STAGE(PG8_SB(0, 0), b2, voffB); PG8_STAGE(PG8_SB(0, 1), b2 + hstep, voffB); PG8_STAGE(PG8_SA(0, 0), a2, voffA);
;             PG8_WAIT_V(8); PG8_WAIT_L(0); PG8_BAR; PG8_MMA(1, 0, At, B0); PG8_MMA(1, 1, At, B1); PG8_BAR; PG8_SCHED;
	s_setprio 1
	s_waitcnt lgkmcnt(0)
	v_mfma_f32_16x16x32_bf16 v[140:143], v[80:83], v[208:211], v[140:143]
	v_mfma_f32_16x16x32_bf16 v[132:135], v[88:91], v[208:211], v[132:135]
	v_mfma_f32_16x16x32_bf16 v[124:127], v[80:83], v[216:219], v[124:127]
	v_mfma_f32_16x16x32_bf16 v[120:123], v[88:91], v[216:219], v[120:123]
	v_mfma_f32_16x16x32_bf16 v[108:111], v[80:83], v[232:235], v[108:111]
	v_mfma_f32_16x16x32_bf16 v[104:107], v[88:91], v[232:235], v[104:107]
	v_mfma_f32_16x16x32_bf16 v[76:79], v[80:83], v[240:243], v[76:79]
	v_mfma_f32_16x16x32_bf16 v[72:75], v[88:91], v[240:243], v[72:75]
	v_mfma_f32_16x16x32_bf16 v[140:143], v[84:87], v[212:215], v[140:143]
	v_mfma_f32_16x16x32_bf16 v[132:135], v[92:95], v[212:215], v[132:135]
	v_mfma_f32_16x16x32_bf16 v[124:127], v[84:87], v[220:223], v[124:127]
	v_mfma_f32_16x16x32_bf16 v[120:123], v[92:95], v[220:223], v[120:123]
	v_mfma_f32_16x16x32_bf16 v[108:111], v[84:87], v[236:239], v[108:111]
	v_mfma_f32_16x16x32_bf16 v[104:107], v[92:95], v[236:239], v[104:107]
	v_mfma_f32_16x16x32_bf16 v[76:79], v[84:87], v[244:247], v[76:79]
	v_mfma_f32_16x16x32_bf16 v[72:75], v[92:95], v[244:247], v[72:75]
	s_setprio 0
	s_setprio 1
	v_mfma_f32_16x16x32_bf16 v[136:139], v[144:147], v[208:211], v[136:139]
	v_mfma_f32_16x16x32_bf16 v[128:131], v[152:155], v[208:211], v[128:131]
	v_mfma_f32_16x16x32_bf16 v[116:119], v[144:147], v[216:219], v[116:119]
	v_mfma_f32_16x16x32_bf16 v[112:115], v[152:155], v[216:219], v[112:115]
	v_mfma_f32_16x16x32_bf16 v[100:103], v[144:147], v[232:235], v[100:103]
	v_mfma_f32_16x16x32_bf16 v[96:99], v[152:155], v[232:235], v[96:99]
	v_mfma_f32_16x16x32_bf16 v[68:71], v[144:147], v[240:243], v[68:71]
	v_mfma_f32_16x16x32_bf16 v[64:67], v[152:155], v[240:243], v[64:67]
	v_mfma_f32_16x16x32_bf16 v[136:139], v[148:151], v[212:215], v[136:139]
	v_mfma_f32_16x16x32_bf16 v[128:131], v[156:159], v[212:215], v[128:131]
	v_mfma_f32_16x16x32_bf16 v[116:119], v[148:151], v[220:223], v[116:119]
	v_mfma_f32_16x16x32_bf16 v[112:115], v[156:159], v[220:223], v[112:115]
	v_mfma_f32_16x16x32_bf16 v[100:103], v[148:151], v[236:239], v[100:103]
	v_mfma_f32_16x16x32_bf16 v[96:99], v[156:159], v[236:239], v[96:99]
	v_mfma_f32_16x16x32_bf16 v[68:71], v[148:151], v[244:247], v[68:71]
	v_mfma_f32_16x16x32_bf16 v[64:67], v[156:159], v[244:247], v[64:67]
	s_setprio 0
	s_barrier
	s_add_i32 s49, s31, s18
	v_lshl_add_u64 v[192:193], s[14:15], 0, v[166:167]
	s_mov_b32 m0, s49
	ds_read_b128 v[208:211], v203 offset:16384
	ds_read_b128 v[212:215], v203 offset:17408
	ds_read_b128 v[216:219], v203 offset:18432
	ds_read_b128 v[220:223], v203 offset:19456
	ds_read_b128 v[232:235], v203 offset:20480
	ds_read_b128 v[236:239], v203 offset:21504
	ds_read_b128 v[240:243], v203 offset:22528
	ds_read_b128 v[244:247], v203 offset:23552
	global_load_lds_dwordx4 v[192:193], off
	s_add_i32 m0, s49, 0x2000
	s_add_u32 s50, s14, 0x80000
	v_lshl_add_u64 v[248:249], s[14:15], 0, v[170:171]
	s_addc_u32 s51, s15, 0
	s_add_i32 s49, s34, s18
	global_load_lds_dwordx4 v[248:249], off
	v_lshl_add_u64 v[250:251], s[50:51], 0, v[166:167]
	s_mov_b32 m0, s49
	v_lshl_add_u64 v[252:253], s[16:17], 0, v[168:169]
	global_load_lds_dwordx4 v[250:251], off
	v_lshl_add_u64 v[250:251], s[50:51], 0, v[170:171]
	s_add_i32 m0, s49, 0x2000
	s_nop 0
	global_load_lds_dwordx4 v[250:251], off
	v_lshl_add_u64 v[250:251], s[16:17], 0, v[164:165]
	s_mov_b32 m0, s19
	s_nop 0
	global_load_lds_dwordx4 v[250:251], off
	s_mov_b32 m0, s20
	s_nop 0
	global_load_lds_dwordx4 v[252:253], off
	s_waitcnt vmcnt(8)
	s_waitcnt lgkmcnt(0)
	s_barrier
	s_setprio 1
	s_waitcnt lgkmcnt(0)
	v_mfma_f32_16x16x32_bf16 v[60:63], v[80:83], v[208:211], v[60:63]
	v_mfma_f32_16x16x32_bf16 v[56:59], v[88:91], v[208:211], v[56:59]
	v_mfma_f32_16x16x32_bf16 v[44:47], v[80:83], v[216:219], v[44:47]
	v_mfma_f32_16x16x32_bf16 v[40:43], v[88:91], v[216:219], v[40:43]
	v_mfma_f32_16x16x32_bf16 v[28:31], v[80:83], v[232:235], v[28:31]
	v_mfma_f32_16x16x32_bf16 v[24:27], v[88:91], v[232:235], v[24:27]
	v_mfma_f32_16x16x32_bf16 v[12:15], v[80:83], v[240:243], v[12:15]
	v_mfma_f32_16x16x32_bf16 v[8:11], v[88:91], v[240:243], v[8:11]
	v_mfma_f32_16x16x32_bf16 v[60:63], v[84:87], v[212:215], v[60:63]
	v_mfma_f32_16x16x32_bf16 v[56:59], v[92:95], v[212:215], v[56:59]
	v_mfma_f32_16x16x32_bf16 v[44:47], v[84:87], v[220:223], v[44:47]
	v_mfma_f32_16x16x32_bf16 v[40:43], v[92:95], v[220:223], v[40:43]
	v_mfma_f32_16x16x32_bf16 v[28:31], v[84:87], v[236:239], v[28:31]
	v_mfma_f32_16x16x32_bf16 v[24:27], v[92:95], v[236:239], v[24:27]
	v_mfma_f32_16x16x32_bf16 v[12:15], v[84:87], v[244:247], v[12:15]
	v_mfma_f32_16x16x32_bf16 v[8:11], v[92:95], v[244:247], v[8:11]
	s_setprio 0
	s_setprio 1
	v_mfma_f32_16x16x32_bf16 v[52:55], v[144:147], v[208:211], v[52:55]
	v_mfma_f32_16x16x32_bf16 v[48:51], v[152:155], v[208:211], v[48:51]
	v_mfma_f32_16x16x32_bf16 v[36:39], v[144:147], v[216:219], v[36:39]
	v_mfma_f32_16x16x32_bf16 v[32:35], v[152:155], v[216:219], v[32:35]
	v_mfma_f32_16x16x32_bf16 v[20:23], v[144:147], v[232:235], v[20:23]
	v_mfma_f32_16x16x32_bf16 v[16:19], v[152:155], v[232:235], v[16:19]
	v_mfma_f32_16x16x32_bf16 v[4:7], v[144:147], v[240:243], v[4:7]
	v_mfma_f32_16x16x32_bf16 v[0:3], v[152:155], v[240:243], v[0:3]
	v_mfma_f32_16x16x32_bf16 v[52:55], v[148:151], v[212:215], v[52:55]
	v_mfma_f32_16x16x32_bf16 v[48:51], v[156:159], v[212:215], v[48:51]
	v_mfma_f32_16x16x32_bf16 v[36:39], v[148:151], v[220:223], v[36:39]
	v_mfma_f32_16x16x32_bf16 v[32:35], v[156:159], v[220:223], v[32:35]
	v_mfma_f32_16x16x32_bf16 v[20:23], v[148:151], v[236:239], v[20:23]
	v_mfma_f32_16x16x32_bf16 v[16:19], v[156:159], v[236:239], v[16:19]
	v_mfma_f32_16x16x32_bf16 v[4:7], v[148:151], v[244:247], v[4:7]
	v_mfma_f32_16x16x32_bf16 v[0:3], v[156:159], v[244:247], v[0:3]
	s_setprio 0
	s_barrier
; #define PG8_STAGE(bufoff, gbase, voff) do { _Pragma("unroll") for (int _i = 0; _i < 2; ++_i) \
;         __builtin_amdgcn_global_load_lds((const unsigned*)((const char*)(gbase) + (voff)[_i]), (PG8_LAS unsigned*)(lds + (bufoff) + ldsw + _i * 8192), 16, 0, 0); } while (0)
; #define PG8_LDA(dst, b, h) do { _Pragma("unroll") for (int m = 0; m < 4; ++m) _Pragma("unroll") for (int k = 0; k < 2; ++k) dst[m][k] = *(const PG8_LAS bf16x8*)(lds + PG8_SA(b, h) + aoff + m * 2048 + k * 1024); } while (0)
; #define PG8_LDB(dst, b, h) do { _Pragma("unroll") for (int n = 0; n < 2; ++n) _Pragma("unroll") for (int k = 0; k < 2; ++k) dst[n][k] = *(const PG8_LAS bf16x8*)(lds + PG8_SB(b, h) + boff + n * 2048 + k * 1024); } while (0)
; #define PG8_MMA(ai, bj, At, Bt) do { __builtin_amdgcn_s_setprio(1); _Pragma("unroll") for (int m = 0; m < 4; ++m) _Pragma("unroll") for (int n = 0; n < 2; ++n) _Pragma("unroll") for (int k = 0; k < 2; ++k) \
;         acc[ai][bj][m][n] = __builtin_amdgcn_mfma_f32_16x16x32_bf16(Bt[n][k], At[m][k], acc[ai][bj][m][n], 0, 0, 0); __builtin_amdgcn_s_setprio(0); } while (0)
; #define PG8_WAIT_V(n) asm volatile("s_waitcnt vmcnt(" #n ")" ::: "memory")
; #define PG8_WAIT_L(n) asm volatile("s_waitcnt lgkmcnt(" #n ")" ::: "memory")
; #define PG8_BAR __builtin_amdgcn_s_barrier()
; #define PG8_SCHED __builtin_amdgcn_sched_barrier(0)
; template <class Epi, class Sched, bool ALIGN_EPI = false, bool SP2 = false, bool DUAL = false>
; __device__ __forceinline__ void gemm_phase(PG8_LAS unsigned char* lds, const Gemm g, const Sched& S, const Epi& E) {
;     ...
;             PG8_LDB(B0, 1, 0); PG8_LDB(B1, 1, 1); PG8_SCHED; PG8_LDA(At, 1, 0); PG8_STAGE(PG8_SA(0, 1), a2 + hstep, voffA);
;             PG8_WAIT_V(8); PG8_WAIT_L(0); PG8_BAR; PG8_MMA(0, 0, At, B0); PG8_MMA(0, 1, At, B1); PG8_BAR; PG8_SCHED;
	s_add_i32 s49, 0, 0x18000
	s_add_i32 s50, 0, 0x1c000
	v_add_u32_e32 v92, s49, v196
	v_add_u32_e32 v156, s50, v196
	ds_read_b128 v[80:83], v92
	ds_read_b128 v[84:87], v92 offset:1024
	ds_read_b128 v[88:91], v92 offset:2048
	ds_read_b128 v[92:95], v92 offset:3072
	ds_read_b128 v[144:147], v156
	ds_read_b128 v[148:151], v156 offset:1024
	ds_read_b128 v[152:155], v156 offset:2048
	ds_read_b128 v[156:159], v156 offset:3072
	s_add_u32 s16, s16, 0x80000
	s_addc_u32 s17, s17, 0
	s_mov_b32 m0, s21
	v_lshl_add_u64 v[228:229], s[16:17], 0, v[164:165]
	ds_read_b128 v[208:211], v203 offset:32768
	ds_read_b128 v[212:215], v203 offset:33792
	ds_read_b128 v[216:219], v203 offset:34816
	ds_read_b128 v[220:223], v203 offset:35840
	ds_read_b128 v[232:235], v203 offset:36864
	ds_read_b128 v[236:239], v203 offset:37888
	ds_read_b128 v[240:243], v203 offset:38912
	ds_read_b128 v[244:247], v203 offset:39936
	global_load_lds_dwordx4 v[228:229], off
	v_lshl_add_u64 v[228:229], s[16:17], 0, v[168:169]
	s_mov_b32 m0, s22
	s_nop 0
	global_load_lds_dwordx4 v[228:229], off
	s_waitcnt vmcnt(8)
	s_waitcnt lgkmcnt(0)
	s_barrier
	s_setprio 1
	s_waitcnt lgkmcnt(0)
	v_mfma_f32_16x16x32_bf16 v[140:143], v[80:83], v[208:211], v[140:143]
	v_mfma_f32_16x16x32_bf16 v[132:135], v[88:91], v[208:211], v[132:135]
	v_mfma_f32_16x16x32_bf16 v[124:127], v[80:83], v[216:219], v[124:127]
	v_mfma_f32_16x16x32_bf16 v[120:123], v[88:91], v[216:219], v[120:123]
	v_mfma_f32_16x16x32_bf16 v[108:111], v[80:83], v[232:235], v[108:111]
	v_mfma_f32_16x16x32_bf16 v[104:107], v[88:91], v[232:235], v[104:107]
	v_mfma_f32_16x16x32_bf16 v[76:79], v[80:83], v[240:243], v[76:79]
	v_mfma_f32_16x16x32_bf16 v[72:75], v[88:91], v[240:243], v[72:75]
	v_mfma_f32_16x16x32_bf16 v[140:143], v[84:87], v[212:215], v[140:143]
	v_mfma_f32_16x16x32_bf16 v[132:135], v[92:95], v[212:215], v[132:135]
	v_mfma_f32_16x16x32_bf16 v[124:127], v[84:87], v[220:223], v[124:127]
	v_mfma_f32_16x16x32_bf16 v[120:123], v[92:95], v[220:223], v[120:123]
	v_mfma_f32_16x16x32_bf16 v[108:111], v[84:87], v[236:239], v[108:111]
	v_mfma_f32_16x16x32_bf16 v[104:107], v[92:95], v[236:239], v[104:107]
	v_mfma_f32_16x16x32_bf16 v[76:79], v[84:87], v[244:247], v[76:79]
	v_mfma_f32_16x16x32_bf16 v[72:75], v[92:95], v[244:247], v[72:75]
	s_setprio 0
	s_setprio 1
	v_mfma_f32_16x16x32_bf16 v[136:139], v[144:147], v[208:211], v[136:139]
	v_mfma_f32_16x16x32_bf16 v[128:131], v[152:155], v[208:211], v[128:131]
	v_mfma_f32_16x16x32_bf16 v[116:119], v[144:147], v[216:219], v[116:119]
	v_mfma_f32_16x16x32_bf16 v[112:115], v[152:155], v[216:219], v[112:115]
	v_mfma_f32_16x16x32_bf16 v[100:103], v[144:147], v[232:235], v[100:103]
	v_mfma_f32_16x16x32_bf16 v[96:99], v[152:155], v[232:235], v[96:99]
	v_mfma_f32_16x16x32_bf16 v[68:71], v[144:147], v[240:243], v[68:71]
	v_mfma_f32_16x16x32_bf16 v[64:67], v[152:155], v[240:243], v[64:67]
	v_mfma_f32_16x16x32_bf16 v[136:139], v[148:151], v[212:215], v[136:139]
	v_mfma_f32_16x16x32_bf16 v[128:131], v[156:159], v[212:215], v[128:131]
	v_mfma_f32_16x16x32_bf16 v[116:119], v[148:151], v[220:223], v[116:119]
	v_mfma_f32_16x16x32_bf16 v[112:115], v[156:159], v[220:223], v[112:115]
	v_mfma_f32_16x16x32_bf16 v[100:103], v[148:151], v[236:239], v[100:103]
	v_mfma_f32_16x16x32_bf16 v[96:99], v[156:159], v[236:239], v[96:99]
	v_mfma_f32_16x16x32_bf16 v[68:71], v[148:151], v[244:247], v[68:71]
	v_mfma_f32_16x16x32_bf16 v[64:67], v[156:159], v[244:247], v[64:67]
	s_setprio 0
	s_barrier
; #define PG8_STAGE(bufoff, gbase, voff) do { _Pragma("unroll") for (int _i = 0; _i < 2; ++_i) \
;         __builtin_amdgcn_global_load_lds((const unsigned*)((const char*)(gbase) + (voff)[_i]), (PG8_LAS unsigned*)(lds + (bufoff) + ldsw + _i * 8192), 16, 0, 0); } while (0)
; #define PG8_LDA(dst, b, h) do { _Pragma("unroll") for (int m = 0; m < 4; ++m) _Pragma("unroll") for (int k = 0; k < 2; ++k) dst[m][k] = *(const PG8_LAS bf16x8*)(lds + PG8_SA(b, h) + aoff + m * 2048 + k * 1024); } while (0)
; #define PG8_MMA(ai, bj, At, Bt) do { __builtin_amdgcn_s_setprio(1); _Pragma("unroll") for (int m = 0; m < 4; ++m) _Pragma("unroll") for (int n = 0; n < 2; ++n) _Pragma("unroll") for (int k = 0; k < 2; ++k) \
;         acc[ai][bj][m][n] = __builtin_amdgcn_mfma_f32_16x16x32_bf16(Bt[n][k], At[m][k], acc[ai][bj][m][n], 0, 0, 0); __builtin_amdgcn_s_setprio(0); } while (0)
; #define PG8_WAIT_V(n) asm volatile("s_waitcnt vmcnt(" #n ")" ::: "memory")
; #define PG8_WAIT_L(n) asm volatile("s_waitcnt lgkmcnt(" #n ")" ::: "memory")
; #define PG8_BAR __builtin_amdgcn_s_barrier()
; #define PG8_SCHED __builtin_amdgcn_sched_barrier(0)
; template <class Epi, class Sched, bool ALIGN_EPI = false, bool SP2 = false, bool DUAL = false>
; __device__ __forceinline__ void gemm_phase(PG8_LAS unsigned char* lds, const Gemm g, const Sched& S, const Epi& E) {
;     ...
;             PG8_LDA(At, 1, 1); PG8_STAGE(PG8_SB(1, 0), b3, voffB); PG8_STAGE(PG8_SB(1, 1), b3 + hstep, voffB); PG8_STAGE(PG8_SA(1, 0), a3, voffA);
;             PG8_WAIT_V(8); PG8_WAIT_L(0); PG8_BAR; PG8_MMA(1, 0, At, B0); PG8_MMA(1, 1, At, B1); PG8_BAR; PG8_SCHED;
;     ...
;         if constexpr (ALIGN_EPI) { if (wr == 0) PG8_BAR; }
	s_add_i32 s16, s49, s18
	v_lshl_add_u64 v[192:193], v[192:193], 0, s[76:77]
	s_mov_b32 m0, s16
	ds_read_b128 v[208:211], v203 offset:49152
	ds_read_b128 v[212:215], v203 offset:50176
	ds_read_b128 v[216:219], v203 offset:51200
	ds_read_b128 v[220:223], v203 offset:52224
	ds_read_b128 v[232:235], v203 offset:53248
	ds_read_b128 v[236:239], v203 offset:54272
	ds_read_b128 v[240:243], v203 offset:55296
	ds_read_b128 v[244:247], v203 offset:56320
	global_load_lds_dwordx4 v[192:193], off
	s_add_i32 m0, s16, 0x2000
	s_add_u32 s14, s14, 0x80080
	v_lshl_add_u64 v[192:193], v[248:249], 0, s[76:77]
	s_addc_u32 s15, s15, 0
	s_add_i32 s16, s50, s18
	global_load_lds_dwordx4 v[192:193], off
	v_lshl_add_u64 v[192:193], s[14:15], 0, v[166:167]
	s_mov_b32 m0, s16
	s_nop 0
	global_load_lds_dwordx4 v[192:193], off
	v_lshl_add_u64 v[192:193], s[14:15], 0, v[170:171]
	s_add_i32 m0, s16, 0x2000
	s_nop 0
	global_load_lds_dwordx4 v[192:193], off
	v_lshl_add_u64 v[192:193], v[250:251], 0, s[76:77]
	s_mov_b32 m0, s27
	s_nop 0
	global_load_lds_dwordx4 v[192:193], off
	v_lshl_add_u64 v[192:193], v[252:253], 0, s[76:77]
	s_mov_b32 m0, s28
	s_nop 0
	global_load_lds_dwordx4 v[192:193], off
	s_waitcnt vmcnt(8)
	s_waitcnt lgkmcnt(0)
	s_barrier
	s_setprio 1
	s_waitcnt lgkmcnt(0)
	v_mfma_f32_16x16x32_bf16 v[60:63], v[80:83], v[208:211], v[60:63]
	v_mfma_f32_16x16x32_bf16 v[56:59], v[88:91], v[208:211], v[56:59]
	v_mfma_f32_16x16x32_bf16 v[44:47], v[80:83], v[216:219], v[44:47]
	v_mfma_f32_16x16x32_bf16 v[40:43], v[88:91], v[216:219], v[40:43]
	v_mfma_f32_16x16x32_bf16 v[28:31], v[80:83], v[232:235], v[28:31]
	v_mfma_f32_16x16x32_bf16 v[24:27], v[88:91], v[232:235], v[24:27]
	v_mfma_f32_16x16x32_bf16 v[12:15], v[80:83], v[240:243], v[12:15]
	v_mfma_f32_16x16x32_bf16 v[8:11], v[88:91], v[240:243], v[8:11]
	v_mfma_f32_16x16x32_bf16 v[60:63], v[84:87], v[212:215], v[60:63]
	v_mfma_f32_16x16x32_bf16 v[56:59], v[92:95], v[212:215], v[56:59]
	v_mfma_f32_16x16x32_bf16 v[44:47], v[84:87], v[220:223], v[44:47]
	v_mfma_f32_16x16x32_bf16 v[40:43], v[92:95], v[220:223], v[40:43]
	v_mfma_f32_16x16x32_bf16 v[28:31], v[84:87], v[236:239], v[28:31]
	v_mfma_f32_16x16x32_bf16 v[24:27], v[92:95], v[236:239], v[24:27]
	v_mfma_f32_16x16x32_bf16 v[12:15], v[84:87], v[244:247], v[12:15]
	v_mfma_f32_16x16x32_bf16 v[8:11], v[92:95], v[244:247], v[8:11]
	s_setprio 0
	s_setprio 1
	v_mfma_f32_16x16x32_bf16 v[52:55], v[144:147], v[208:211], v[52:55]
	v_mfma_f32_16x16x32_bf16 v[48:51], v[152:155], v[208:211], v[48:51]
	v_mfma_f32_16x16x32_bf16 v[36:39], v[144:147], v[216:219], v[36:39]
	v_mfma_f32_16x16x32_bf16 v[32:35], v[152:155], v[216:219], v[32:35]
	v_mfma_f32_16x16x32_bf16 v[20:23], v[144:147], v[232:235], v[20:23]
	v_mfma_f32_16x16x32_bf16 v[16:19], v[152:155], v[232:235], v[16:19]
	v_mfma_f32_16x16x32_bf16 v[4:7], v[144:147], v[240:243], v[4:7]
	v_mfma_f32_16x16x32_bf16 v[0:3], v[152:155], v[240:243], v[0:3]
	v_mfma_f32_16x16x32_bf16 v[52:55], v[148:151], v[212:215], v[52:55]
	v_mfma_f32_16x16x32_bf16 v[48:51], v[156:159], v[212:215], v[48:51]
	v_mfma_f32_16x16x32_bf16 v[36:39], v[148:151], v[220:223], v[36:39]
	v_mfma_f32_16x16x32_bf16 v[32:35], v[156:159], v[220:223], v[32:35]
	v_mfma_f32_16x16x32_bf16 v[20:23], v[148:151], v[236:239], v[20:23]
	v_mfma_f32_16x16x32_bf16 v[16:19], v[156:159], v[236:239], v[16:19]
	v_mfma_f32_16x16x32_bf16 v[4:7], v[148:151], v[244:247], v[4:7]
	v_mfma_f32_16x16x32_bf16 v[0:3], v[156:159], v[244:247], v[0:3]
	s_setprio 0
	s_barrier
	s_add_i32 s48, s48, 2
	s_add_u32 s10, s10, 0x100
	s_addc_u32 s11, s11, 0
	s_add_u32 s46, s46, 0x100
	s_addc_u32 s47, s47, 0
	s_cmp_gt_u32 s48, 29
	s_cbranch_scc0 .LBB0_252
	s_and_b64 vcc, exec, s[38:39]
	s_cbranch_vccz .LBB0_255
	s_barrier

; #define PG8_STAGE(bufoff, gbase, voff) do { _Pragma("unroll") for (int _i = 0; _i < 2; ++_i) \
;         __builtin_amdgcn_global_load_lds((const unsigned*)((const char*)(gbase) + (voff)[_i]), (PG8_LAS unsigned*)(lds + (bufoff) + ldsw + _i * 8192), 16, 0, 0); } while (0)
; #define PG8_WAIT_V(n) asm volatile("s_waitcnt vmcnt(" #n ")" ::: "memory")
; #define PG8_BAR __builtin_amdgcn_s_barrier()
; template <class Epi, class Sched, bool ALIGN_EPI = false, bool SP2 = false, bool DUAL = false>
; __device__ __forceinline__ void gemm_phase(PG8_LAS unsigned char* lds, const Gemm g, const Sched& S, const Epi& E) {
;     ...
;     f32x4 acc[2][2][4][2];
; #pragma unroll
;     for (int a = 0; a < 2; ++a)
; #pragma unroll
;         for (int b = 0; b < 2; ++b)
; #pragma unroll
;             for (int m = 0; m < 4; ++m)
; #pragma unroll
;                 for (int n = 0; n < 2; ++n) acc[a][b][m][n] = (f32x4){0.f, 0.f, 0.f, 0.f};
;     bf16x8 At[4][2], B0[2][2], B1[2][2];
;     const char* cA = (const char*)((DUAL && cur.sub) ? g.A2 : g.A) + (size_t)cur.pm * tstep; const char* cB = (const char*)((DUAL && cur.sub) ? g.Bt2 : g.Bt) + (size_t)cur.pn * tstep;
;     S.a_ready(cur);
;     if constexpr (SP2) {
;         PG8_STAGE(PG8_SB(0, 0), cB, voffB); PG8_STAGE(PG8_SB(0, 1), cB + hstep, voffB); PG8_STAGE(PG8_SA(0, 0), cA, voffA); PG8_STAGE(PG8_SA(0, 1), cA + hstep, voffA);
;         if (wr == 1) PG8_BAR;
;         PG8_WAIT_V(2); PG8_BAR;
;         PG8_STAGE(PG8_SB(1, 0), cB + kstep, voffB); PG8_STAGE(PG8_SA(1, 0), cA + kstep, voffA); PG8_STAGE(PG8_SB(1, 1), cB + hstep + kstep, voffB);
;         PG8_WAIT_V(6); PG8_BAR;
.LBB0_795:
	s_lshl_b32 s19, s19, 5
	s_mov_b64 s[36:37], 0x80
	s_and_b32 s19, s19, 0x60
	s_add_i32 m0, s28, 0x18000
	v_lshl_add_u64 v[8:9], v[8:9], 0, s[36:37]
	s_lshl_b32 s40, s5, 13
	s_lshl_b32 s41, s19, 7
	s_waitcnt vmcnt(2)
	s_barrier
	global_load_lds_dwordx4 v[8:9], off
	v_lshl_add_u64 v[4:5], v[4:5], 0, s[36:37]
	s_add_i32 m0, s28, 0x1a000
	s_add_i32 s42, s28, 0x8000
	s_add_i32 s43, s28, 0xa000
	global_load_lds_dwordx4 v[4:5], off
	v_lshl_add_u64 v[2:3], v[2:3], 0, s[36:37]
	s_mov_b32 m0, s42
	s_add_u32 s38, s16, 0x80080
	global_load_lds_dwordx4 v[2:3], off
	v_lshl_add_u64 v[2:3], v[6:7], 0, s[36:37]
	s_mov_b32 m0, s43
	s_addc_u32 s39, s17, 0
	global_load_lds_dwordx4 v[2:3], off
	s_add_i32 m0, s28, 0x1c000
	v_lshl_add_u64 v[2:3], s[38:39], 0, v[186:187]
	global_load_lds_dwordx4 v[2:3], off
	v_lshl_add_u64 v[2:3], s[38:39], 0, v[190:191]
	s_add_i32 m0, s28, 0x1e000
	s_sext_i32_i8 s48, s4
	global_load_lds_dwordx4 v[2:3], off
	v_lshlrev_b32_e32 v2, 6, v231
	v_lshlrev_b32_e32 v3, 1, v12
	s_movk_i32 s4, 0x3c0
	v_lshlrev_b32_e32 v4, 2, v231
	v_and_or_b32 v2, v2, s4, v3
	v_and_b32_e32 v4, 32, v4
	v_bitop3_b32 v4, v2, s40, v4 bitop3:0xde
	v_lshlrev_b32_e32 v2, 6, v200
	v_and_or_b32 v2, v2, s4, v3
	v_and_b32_e32 v3, 32, v233
	v_bitop3_b32 v235, s41, v2, v3 bitop3:0xf6
	v_lshlrev_b32_e32 v2, 9, v200
	v_and_b32_e32 v2, 0x70000, v2
	v_lshlrev_b32_e32 v3, 12, v11
	v_or3_b32 v2, v1, v2, v3
	v_add_u32_e32 v192, v2, v10
	v_lshlrev_b32_e32 v2, 5, v13
	v_and_b32_e32 v2, 0xf0000, v2
	s_waitcnt vmcnt(6)
	v_or3_b32 v1, v1, v2, v3
	v_mov_b32_e32 v2, v0
	v_mov_b32_e32 v3, v0
	s_cmpk_lt_u32 s18, 0x100
	v_or_b32_e32 v236, s19, v12
	v_add_u32_e32 v194, v1, v10
	v_mov_b32_e32 v1, v0
	v_add_u32_e32 v237, 0, v4
	v_mov_b64_e32 v[6:7], v[2:3]
	v_mov_b64_e32 v[10:11], v[2:3]
	v_mov_b64_e32 v[14:15], v[2:3]
	v_mov_b64_e32 v[18:19], v[2:3]
	v_mov_b64_e32 v[22:23], v[2:3]
	v_mov_b64_e32 v[26:27], v[2:3]
	v_mov_b64_e32 v[30:31], v[2:3]
	v_mov_b64_e32 v[34:35], v[2:3]
	v_mov_b64_e32 v[38:39], v[2:3]
	v_mov_b64_e32 v[42:43], v[2:3]
	v_mov_b64_e32 v[46:47], v[2:3]
	v_mov_b64_e32 v[50:51], v[2:3]
	v_mov_b64_e32 v[54:55], v[2:3]
	v_mov_b64_e32 v[58:59], v[2:3]
	v_mov_b64_e32 v[62:63], v[2:3]
	v_mov_b64_e32 v[66:67], v[2:3]
	v_mov_b64_e32 v[70:71], v[2:3]
	v_mov_b64_e32 v[74:75], v[2:3]
	v_mov_b64_e32 v[78:79], v[2:3]
	v_mov_b64_e32 v[82:83], v[2:3]
	v_mov_b64_e32 v[86:87], v[2:3]
	v_mov_b64_e32 v[90:91], v[2:3]
	v_mov_b64_e32 v[94:95], v[2:3]
	v_mov_b64_e32 v[98:99], v[2:3]
	v_mov_b64_e32 v[102:103], v[2:3]
	v_mov_b64_e32 v[106:107], v[2:3]
	v_mov_b64_e32 v[110:111], v[2:3]
	v_mov_b64_e32 v[114:115], v[2:3]
	v_mov_b64_e32 v[118:119], v[2:3]
	v_mov_b64_e32 v[122:123], v[2:3]
	v_mov_b64_e32 v[126:127], v[2:3]
	v_mov_b64_e32 v[130:131], v[2:3]
	v_lshl_or_b32 v234, s5, 6, v231
	s_cselect_b64 s[38:39], -1, 0
	v_mov_b32_e32 v193, v0
	v_mov_b32_e32 v195, v0
	s_mov_b32 s49, 0
	v_mov_b64_e32 v[196:197], 0x400
	v_mov_b64_e32 v[198:199], 0x3ff
	s_add_i32 s44, 0, 0x10000
	s_add_i32 s45, 0, 0x14000
	s_mov_b64 s[40:41], 0x90000
	s_mov_b64 s[60:61], 0xa0000
	s_mov_b64 s[62:63], 0xb0000
	v_mov_b64_e32 v[4:5], v[0:1]
	v_mov_b64_e32 v[8:9], v[0:1]
	v_mov_b64_e32 v[12:13], v[0:1]
	v_mov_b64_e32 v[16:17], v[0:1]
	v_mov_b64_e32 v[20:21], v[0:1]
	v_mov_b64_e32 v[24:25], v[0:1]
	v_mov_b64_e32 v[28:29], v[0:1]
	v_mov_b64_e32 v[32:33], v[0:1]
	v_mov_b64_e32 v[36:37], v[0:1]
	v_mov_b64_e32 v[40:41], v[0:1]
	v_mov_b64_e32 v[44:45], v[0:1]
	v_mov_b64_e32 v[48:49], v[0:1]
	v_mov_b64_e32 v[52:53], v[0:1]
	v_mov_b64_e32 v[56:57], v[0:1]
	v_mov_b64_e32 v[60:61], v[0:1]
	v_mov_b64_e32 v[64:65], v[0:1]
	v_mov_b64_e32 v[68:69], v[0:1]
	v_mov_b64_e32 v[72:73], v[0:1]
	v_mov_b64_e32 v[76:77], v[0:1]
	v_mov_b64_e32 v[80:81], v[0:1]
	v_mov_b64_e32 v[84:85], v[0:1]
	v_mov_b64_e32 v[88:89], v[0:1]
	v_mov_b64_e32 v[92:93], v[0:1]
	v_mov_b64_e32 v[96:97], v[0:1]
	v_mov_b64_e32 v[100:101], v[0:1]
	v_mov_b64_e32 v[104:105], v[0:1]
	v_mov_b64_e32 v[108:109], v[0:1]
	v_mov_b64_e32 v[112:113], v[0:1]
	v_mov_b64_e32 v[116:117], v[0:1]
	v_mov_b64_e32 v[120:121], v[0:1]
	v_mov_b64_e32 v[124:125], v[0:1]
	v_mov_b64_e32 v[128:129], v[0:1]
	s_mov_b32 s46, 0
	s_barrier
	s_branch .LBB0_798

; #define PG8_STAGE(bufoff, gbase, voff) do { _Pragma("unroll") for (int _i = 0; _i < 2; ++_i) \
;         __builtin_amdgcn_global_load_lds((const unsigned*)((const char*)(gbase) + (voff)[_i]), (PG8_LAS unsigned*)(lds + (bufoff) + ldsw + _i * 8192), 16, 0, 0); } while (0)
; #define PG8_LDA(dst, b, h) do { _Pragma("unroll") for (int m = 0; m < 4; ++m) _Pragma("unroll") for (int k = 0; k < 2; ++k) dst[m][k] = *(const PG8_LAS bf16x8*)(lds + PG8_SA(b, h) + aoff + m * 2048 + k * 1024); } while (0)
; #define PG8_LDB(dst, b, h) do { _Pragma("unroll") for (int n = 0; n < 2; ++n) _Pragma("unroll") for (int k = 0; k < 2; ++k) dst[n][k] = *(const PG8_LAS bf16x8*)(lds + PG8_SB(b, h) + boff + n * 2048 + k * 1024); } while (0)
; #define PG8_MMA(ai, bj, At, Bt) do { __builtin_amdgcn_s_setprio(1); _Pragma("unroll") for (int m = 0; m < 4; ++m) _Pragma("unroll") for (int n = 0; n < 2; ++n) _Pragma("unroll") for (int k = 0; k < 2; ++k) \
;         acc[ai][bj][m][n] = __builtin_amdgcn_mfma_f32_16x16x32_bf16(Bt[n][k], At[m][k], acc[ai][bj][m][n], 0, 0, 0); __builtin_amdgcn_s_setprio(0); } while (0)
; #define PG8_WAIT_V(n) asm volatile("s_waitcnt vmcnt(" #n ")" ::: "memory")
; #define PG8_WAIT_L(n) asm volatile("s_waitcnt lgkmcnt(" #n ")" ::: "memory")
; #define PG8_BAR __builtin_amdgcn_s_barrier()
; #define PG8_SCHED __builtin_amdgcn_sched_barrier(0)
; template <class Epi, class Sched, bool ALIGN_EPI = false, bool SP2 = false, bool DUAL = false>
; __device__ __forceinline__ void gemm_phase(PG8_LAS unsigned char* lds, const Gemm g, const Sched& S, const Epi& E) {
;     ...
;             PG8_LDB(B0, 0, 0); PG8_LDB(B1, 0, 1); PG8_SCHED; PG8_LDA(At, 0, 0); PG8_STAGE(PG8_SA(1, 1), a1 + hstep, voffA);
;             PG8_WAIT_V(8); PG8_WAIT_L(0); PG8_BAR; PG8_MMA(0, 0, At, B0); PG8_MMA(0, 1, At, B1); PG8_BAR; PG8_SCHED;
;             PG8_LDA(At, 0, 1); PG8_STAGE(PG8_SB(0, 0), b2, voffB); PG8_STAGE(PG8_SB(0, 1), b2 + hstep, voffB); PG8_STAGE(PG8_SA(0, 0), a2, voffA);
;             PG8_WAIT_V(8); PG8_WAIT_L(0); PG8_BAR; PG8_MMA(1, 0, At, B0); PG8_MMA(1, 1, At, B1); PG8_BAR; PG8_SCHED;
.LBB0_805:
	v_add_u32_e32 v1, s44, v235
	ds_read_b128 v[132:135], v1
	ds_read_b128 v[136:139], v1 offset:1024
	ds_read_b128 v[140:143], v1 offset:2048
	ds_read_b128 v[144:147], v1 offset:3072
	v_add_u32_e32 v1, s45, v235
	ds_read_b128 v[148:151], v1
	ds_read_b128 v[152:155], v1 offset:1024
	ds_read_b128 v[156:159], v1 offset:2048
	ds_read_b128 v[160:163], v1 offset:3072
	s_add_u32 s16, s14, 0xfff80080
	s_addc_u32 s17, s15, -1
	s_cmp_eq_u32 s75, 28
	s_cselect_b32 s19, s50, s17
	s_cselect_b32 s18, s51, s16
	s_cselect_b32 s17, s65, s73
	s_cselect_b32 s16, s67, s72
	v_lshl_add_u64 v[2:3], s[14:15], 0, v[192:193]
	s_add_i32 m0, s28, 0xc000
	ds_read_b128 v[164:167], v237
	ds_read_b128 v[168:171], v237 offset:1024
	ds_read_b128 v[172:175], v237 offset:2048
	ds_read_b128 v[176:179], v237 offset:3072
	ds_read_b128 v[180:183], v237 offset:4096
	ds_read_b128 v[202:205], v237 offset:5120
	ds_read_b128 v[206:209], v237 offset:6144
	ds_read_b128 v[210:213], v237 offset:7168
	global_load_lds_dwordx4 v[2:3], off
	v_lshl_add_u64 v[2:3], s[14:15], 0, v[194:195]
	s_add_i32 m0, s28, 0xe000
	s_nop 0
	global_load_lds_dwordx4 v[2:3], off
	s_waitcnt vmcnt(8)
	s_waitcnt lgkmcnt(0)
	s_barrier
	s_setprio 1
	s_waitcnt lgkmcnt(0)
	v_mfma_f32_16x16x32_bf16 v[128:131], v[132:135], v[164:167], v[128:131]
	v_mfma_f32_16x16x32_bf16 v[124:127], v[140:143], v[164:167], v[124:127]
	v_mfma_f32_16x16x32_bf16 v[120:123], v[132:135], v[172:175], v[120:123]
	v_mfma_f32_16x16x32_bf16 v[116:119], v[140:143], v[172:175], v[116:119]
	v_mfma_f32_16x16x32_bf16 v[112:115], v[132:135], v[180:183], v[112:115]
	v_mfma_f32_16x16x32_bf16 v[108:111], v[140:143], v[180:183], v[108:111]
	v_mfma_f32_16x16x32_bf16 v[104:107], v[132:135], v[206:209], v[104:107]
	v_mfma_f32_16x16x32_bf16 v[100:103], v[140:143], v[206:209], v[100:103]
	v_mfma_f32_16x16x32_bf16 v[128:131], v[136:139], v[168:171], v[128:131]
	v_mfma_f32_16x16x32_bf16 v[124:127], v[144:147], v[168:171], v[124:127]
	v_mfma_f32_16x16x32_bf16 v[120:123], v[136:139], v[176:179], v[120:123]
	v_mfma_f32_16x16x32_bf16 v[116:119], v[144:147], v[176:179], v[116:119]
	v_mfma_f32_16x16x32_bf16 v[112:115], v[136:139], v[202:205], v[112:115]
	v_mfma_f32_16x16x32_bf16 v[108:111], v[144:147], v[202:205], v[108:111]
	v_mfma_f32_16x16x32_bf16 v[104:107], v[136:139], v[210:213], v[104:107]
	v_mfma_f32_16x16x32_bf16 v[100:103], v[144:147], v[210:213], v[100:103]
	s_setprio 0
	s_setprio 1
	v_mfma_f32_16x16x32_bf16 v[96:99], v[148:151], v[164:167], v[96:99]
	v_mfma_f32_16x16x32_bf16 v[92:95], v[156:159], v[164:167], v[92:95]
	v_mfma_f32_16x16x32_bf16 v[88:91], v[148:151], v[172:175], v[88:91]
	v_mfma_f32_16x16x32_bf16 v[84:87], v[156:159], v[172:175], v[84:87]
	v_mfma_f32_16x16x32_bf16 v[80:83], v[148:151], v[180:183], v[80:83]
	v_mfma_f32_16x16x32_bf16 v[76:79], v[156:159], v[180:183], v[76:79]
	v_mfma_f32_16x16x32_bf16 v[72:75], v[148:151], v[206:209], v[72:75]
	v_mfma_f32_16x16x32_bf16 v[68:71], v[156:159], v[206:209], v[68:71]
	v_mfma_f32_16x16x32_bf16 v[96:99], v[152:155], v[168:171], v[96:99]
	v_mfma_f32_16x16x32_bf16 v[92:95], v[160:163], v[168:171], v[92:95]
	v_mfma_f32_16x16x32_bf16 v[88:91], v[152:155], v[176:179], v[88:91]
	v_mfma_f32_16x16x32_bf16 v[84:87], v[160:163], v[176:179], v[84:87]
	v_mfma_f32_16x16x32_bf16 v[80:83], v[152:155], v[202:205], v[80:83]
	v_mfma_f32_16x16x32_bf16 v[76:79], v[160:163], v[202:205], v[76:79]
	v_mfma_f32_16x16x32_bf16 v[72:75], v[152:155], v[210:213], v[72:75]
	v_mfma_f32_16x16x32_bf16 v[68:71], v[160:163], v[210:213], v[68:71]
	s_setprio 0
	s_barrier
	s_add_i32 s76, s44, s27
	v_lshl_add_u64 v[214:215], s[16:17], 0, v[186:187]
	s_mov_b32 m0, s76
	ds_read_b128 v[164:167], v237 offset:16384
	ds_read_b128 v[168:171], v237 offset:17408
	ds_read_b128 v[172:175], v237 offset:18432
	ds_read_b128 v[176:179], v237 offset:19456
	ds_read_b128 v[180:183], v237 offset:20480
	ds_read_b128 v[202:205], v237 offset:21504
	ds_read_b128 v[206:209], v237 offset:22528
	ds_read_b128 v[210:213], v237 offset:23552
	global_load_lds_dwordx4 v[214:215], off
	s_add_i32 m0, s76, 0x2000
	s_add_u32 s76, s16, 0x80000
	v_lshl_add_u64 v[216:217], s[16:17], 0, v[190:191]
	s_addc_u32 s77, s17, 0
	s_add_i32 s78, s45, s27
	global_load_lds_dwordx4 v[216:217], off
	v_lshl_add_u64 v[2:3], s[76:77], 0, v[186:187]
	s_mov_b32 m0, s78
	v_lshl_add_u64 v[218:219], s[18:19], 0, v[184:185]
	global_load_lds_dwordx4 v[2:3], off
	v_lshl_add_u64 v[2:3], s[76:77], 0, v[190:191]
	s_add_i32 m0, s78, 0x2000
	v_lshl_add_u64 v[220:221], s[18:19], 0, v[188:189]
	global_load_lds_dwordx4 v[2:3], off
	s_mov_b32 m0, s28
	s_nop 0
	global_load_lds_dwordx4 v[218:219], off
	s_mov_b32 m0, s29
	s_nop 0
	global_load_lds_dwordx4 v[220:221], off
	s_waitcnt vmcnt(8)
	s_waitcnt lgkmcnt(0)
	s_barrier
; #define PG8_STAGE(bufoff, gbase, voff) do { _Pragma("unroll") for (int _i = 0; _i < 2; ++_i) \
;         __builtin_amdgcn_global_load_lds((const unsigned*)((const char*)(gbase) + (voff)[_i]), (PG8_LAS unsigned*)(lds + (bufoff) + ldsw + _i * 8192), 16, 0, 0); } while (0)
; #define PG8_LDA(dst, b, h) do { _Pragma("unroll") for (int m = 0; m < 4; ++m) _Pragma("unroll") for (int k = 0; k < 2; ++k) dst[m][k] = *(const PG8_LAS bf16x8*)(lds + PG8_SA(b, h) + aoff + m * 2048 + k * 1024); } while (0)
; #define PG8_LDB(dst, b, h) do { _Pragma("unroll") for (int n = 0; n < 2; ++n) _Pragma("unroll") for (int k = 0; k < 2; ++k) dst[n][k] = *(const PG8_LAS bf16x8*)(lds + PG8_SB(b, h) + boff + n * 2048 + k * 1024); } while (0)
; #define PG8_MMA(ai, bj, At, Bt) do { __builtin_amdgcn_s_setprio(1); _Pragma("unroll") for (int m = 0; m < 4; ++m) _Pragma("unroll") for (int n = 0; n < 2; ++n) _Pragma("unroll") for (int k = 0; k < 2; ++k) \
;         acc[ai][bj][m][n] = __builtin_amdgcn_mfma_f32_16x16x32_bf16(Bt[n][k], At[m][k], acc[ai][bj][m][n], 0, 0, 0); __builtin_amdgcn_s_setprio(0); } while (0)
; #define PG8_WAIT_V(n) asm volatile("s_waitcnt vmcnt(" #n ")" ::: "memory")
; #define PG8_WAIT_L(n) asm volatile("s_waitcnt lgkmcnt(" #n ")" ::: "memory")
; #define PG8_BAR __builtin_amdgcn_s_barrier()
; #define PG8_SCHED __builtin_amdgcn_sched_barrier(0)
; template <class Epi, class Sched, bool ALIGN_EPI = false, bool SP2 = false, bool DUAL = false>
; __device__ __forceinline__ void gemm_phase(PG8_LAS unsigned char* lds, const Gemm g, const Sched& S, const Epi& E) {
;     ...
;             PG8_WAIT_V(8); PG8_WAIT_L(0); PG8_BAR; PG8_MMA(1, 0, At, B0); PG8_MMA(1, 1, At, B1); PG8_BAR; PG8_SCHED;
;             PG8_LDB(B0, 1, 0); PG8_LDB(B1, 1, 1); PG8_SCHED; PG8_LDA(At, 1, 0); PG8_STAGE(PG8_SA(0, 1), a2 + hstep, voffA);
;             PG8_WAIT_V(8); PG8_WAIT_L(0); PG8_BAR; PG8_MMA(0, 0, At, B0); PG8_MMA(0, 1, At, B1); PG8_BAR; PG8_SCHED;
	s_setprio 1
	s_waitcnt lgkmcnt(0)
	v_mfma_f32_16x16x32_bf16 v[64:67], v[132:135], v[164:167], v[64:67]
	v_mfma_f32_16x16x32_bf16 v[60:63], v[140:143], v[164:167], v[60:63]
	v_mfma_f32_16x16x32_bf16 v[56:59], v[132:135], v[172:175], v[56:59]
	v_mfma_f32_16x16x32_bf16 v[52:55], v[140:143], v[172:175], v[52:55]
	v_mfma_f32_16x16x32_bf16 v[48:51], v[132:135], v[180:183], v[48:51]
	v_mfma_f32_16x16x32_bf16 v[44:47], v[140:143], v[180:183], v[44:47]
	v_mfma_f32_16x16x32_bf16 v[40:43], v[132:135], v[206:209], v[40:43]
	v_mfma_f32_16x16x32_bf16 v[36:39], v[140:143], v[206:209], v[36:39]
	v_mfma_f32_16x16x32_bf16 v[64:67], v[136:139], v[168:171], v[64:67]
	v_mfma_f32_16x16x32_bf16 v[60:63], v[144:147], v[168:171], v[60:63]
	v_mfma_f32_16x16x32_bf16 v[56:59], v[136:139], v[176:179], v[56:59]
	v_mfma_f32_16x16x32_bf16 v[52:55], v[144:147], v[176:179], v[52:55]
	v_mfma_f32_16x16x32_bf16 v[48:51], v[136:139], v[202:205], v[48:51]
	v_mfma_f32_16x16x32_bf16 v[44:47], v[144:147], v[202:205], v[44:47]
	v_mfma_f32_16x16x32_bf16 v[40:43], v[136:139], v[210:213], v[40:43]
	v_mfma_f32_16x16x32_bf16 v[36:39], v[144:147], v[210:213], v[36:39]
	s_setprio 0
	s_setprio 1
	v_mfma_f32_16x16x32_bf16 v[32:35], v[148:151], v[164:167], v[32:35]
	v_mfma_f32_16x16x32_bf16 v[28:31], v[156:159], v[164:167], v[28:31]
	v_mfma_f32_16x16x32_bf16 v[24:27], v[148:151], v[172:175], v[24:27]
	v_mfma_f32_16x16x32_bf16 v[20:23], v[156:159], v[172:175], v[20:23]
	v_mfma_f32_16x16x32_bf16 v[16:19], v[148:151], v[180:183], v[16:19]
	v_mfma_f32_16x16x32_bf16 v[12:15], v[156:159], v[180:183], v[12:15]
	v_mfma_f32_16x16x32_bf16 v[8:11], v[148:151], v[206:209], v[8:11]
	v_mfma_f32_16x16x32_bf16 v[2:5], v[156:159], v[206:209], v[4:7]
	v_mfma_f32_16x16x32_bf16 v[32:35], v[152:155], v[168:171], v[32:35]
	v_mfma_f32_16x16x32_bf16 v[28:31], v[160:163], v[168:171], v[28:31]
	v_mfma_f32_16x16x32_bf16 v[24:27], v[152:155], v[176:179], v[24:27]
	v_mfma_f32_16x16x32_bf16 v[20:23], v[160:163], v[176:179], v[20:23]
	v_mfma_f32_16x16x32_bf16 v[16:19], v[152:155], v[202:205], v[16:19]
	v_mfma_f32_16x16x32_bf16 v[12:15], v[160:163], v[202:205], v[12:15]
	v_mfma_f32_16x16x32_bf16 v[8:11], v[152:155], v[210:213], v[8:11]
	v_mfma_f32_16x16x32_bf16 v[2:5], v[160:163], v[210:213], v[2:5]
	s_setprio 0
	s_barrier
	s_add_i32 s76, 0, 0x18000
	v_add_u32_e32 v1, s76, v235
	s_add_i32 s77, 0, 0x1c000
	ds_read_b128 v[132:135], v1
	ds_read_b128 v[136:139], v1 offset:1024
	ds_read_b128 v[140:143], v1 offset:2048
	ds_read_b128 v[144:147], v1 offset:3072
	v_add_u32_e32 v1, s77, v235
	ds_read_b128 v[148:151], v1
	ds_read_b128 v[152:155], v1 offset:1024
	ds_read_b128 v[156:159], v1 offset:2048
	ds_read_b128 v[160:163], v1 offset:3072
	s_add_u32 s18, s18, 0x80000
	s_addc_u32 s19, s19, 0
	s_mov_b32 m0, s34
	v_lshl_add_u64 v[6:7], s[18:19], 0, v[184:185]
	ds_read_b128 v[164:167], v237 offset:32768
	ds_read_b128 v[168:171], v237 offset:33792
	ds_read_b128 v[172:175], v237 offset:34816
	ds_read_b128 v[176:179], v237 offset:35840
	ds_read_b128 v[180:183], v237 offset:36864
	ds_read_b128 v[202:205], v237 offset:37888
	ds_read_b128 v[206:209], v237 offset:38912
	ds_read_b128 v[210:213], v237 offset:39936
	global_load_lds_dwordx4 v[6:7], off
	v_lshl_add_u64 v[6:7], s[18:19], 0, v[188:189]
	s_mov_b32 m0, s35
	s_nop 0
	global_load_lds_dwordx4 v[6:7], off
	s_waitcnt vmcnt(8)
	s_waitcnt lgkmcnt(0)
	s_barrier
	s_setprio 1
	s_waitcnt lgkmcnt(0)
	v_mfma_f32_16x16x32_bf16 v[128:131], v[132:135], v[164:167], v[128:131]
	v_mfma_f32_16x16x32_bf16 v[124:127], v[140:143], v[164:167], v[124:127]
	v_mfma_f32_16x16x32_bf16 v[120:123], v[132:135], v[172:175], v[120:123]
	v_mfma_f32_16x16x32_bf16 v[116:119], v[140:143], v[172:175], v[116:119]
	v_mfma_f32_16x16x32_bf16 v[112:115], v[132:135], v[180:183], v[112:115]
	v_mfma_f32_16x16x32_bf16 v[108:111], v[140:143], v[180:183], v[108:111]
	v_mfma_f32_16x16x32_bf16 v[104:107], v[132:135], v[206:209], v[104:107]
	v_mfma_f32_16x16x32_bf16 v[100:103], v[140:143], v[206:209], v[100:103]
	v_mfma_f32_16x16x32_bf16 v[128:131], v[136:139], v[168:171], v[128:131]
	v_mfma_f32_16x16x32_bf16 v[124:127], v[144:147], v[168:171], v[124:127]
	v_mfma_f32_16x16x32_bf16 v[120:123], v[136:139], v[176:179], v[120:123]
	v_mfma_f32_16x16x32_bf16 v[116:119], v[144:147], v[176:179], v[116:119]
	v_mfma_f32_16x16x32_bf16 v[112:115], v[136:139], v[202:205], v[112:115]
	v_mfma_f32_16x16x32_bf16 v[108:111], v[144:147], v[202:205], v[108:111]
	v_mfma_f32_16x16x32_bf16 v[104:107], v[136:139], v[210:213], v[104:107]
	v_mfma_f32_16x16x32_bf16 v[100:103], v[144:147], v[210:213], v[100:103]
	s_setprio 0
	s_setprio 1
	v_mfma_f32_16x16x32_bf16 v[96:99], v[148:151], v[164:167], v[96:99]
	v_mfma_f32_16x16x32_bf16 v[92:95], v[156:159], v[164:167], v[92:95]
	v_mfma_f32_16x16x32_bf16 v[88:91], v[148:151], v[172:175], v[88:91]
	v_mfma_f32_16x16x32_bf16 v[84:87], v[156:159], v[172:175], v[84:87]
	v_mfma_f32_16x16x32_bf16 v[80:83], v[148:151], v[180:183], v[80:83]
	v_mfma_f32_16x16x32_bf16 v[76:79], v[156:159], v[180:183], v[76:79]
	v_mfma_f32_16x16x32_bf16 v[72:75], v[148:151], v[206:209], v[72:75]
	v_mfma_f32_16x16x32_bf16 v[68:71], v[156:159], v[206:209], v[68:71]
	v_mfma_f32_16x16x32_bf16 v[96:99], v[152:155], v[168:171], v[96:99]
	v_mfma_f32_16x16x32_bf16 v[92:95], v[160:163], v[168:171], v[92:95]
	v_mfma_f32_16x16x32_bf16 v[88:91], v[152:155], v[176:179], v[88:91]
	v_mfma_f32_16x16x32_bf16 v[84:87], v[160:163], v[176:179], v[84:87]
	v_mfma_f32_16x16x32_bf16 v[80:83], v[152:155], v[202:205], v[80:83]
	v_mfma_f32_16x16x32_bf16 v[76:79], v[160:163], v[202:205], v[76:79]
	v_mfma_f32_16x16x32_bf16 v[72:75], v[152:155], v[210:213], v[72:75]
	v_mfma_f32_16x16x32_bf16 v[68:71], v[160:163], v[210:213], v[68:71]
	s_setprio 0
	s_barrier
; #define PG8_STAGE(bufoff, gbase, voff) do { _Pragma("unroll") for (int _i = 0; _i < 2; ++_i) \
;         __builtin_amdgcn_global_load_lds((const unsigned*)((const char*)(gbase) + (voff)[_i]), (PG8_LAS unsigned*)(lds + (bufoff) + ldsw + _i * 8192), 16, 0, 0); } while (0)
; #define PG8_LDA(dst, b, h) do { _Pragma("unroll") for (int m = 0; m < 4; ++m) _Pragma("unroll") for (int k = 0; k < 2; ++k) dst[m][k] = *(const PG8_LAS bf16x8*)(lds + PG8_SA(b, h) + aoff + m * 2048 + k * 1024); } while (0)
; #define PG8_MMA(ai, bj, At, Bt) do { __builtin_amdgcn_s_setprio(1); _Pragma("unroll") for (int m = 0; m < 4; ++m) _Pragma("unroll") for (int n = 0; n < 2; ++n) _Pragma("unroll") for (int k = 0; k < 2; ++k) \
;         acc[ai][bj][m][n] = __builtin_amdgcn_mfma_f32_16x16x32_bf16(Bt[n][k], At[m][k], acc[ai][bj][m][n], 0, 0, 0); __builtin_amdgcn_s_setprio(0); } while (0)
; #define PG8_WAIT_V(n) asm volatile("s_waitcnt vmcnt(" #n ")" ::: "memory")
; #define PG8_WAIT_L(n) asm volatile("s_waitcnt lgkmcnt(" #n ")" ::: "memory")
; #define PG8_BAR __builtin_amdgcn_s_barrier()
; #define PG8_SCHED __builtin_amdgcn_sched_barrier(0)
; template <class Epi, class Sched, bool ALIGN_EPI = false, bool SP2 = false, bool DUAL = false>
; __device__ __forceinline__ void gemm_phase(PG8_LAS unsigned char* lds, const Gemm g, const Sched& S, const Epi& E) {
;     ...
;             PG8_LDA(At, 1, 1); PG8_STAGE(PG8_SB(1, 0), b3, voffB); PG8_STAGE(PG8_SB(1, 1), b3 + hstep, voffB); PG8_STAGE(PG8_SA(1, 0), a3, voffA);
;             PG8_WAIT_V(8); PG8_WAIT_L(0); PG8_BAR; PG8_MMA(1, 0, At, B0); PG8_MMA(1, 1, At, B1); PG8_BAR; PG8_SCHED;
;     ...
;         if constexpr (ALIGN_EPI) { if (wr == 0) PG8_BAR; }
	s_add_i32 s18, s76, s27
	v_lshl_add_u64 v[6:7], v[214:215], 0, s[36:37]
	s_mov_b32 m0, s18
	ds_read_b128 v[164:167], v237 offset:49152
	ds_read_b128 v[168:171], v237 offset:50176
	ds_read_b128 v[172:175], v237 offset:51200
	ds_read_b128 v[176:179], v237 offset:52224
	ds_read_b128 v[180:183], v237 offset:53248
	ds_read_b128 v[202:205], v237 offset:54272
	ds_read_b128 v[206:209], v237 offset:55296
	ds_read_b128 v[210:213], v237 offset:56320
	global_load_lds_dwordx4 v[6:7], off
	s_add_i32 m0, s18, 0x2000
	s_add_u32 s16, s16, 0x80080
	v_lshl_add_u64 v[6:7], v[216:217], 0, s[36:37]
	s_addc_u32 s17, s17, 0
	s_add_i32 s18, s77, s27
	global_load_lds_dwordx4 v[6:7], off
	v_lshl_add_u64 v[6:7], s[16:17], 0, v[186:187]
	s_mov_b32 m0, s18
	s_nop 0
	global_load_lds_dwordx4 v[6:7], off
	v_lshl_add_u64 v[6:7], s[16:17], 0, v[190:191]
	s_add_i32 m0, s18, 0x2000
	s_nop 0
	global_load_lds_dwordx4 v[6:7], off
	v_lshl_add_u64 v[6:7], v[218:219], 0, s[36:37]
	s_mov_b32 m0, s42
	s_nop 0
	global_load_lds_dwordx4 v[6:7], off
	v_lshl_add_u64 v[6:7], v[220:221], 0, s[36:37]
	s_mov_b32 m0, s43
	s_nop 0
	global_load_lds_dwordx4 v[6:7], off
	s_waitcnt vmcnt(8)
	s_waitcnt lgkmcnt(0)
	s_barrier
	s_setprio 1
	s_waitcnt lgkmcnt(0)
	v_mfma_f32_16x16x32_bf16 v[64:67], v[132:135], v[164:167], v[64:67]
	v_mfma_f32_16x16x32_bf16 v[60:63], v[140:143], v[164:167], v[60:63]
	v_mfma_f32_16x16x32_bf16 v[56:59], v[132:135], v[172:175], v[56:59]
	v_mfma_f32_16x16x32_bf16 v[52:55], v[140:143], v[172:175], v[52:55]
	v_mfma_f32_16x16x32_bf16 v[48:51], v[132:135], v[180:183], v[48:51]
	v_mfma_f32_16x16x32_bf16 v[44:47], v[140:143], v[180:183], v[44:47]
	v_mfma_f32_16x16x32_bf16 v[40:43], v[132:135], v[206:209], v[40:43]
	v_mfma_f32_16x16x32_bf16 v[36:39], v[140:143], v[206:209], v[36:39]
	v_mfma_f32_16x16x32_bf16 v[64:67], v[136:139], v[168:171], v[64:67]
	v_mfma_f32_16x16x32_bf16 v[60:63], v[144:147], v[168:171], v[60:63]
	v_mfma_f32_16x16x32_bf16 v[56:59], v[136:139], v[176:179], v[56:59]
	v_mfma_f32_16x16x32_bf16 v[52:55], v[144:147], v[176:179], v[52:55]
	v_mfma_f32_16x16x32_bf16 v[48:51], v[136:139], v[202:205], v[48:51]
	v_mfma_f32_16x16x32_bf16 v[44:47], v[144:147], v[202:205], v[44:47]
	v_mfma_f32_16x16x32_bf16 v[40:43], v[136:139], v[210:213], v[40:43]
	v_mfma_f32_16x16x32_bf16 v[36:39], v[144:147], v[210:213], v[36:39]
	s_setprio 0
	s_setprio 1
	v_mfma_f32_16x16x32_bf16 v[32:35], v[148:151], v[164:167], v[32:35]
	v_mfma_f32_16x16x32_bf16 v[28:31], v[156:159], v[164:167], v[28:31]
	v_mfma_f32_16x16x32_bf16 v[24:27], v[148:151], v[172:175], v[24:27]
	v_mfma_f32_16x16x32_bf16 v[20:23], v[156:159], v[172:175], v[20:23]
	v_mfma_f32_16x16x32_bf16 v[16:19], v[148:151], v[180:183], v[16:19]
	v_mfma_f32_16x16x32_bf16 v[12:15], v[156:159], v[180:183], v[12:15]
	v_mfma_f32_16x16x32_bf16 v[6:9], v[148:151], v[206:209], v[8:11]
	v_mfma_f32_16x16x32_bf16 v[2:5], v[156:159], v[206:209], v[2:5]
	v_mfma_f32_16x16x32_bf16 v[32:35], v[152:155], v[168:171], v[32:35]
	v_mfma_f32_16x16x32_bf16 v[28:31], v[160:163], v[168:171], v[28:31]
	v_mfma_f32_16x16x32_bf16 v[24:27], v[152:155], v[176:179], v[24:27]
	v_mfma_f32_16x16x32_bf16 v[20:23], v[160:163], v[176:179], v[20:23]
	v_mfma_f32_16x16x32_bf16 v[16:19], v[152:155], v[202:205], v[16:19]
	v_mfma_f32_16x16x32_bf16 v[12:15], v[160:163], v[202:205], v[12:15]
	v_mfma_f32_16x16x32_bf16 v[8:11], v[152:155], v[210:213], v[6:9]
	v_mfma_f32_16x16x32_bf16 v[4:7], v[160:163], v[210:213], v[2:5]
	s_setprio 0
	s_barrier
	s_add_i32 s75, s75, 2
	s_add_u32 s14, s14, 0x100
	s_addc_u32 s15, s15, 0
	s_add_u32 s72, s72, 0x100
	s_addc_u32 s73, s73, 0
	s_cmp_gt_u32 s75, 29
	s_cbranch_scc0 .LBB0_805
	s_and_b64 vcc, exec, s[38:39]
	s_cbranch_vccz .LBB0_808
	s_barrier

; #define PG8_STAGE(bufoff, gbase, voff) do { _Pragma("unroll") for (int _i = 0; _i < 2; ++_i) \
;         __builtin_amdgcn_global_load_lds((const unsigned*)((const char*)(gbase) + (voff)[_i]), (PG8_LAS unsigned*)(lds + (bufoff) + ldsw + _i * 8192), 16, 0, 0); } while (0)
; #define PG8_WAIT_V(n) asm volatile("s_waitcnt vmcnt(" #n ")" ::: "memory")
; #define PG8_BAR __builtin_amdgcn_s_barrier()
; template <class Epi, class Sched, bool ALIGN_EPI = false, bool SP2 = false, bool DUAL = false>
; __device__ __forceinline__ void gemm_phase(PG8_LAS unsigned char* lds, const Gemm g, const Sched& S, const Epi& E) {
;     ...
;     const char* cA = (const char*)((DUAL && cur.sub) ? g.A2 : g.A) + (size_t)cur.pm * tstep; const char* cB = (const char*)((DUAL && cur.sub) ? g.Bt2 : g.Bt) + (size_t)cur.pn * tstep;
;     S.a_ready(cur);
;     if constexpr (SP2) {
;         PG8_STAGE(PG8_SB(0, 0), cB, voffB); PG8_STAGE(PG8_SB(0, 1), cB + hstep, voffB); PG8_STAGE(PG8_SA(0, 0), cA, voffA); PG8_STAGE(PG8_SA(0, 1), cA + hstep, voffA);
;         if (wr == 1) PG8_BAR;
;         PG8_WAIT_V(2); PG8_BAR;
;         PG8_STAGE(PG8_SB(1, 0), cB + kstep, voffB); PG8_STAGE(PG8_SA(1, 0), cA + kstep, voffA); PG8_STAGE(PG8_SB(1, 1), cB + hstep + kstep, voffB);
;         PG8_WAIT_V(6); PG8_BAR;
.LBB0_886:
	s_mov_b64 s[36:37], 0x80
	s_and_b32 s35, s5, 3
	s_add_i32 m0, s27, 0x18000
	v_lshl_add_u64 v[6:7], v[6:7], 0, s[36:37]
	s_lshl_b32 s5, s4, 13
	s_lshl_b32 s7, s35, 12
	s_ashr_i32 s42, s92, 31
	s_ashr_i32 s43, s2, 31
	s_waitcnt vmcnt(2)
	s_barrier
	global_load_lds_dwordx4 v[6:7], off
	v_lshl_add_u64 v[4:5], v[4:5], 0, s[36:37]
	s_add_i32 m0, s27, 0x1a000
	s_add_i32 s44, s27, 0x8000
	s_add_i32 s45, s27, 0xa000
	global_load_lds_dwordx4 v[4:5], off
	v_lshl_add_u64 v[2:3], v[2:3], 0, s[36:37]
	s_mov_b32 m0, s44
	s_add_u32 s18, s14, 0x80080
	global_load_lds_dwordx4 v[2:3], off
	v_lshl_add_u64 v[0:1], v[0:1], 0, s[36:37]
	s_mov_b32 m0, s45
	s_addc_u32 s19, s15, 0
	global_load_lds_dwordx4 v[0:1], off
	s_add_i32 m0, s27, 0x1c000
	v_lshl_add_u64 v[0:1], s[18:19], 0, v[182:183]
	global_load_lds_dwordx4 v[0:1], off
	v_lshl_add_u64 v[0:1], s[18:19], 0, v[186:187]
	s_add_i32 m0, s27, 0x1e000
	s_movk_i32 s18, 0x3c0
	global_load_lds_dwordx4 v[0:1], off
	v_lshlrev_b32_e32 v0, 6, v200
	v_and_or_b32 v0, v0, s18, v8
	v_and_b32_e32 v1, 32, v9
	v_bitop3_b32 v216, s7, v0, v1 bitop3:0xf6
	v_lshlrev_b32_e32 v0, 9, v200
	v_and_b32_e32 v0, 0x70000, v0
	v_lshlrev_b32_e32 v1, 12, v12
	v_or3_b32 v0, v10, v0, v1
	v_add_u32_e32 v188, v0, v11
	v_lshlrev_b32_e32 v0, 5, v13
	v_lshlrev_b32_e32 v3, 2, v211
	v_and_b32_e32 v0, 0xf0000, v0
	v_lshl_or_b32 v2, v211, 6, v8
	v_and_b32_e32 v3, 32, v3
	s_waitcnt vmcnt(6)
	s_cmpk_lt_u32 s6, 0x100
	v_or3_b32 v0, v10, v0, v1
	v_bitop3_b32 v2, v2, s5, v3 bitop3:0xde
	s_cselect_b64 s[38:39], -1, 0
	v_add_u32_e32 v190, v0, v11
	s_add_i32 s48, 0, 0x10000
	s_add_i32 s49, 0, 0x14000
	v_mbcnt_lo_u32_b32 v0, -1, 0
	v_lshl_or_b32 v179, s4, 6, v211
	v_cmp_eq_u32_e64 s[4:5], 0, v210
	s_mov_b32 s46, s92
	s_mov_b32 s47, 0x8000
	v_lshl_or_b32 v217, s35, 5, v176
	v_mov_b32_e32 v189, v183
	v_mov_b32_e32 v191, v183
	v_mov_b64_e32 v[192:193], 0x400
	v_mov_b64_e32 v[194:195], 0x3ff
	v_add_u32_e32 v218, s48, v216
	v_add_u32_e32 v219, s49, v216
	v_add_u32_e32 v220, 0, v2
	v_mbcnt_hi_u32_b32 v221, -1, v0
	s_movk_i32 s50, 0x7f50
	s_mov_b32 s51, 0
	s_barrier
	s_branch .LBB0_889

;     __device__ bool next(int i, Unit& u) const { if (!base.next(i >> 1, u)) return false; u.sub = i & 1; return true; }
; #define PG8_STAGE(bufoff, gbase, voff) do { _Pragma("unroll") for (int _i = 0; _i < 2; ++_i) \
;         __builtin_amdgcn_global_load_lds((const unsigned*)((const char*)(gbase) + (voff)[_i]), (PG8_LAS unsigned*)(lds + (bufoff) + ldsw + _i * 8192), 16, 0, 0); } while (0)
; #define PG8_LDA(dst, b, h) do { _Pragma("unroll") for (int m = 0; m < 4; ++m) _Pragma("unroll") for (int k = 0; k < 2; ++k) dst[m][k] = *(const PG8_LAS bf16x8*)(lds + PG8_SA(b, h) + aoff + m * 2048 + k * 1024); } while (0)
; #define PG8_LDB(dst, b, h) do { _Pragma("unroll") for (int n = 0; n < 2; ++n) _Pragma("unroll") for (int k = 0; k < 2; ++k) dst[n][k] = *(const PG8_LAS bf16x8*)(lds + PG8_SB(b, h) + boff + n * 2048 + k * 1024); } while (0)
; #define PG8_WAIT_V(n) asm volatile("s_waitcnt vmcnt(" #n ")" ::: "memory")
; template <class Epi, class Sched, bool ALIGN_EPI = false, bool SP2 = false, bool DUAL = false>
; __device__ __forceinline__ void gemm_phase(PG8_LAS unsigned char* lds, const Gemm g, const Sched& S, const Epi& E) {
;     ...
;         const bool has_next = S.next(ui + 1, nxt);
;         const char* nA = has_next ? (const char*)((DUAL && nxt.sub) ? g.A2 : g.A) + (size_t)nxt.pm * tstep : cA; const char* nB = has_next ? (const char*)((DUAL && nxt.sub) ? g.Bt2 : g.Bt) + (size_t)nxt.pn * tstep : cB;
;         for (int t = 0; t < nt; t += 2) {
;             const bool last = (t == nt - 2);
;             const char* a1 = cA + (size_t)(t + 1) * kstep;
;             const char* a2 = last ? nA : cA + (size_t)(t + 2) * kstep; const char* b2 = last ? nB : cB + (size_t)(t + 2) * kstep;
;             const char* a3 = a2 + kstep; const char* b3 = b2 + kstep;
;             if (last && has_next) S.a_ready(nxt);
;             if constexpr (SP2) {
;             PG8_LDB(B0, 0, 0); PG8_LDB(B1, 0, 1); PG8_SCHED; PG8_LDA(At, 0, 0); PG8_STAGE(PG8_SA(1, 1), a1 + hstep, voffA);
;             PG8_WAIT_V(8); PG8_WAIT_L(0); PG8_BAR; PG8_MMA(0, 0, At, B0); PG8_MMA(0, 1, At, B1); PG8_BAR; PG8_SCHED;
;             PG8_LDA(At, 0, 1); PG8_STAGE(PG8_SB(0, 0), b2, voffB); PG8_STAGE(PG8_SB(0, 1), b2 + hstep, voffB); PG8_STAGE(PG8_SA(0, 0), a2, voffA);
;             PG8_WAIT_V(8); PG8_WAIT_L(0); PG8_BAR; PG8_MMA(1, 0, At, B0); PG8_MMA(1, 1, At, B1); PG8_BAR; PG8_SCHED;
.LBB0_895:
	s_ashr_i32 s61, s60, 31
	s_lshl_b64 s[18:19], s[60:61], 20
	s_add_u32 s62, s10, s18
	s_addc_u32 s63, s11, s19
	s_and_b64 s[18:19], s[6:7], exec
	s_cselect_b32 s18, s63, s17
	s_cselect_b32 s19, s62, s16
	s_ashr_i32 s41, s40, 31
	s_lshl_b64 s[64:65], s[40:41], 20
	s_add_u32 s64, s12, s64
	s_addc_u32 s65, s13, s65
	s_and_b64 s[68:69], s[6:7], exec
	s_cselect_b32 s41, s65, s15
	s_cselect_b32 s61, s64, s14
	s_add_u32 s68, s16, 0x80080
	s_addc_u32 s69, s17, 0
	s_add_u32 s67, s14, 0x100
	s_addc_u32 s70, s15, 0
	s_mov_b32 s71, -2
	s_waitcnt lgkmcnt(0)
	ds_read_b128 v[128:131], v218
	ds_read_b128 v[132:135], v218 offset:1024
	ds_read_b128 v[136:139], v218 offset:2048
	ds_read_b128 v[140:143], v218 offset:3072
	ds_read_b128 v[144:147], v219
	ds_read_b128 v[148:151], v219 offset:1024
	ds_read_b128 v[152:155], v219 offset:2048
	ds_read_b128 v[156:159], v219 offset:3072
	s_add_u32 s14, s68, 0xfff80080
	s_addc_u32 s15, s69, -1
	s_cmp_eq_u32 s71, 28
	s_cselect_b32 s17, s18, s15
	s_cselect_b32 s16, s19, s14
	s_cselect_b32 s15, s41, s70
	s_cselect_b32 s14, s61, s67
	v_lshl_add_u64 v[222:223], s[68:69], 0, v[188:189]
	s_add_i32 m0, s27, 0xc000
	ds_read_b128 v[160:163], v220
	ds_read_b128 v[164:167], v220 offset:1024
	ds_read_b128 v[168:171], v220 offset:2048
	ds_read_b128 v[172:175], v220 offset:3072
	ds_read_b128 v[196:199], v220 offset:4096
	ds_read_b128 v[202:205], v220 offset:5120
	ds_read_b128 v[206:209], v220 offset:6144
	ds_read_b128 v[232:235], v220 offset:7168
	global_load_lds_dwordx4 v[222:223], off
	v_lshl_add_u64 v[222:223], s[68:69], 0, v[190:191]
	s_add_i32 m0, s27, 0xe000
	s_nop 0
	global_load_lds_dwordx4 v[222:223], off
	s_waitcnt vmcnt(8)
	s_waitcnt lgkmcnt(0)
	s_barrier
	s_setprio 1
	s_waitcnt lgkmcnt(0)
	v_mfma_f32_16x16x32_bf16 v[124:127], v[128:131], v[160:163], 0
	v_mfma_f32_16x16x32_bf16 v[120:123], v[136:139], v[160:163], 0
	v_mfma_f32_16x16x32_bf16 v[108:111], v[128:131], v[168:171], 0
	v_mfma_f32_16x16x32_bf16 v[104:107], v[136:139], v[168:171], 0
	v_mfma_f32_16x16x32_bf16 v[92:95], v[128:131], v[196:199], 0
	v_mfma_f32_16x16x32_bf16 v[88:91], v[136:139], v[196:199], 0
	v_mfma_f32_16x16x32_bf16 v[76:79], v[128:131], v[206:209], 0
	v_mfma_f32_16x16x32_bf16 v[72:75], v[136:139], v[206:209], 0
	v_mfma_f32_16x16x32_bf16 v[124:127], v[132:135], v[164:167], v[124:127]
	v_mfma_f32_16x16x32_bf16 v[120:123], v[140:143], v[164:167], v[120:123]
	v_mfma_f32_16x16x32_bf16 v[108:111], v[132:135], v[172:175], v[108:111]
	v_mfma_f32_16x16x32_bf16 v[104:107], v[140:143], v[172:175], v[104:107]
	v_mfma_f32_16x16x32_bf16 v[92:95], v[132:135], v[202:205], v[92:95]
	v_mfma_f32_16x16x32_bf16 v[88:91], v[140:143], v[202:205], v[88:91]
	v_mfma_f32_16x16x32_bf16 v[76:79], v[132:135], v[232:235], v[76:79]
	v_mfma_f32_16x16x32_bf16 v[72:75], v[140:143], v[232:235], v[72:75]
	s_setprio 0
	s_setprio 1
	v_mfma_f32_16x16x32_bf16 v[116:119], v[144:147], v[160:163], 0
	v_mfma_f32_16x16x32_bf16 v[112:115], v[152:155], v[160:163], 0
	v_mfma_f32_16x16x32_bf16 v[100:103], v[144:147], v[168:171], 0
	v_mfma_f32_16x16x32_bf16 v[96:99], v[152:155], v[168:171], 0
	v_mfma_f32_16x16x32_bf16 v[84:87], v[144:147], v[196:199], 0
	v_mfma_f32_16x16x32_bf16 v[80:83], v[152:155], v[196:199], 0
	v_mfma_f32_16x16x32_bf16 v[68:71], v[144:147], v[206:209], 0
	v_mfma_f32_16x16x32_bf16 v[64:67], v[152:155], v[206:209], 0
	v_mfma_f32_16x16x32_bf16 v[116:119], v[148:151], v[164:167], v[116:119]
	v_mfma_f32_16x16x32_bf16 v[112:115], v[156:159], v[164:167], v[112:115]
	v_mfma_f32_16x16x32_bf16 v[100:103], v[148:151], v[172:175], v[100:103]
	v_mfma_f32_16x16x32_bf16 v[96:99], v[156:159], v[172:175], v[96:99]
	v_mfma_f32_16x16x32_bf16 v[84:87], v[148:151], v[202:205], v[84:87]
	v_mfma_f32_16x16x32_bf16 v[80:83], v[156:159], v[202:205], v[80:83]
	v_mfma_f32_16x16x32_bf16 v[68:71], v[148:151], v[232:235], v[68:71]
	v_mfma_f32_16x16x32_bf16 v[64:67], v[156:159], v[232:235], v[64:67]
	s_setprio 0
	s_barrier
	s_add_i32 s72, s48, s26
	v_lshl_add_u64 v[222:223], s[14:15], 0, v[182:183]
	s_mov_b32 m0, s72
	ds_read_b128 v[160:163], v220 offset:16384
	ds_read_b128 v[164:167], v220 offset:17408
	ds_read_b128 v[168:171], v220 offset:18432
	ds_read_b128 v[172:175], v220 offset:19456
	ds_read_b128 v[196:199], v220 offset:20480
	ds_read_b128 v[202:205], v220 offset:21504
	ds_read_b128 v[206:209], v220 offset:22528
	ds_read_b128 v[232:235], v220 offset:23552
	global_load_lds_dwordx4 v[222:223], off
	s_add_i32 m0, s72, 0x2000
	s_add_u32 s72, s14, 0x80000
	v_lshl_add_u64 v[228:229], s[14:15], 0, v[186:187]
	s_addc_u32 s73, s15, 0
	s_add_i32 s74, s49, s26
	global_load_lds_dwordx4 v[228:229], off
	v_lshl_add_u64 v[236:237], s[72:73], 0, v[182:183]
	s_mov_b32 m0, s74
	v_lshl_add_u64 v[238:239], s[16:17], 0, v[184:185]
	global_load_lds_dwordx4 v[236:237], off
	v_lshl_add_u64 v[236:237], s[72:73], 0, v[186:187]
	s_add_i32 m0, s74, 0x2000
	s_nop 0
	global_load_lds_dwordx4 v[236:237], off
	v_lshl_add_u64 v[236:237], s[16:17], 0, v[180:181]
	s_mov_b32 m0, s27
	s_nop 0
	global_load_lds_dwordx4 v[236:237], off
	s_mov_b32 m0, s28
	s_nop 0
	global_load_lds_dwordx4 v[238:239], off
	s_waitcnt vmcnt(8)
	s_waitcnt lgkmcnt(0)
	s_barrier
; #define PG8_STAGE(bufoff, gbase, voff) do { _Pragma("unroll") for (int _i = 0; _i < 2; ++_i) \
;         __builtin_amdgcn_global_load_lds((const unsigned*)((const char*)(gbase) + (voff)[_i]), (PG8_LAS unsigned*)(lds + (bufoff) + ldsw + _i * 8192), 16, 0, 0); } while (0)
; #define PG8_LDA(dst, b, h) do { _Pragma("unroll") for (int m = 0; m < 4; ++m) _Pragma("unroll") for (int k = 0; k < 2; ++k) dst[m][k] = *(const PG8_LAS bf16x8*)(lds + PG8_SA(b, h) + aoff + m * 2048 + k * 1024); } while (0)
; #define PG8_LDB(dst, b, h) do { _Pragma("unroll") for (int n = 0; n < 2; ++n) _Pragma("unroll") for (int k = 0; k < 2; ++k) dst[n][k] = *(const PG8_LAS bf16x8*)(lds + PG8_SB(b, h) + boff + n * 2048 + k * 1024); } while (0)
; #define PG8_MMA(ai, bj, At, Bt) do { __builtin_amdgcn_s_setprio(1); _Pragma("unroll") for (int m = 0; m < 4; ++m) _Pragma("unroll") for (int n = 0; n < 2; ++n) _Pragma("unroll") for (int k = 0; k < 2; ++k) \
;         acc[ai][bj][m][n] = __builtin_amdgcn_mfma_f32_16x16x32_bf16(Bt[n][k], At[m][k], acc[ai][bj][m][n], 0, 0, 0); __builtin_amdgcn_s_setprio(0); } while (0)
; #define PG8_WAIT_V(n) asm volatile("s_waitcnt vmcnt(" #n ")" ::: "memory")
; #define PG8_WAIT_L(n) asm volatile("s_waitcnt lgkmcnt(" #n ")" ::: "memory")
; #define PG8_BAR __builtin_amdgcn_s_barrier()
; #define PG8_SCHED __builtin_amdgcn_sched_barrier(0)
; template <class Epi, class Sched, bool ALIGN_EPI = false, bool SP2 = false, bool DUAL = false>
; __device__ __forceinline__ void gemm_phase(PG8_LAS unsigned char* lds, const Gemm g, const Sched& S, const Epi& E) {
;     ...
;             PG8_WAIT_V(8); PG8_WAIT_L(0); PG8_BAR; PG8_MMA(1, 0, At, B0); PG8_MMA(1, 1, At, B1); PG8_BAR; PG8_SCHED;
;             PG8_LDB(B0, 1, 0); PG8_LDB(B1, 1, 1); PG8_SCHED; PG8_LDA(At, 1, 0); PG8_STAGE(PG8_SA(0, 1), a2 + hstep, voffA);
;             PG8_WAIT_V(8); PG8_WAIT_L(0); PG8_BAR; PG8_MMA(0, 0, At, B0); PG8_MMA(0, 1, At, B1); PG8_BAR; PG8_SCHED;
	s_setprio 1
	s_waitcnt lgkmcnt(0)
	v_mfma_f32_16x16x32_bf16 v[60:63], v[128:131], v[160:163], 0
	v_mfma_f32_16x16x32_bf16 v[56:59], v[136:139], v[160:163], 0
	v_mfma_f32_16x16x32_bf16 v[44:47], v[128:131], v[168:171], 0
	v_mfma_f32_16x16x32_bf16 v[40:43], v[136:139], v[168:171], 0
	v_mfma_f32_16x16x32_bf16 v[28:31], v[128:131], v[196:199], 0
	v_mfma_f32_16x16x32_bf16 v[24:27], v[136:139], v[196:199], 0
	v_mfma_f32_16x16x32_bf16 v[12:15], v[128:131], v[206:209], 0
	v_mfma_f32_16x16x32_bf16 v[8:11], v[136:139], v[206:209], 0
	v_mfma_f32_16x16x32_bf16 v[60:63], v[132:135], v[164:167], v[60:63]
	v_mfma_f32_16x16x32_bf16 v[56:59], v[140:143], v[164:167], v[56:59]
	v_mfma_f32_16x16x32_bf16 v[44:47], v[132:135], v[172:175], v[44:47]
	v_mfma_f32_16x16x32_bf16 v[40:43], v[140:143], v[172:175], v[40:43]
	v_mfma_f32_16x16x32_bf16 v[28:31], v[132:135], v[202:205], v[28:31]
	v_mfma_f32_16x16x32_bf16 v[24:27], v[140:143], v[202:205], v[24:27]
	v_mfma_f32_16x16x32_bf16 v[12:15], v[132:135], v[232:235], v[12:15]
	v_mfma_f32_16x16x32_bf16 v[8:11], v[140:143], v[232:235], v[8:11]
	s_setprio 0
	s_setprio 1
	v_mfma_f32_16x16x32_bf16 v[52:55], v[144:147], v[160:163], 0
	v_mfma_f32_16x16x32_bf16 v[48:51], v[152:155], v[160:163], 0
	v_mfma_f32_16x16x32_bf16 v[36:39], v[144:147], v[168:171], 0
	v_mfma_f32_16x16x32_bf16 v[32:35], v[152:155], v[168:171], 0
	v_mfma_f32_16x16x32_bf16 v[20:23], v[144:147], v[196:199], 0
	v_mfma_f32_16x16x32_bf16 v[16:19], v[152:155], v[196:199], 0
	v_mfma_f32_16x16x32_bf16 v[4:7], v[144:147], v[206:209], 0
	v_mfma_f32_16x16x32_bf16 v[0:3], v[152:155], v[206:209], 0
	v_mfma_f32_16x16x32_bf16 v[52:55], v[148:151], v[164:167], v[52:55]
	v_mfma_f32_16x16x32_bf16 v[48:51], v[156:159], v[164:167], v[48:51]
	v_mfma_f32_16x16x32_bf16 v[36:39], v[148:151], v[172:175], v[36:39]
	v_mfma_f32_16x16x32_bf16 v[32:35], v[156:159], v[172:175], v[32:35]
	v_mfma_f32_16x16x32_bf16 v[20:23], v[148:151], v[202:205], v[20:23]
	v_mfma_f32_16x16x32_bf16 v[16:19], v[156:159], v[202:205], v[16:19]
	v_mfma_f32_16x16x32_bf16 v[4:7], v[148:151], v[232:235], v[4:7]
	v_mfma_f32_16x16x32_bf16 v[0:3], v[156:159], v[232:235], v[0:3]
	s_setprio 0
	s_barrier
	s_add_i32 s72, 0, 0x18000
	s_add_i32 s73, 0, 0x1c000
	v_add_u32_e32 v140, s72, v216
	v_add_u32_e32 v156, s73, v216
	ds_read_b128 v[128:131], v140
	ds_read_b128 v[132:135], v140 offset:1024
	ds_read_b128 v[136:139], v140 offset:2048
	ds_read_b128 v[140:143], v140 offset:3072
	ds_read_b128 v[144:147], v156
	ds_read_b128 v[148:151], v156 offset:1024
	ds_read_b128 v[152:155], v156 offset:2048
	ds_read_b128 v[156:159], v156 offset:3072
	s_add_u32 s16, s16, 0x80000
	s_addc_u32 s17, s17, 0
	s_mov_b32 m0, s29
	v_lshl_add_u64 v[240:241], s[16:17], 0, v[180:181]
	ds_read_b128 v[160:163], v220 offset:32768
	ds_read_b128 v[164:167], v220 offset:33792
	ds_read_b128 v[168:171], v220 offset:34816
	ds_read_b128 v[172:175], v220 offset:35840
	ds_read_b128 v[196:199], v220 offset:36864
	ds_read_b128 v[202:205], v220 offset:37888
	ds_read_b128 v[206:209], v220 offset:38912
	ds_read_b128 v[232:235], v220 offset:39936
	global_load_lds_dwordx4 v[240:241], off
	v_lshl_add_u64 v[240:241], s[16:17], 0, v[184:185]
	s_mov_b32 m0, s34
	s_nop 0
	global_load_lds_dwordx4 v[240:241], off
	s_waitcnt vmcnt(8)
	s_waitcnt lgkmcnt(0)
	s_barrier
	s_setprio 1
	s_waitcnt lgkmcnt(0)
	v_mfma_f32_16x16x32_bf16 v[124:127], v[128:131], v[160:163], v[124:127]
	v_mfma_f32_16x16x32_bf16 v[120:123], v[136:139], v[160:163], v[120:123]
	v_mfma_f32_16x16x32_bf16 v[108:111], v[128:131], v[168:171], v[108:111]
	v_mfma_f32_16x16x32_bf16 v[104:107], v[136:139], v[168:171], v[104:107]
	v_mfma_f32_16x16x32_bf16 v[92:95], v[128:131], v[196:199], v[92:95]
	v_mfma_f32_16x16x32_bf16 v[88:91], v[136:139], v[196:199], v[88:91]
	v_mfma_f32_16x16x32_bf16 v[76:79], v[128:131], v[206:209], v[76:79]
	v_mfma_f32_16x16x32_bf16 v[72:75], v[136:139], v[206:209], v[72:75]
	v_mfma_f32_16x16x32_bf16 v[124:127], v[132:135], v[164:167], v[124:127]
	v_mfma_f32_16x16x32_bf16 v[120:123], v[140:143], v[164:167], v[120:123]
	v_mfma_f32_16x16x32_bf16 v[108:111], v[132:135], v[172:175], v[108:111]
	v_mfma_f32_16x16x32_bf16 v[104:107], v[140:143], v[172:175], v[104:107]
	v_mfma_f32_16x16x32_bf16 v[92:95], v[132:135], v[202:205], v[92:95]
	v_mfma_f32_16x16x32_bf16 v[88:91], v[140:143], v[202:205], v[88:91]
	v_mfma_f32_16x16x32_bf16 v[76:79], v[132:135], v[232:235], v[76:79]
	v_mfma_f32_16x16x32_bf16 v[72:75], v[140:143], v[232:235], v[72:75]
	s_setprio 0
	s_setprio 1
	v_mfma_f32_16x16x32_bf16 v[116:119], v[144:147], v[160:163], v[116:119]
	v_mfma_f32_16x16x32_bf16 v[112:115], v[152:155], v[160:163], v[112:115]
	v_mfma_f32_16x16x32_bf16 v[100:103], v[144:147], v[168:171], v[100:103]
	v_mfma_f32_16x16x32_bf16 v[96:99], v[152:155], v[168:171], v[96:99]
	v_mfma_f32_16x16x32_bf16 v[84:87], v[144:147], v[196:199], v[84:87]
	v_mfma_f32_16x16x32_bf16 v[80:83], v[152:155], v[196:199], v[80:83]
	v_mfma_f32_16x16x32_bf16 v[68:71], v[144:147], v[206:209], v[68:71]
	v_mfma_f32_16x16x32_bf16 v[64:67], v[152:155], v[206:209], v[64:67]
	v_mfma_f32_16x16x32_bf16 v[116:119], v[148:151], v[164:167], v[116:119]
	v_mfma_f32_16x16x32_bf16 v[112:115], v[156:159], v[164:167], v[112:115]
	v_mfma_f32_16x16x32_bf16 v[100:103], v[148:151], v[172:175], v[100:103]
	v_mfma_f32_16x16x32_bf16 v[96:99], v[156:159], v[172:175], v[96:99]
	v_mfma_f32_16x16x32_bf16 v[84:87], v[148:151], v[202:205], v[84:87]
	v_mfma_f32_16x16x32_bf16 v[80:83], v[156:159], v[202:205], v[80:83]
	v_mfma_f32_16x16x32_bf16 v[68:71], v[148:151], v[232:235], v[68:71]
	v_mfma_f32_16x16x32_bf16 v[64:67], v[156:159], v[232:235], v[64:67]
	s_setprio 0
	s_barrier
; #define PG8_STAGE(bufoff, gbase, voff) do { _Pragma("unroll") for (int _i = 0; _i < 2; ++_i) \
;         __builtin_amdgcn_global_load_lds((const unsigned*)((const char*)(gbase) + (voff)[_i]), (PG8_LAS unsigned*)(lds + (bufoff) + ldsw + _i * 8192), 16, 0, 0); } while (0)
; #define PG8_LDA(dst, b, h) do { _Pragma("unroll") for (int m = 0; m < 4; ++m) _Pragma("unroll") for (int k = 0; k < 2; ++k) dst[m][k] = *(const PG8_LAS bf16x8*)(lds + PG8_SA(b, h) + aoff + m * 2048 + k * 1024); } while (0)
; #define PG8_LDB(dst, b, h) do { _Pragma("unroll") for (int n = 0; n < 2; ++n) _Pragma("unroll") for (int k = 0; k < 2; ++k) dst[n][k] = *(const PG8_LAS bf16x8*)(lds + PG8_SB(b, h) + boff + n * 2048 + k * 1024); } while (0)
; #define PG8_MMA(ai, bj, At, Bt) do { __builtin_amdgcn_s_setprio(1); _Pragma("unroll") for (int m = 0; m < 4; ++m) _Pragma("unroll") for (int n = 0; n < 2; ++n) _Pragma("unroll") for (int k = 0; k < 2; ++k) \
;         acc[ai][bj][m][n] = __builtin_amdgcn_mfma_f32_16x16x32_bf16(Bt[n][k], At[m][k], acc[ai][bj][m][n], 0, 0, 0); __builtin_amdgcn_s_setprio(0); } while (0)
; #define PG8_BAR __builtin_amdgcn_s_barrier()
; template <class Epi, class Sched, bool ALIGN_EPI = false, bool SP2 = false, bool DUAL = false>
; __device__ __forceinline__ void gemm_phase(PG8_LAS unsigned char* lds, const Gemm g, const Sched& S, const Epi& E) {
;     ...
;             PG8_LDB(B0, 0, 0); PG8_LDB(B1, 0, 1); PG8_SCHED; PG8_LDA(At, 0, 0); PG8_STAGE(PG8_SA(1, 1), a1 + hstep, voffA);
;             PG8_WAIT_V(8); PG8_WAIT_L(0); PG8_BAR; PG8_MMA(0, 0, At, B0); PG8_MMA(0, 1, At, B1); PG8_BAR; PG8_SCHED;
;             PG8_LDA(At, 0, 1); PG8_STAGE(PG8_SB(0, 0), b2, voffB); PG8_STAGE(PG8_SB(0, 1), b2 + hstep, voffB); PG8_STAGE(PG8_SA(0, 0), a2, voffA);
;             PG8_WAIT_V(8); PG8_WAIT_L(0); PG8_BAR; PG8_MMA(1, 0, At, B0); PG8_MMA(1, 1, At, B1); PG8_BAR; PG8_SCHED;
;             PG8_LDB(B0, 1, 0); PG8_LDB(B1, 1, 1); PG8_SCHED; PG8_LDA(At, 1, 0); PG8_STAGE(PG8_SA(0, 1), a2 + hstep, voffA);
;             PG8_WAIT_V(8); PG8_WAIT_L(0); PG8_BAR; PG8_MMA(0, 0, At, B0); PG8_MMA(0, 1, At, B1); PG8_BAR; PG8_SCHED;
;             PG8_LDA(At, 1, 1); PG8_STAGE(PG8_SB(1, 0), b3, voffB); PG8_STAGE(PG8_SB(1, 1), b3 + hstep, voffB); PG8_STAGE(PG8_SA(1, 0), a3, voffA);
;             PG8_WAIT_V(8); PG8_WAIT_L(0); PG8_BAR; PG8_MMA(1, 0, At, B0); PG8_MMA(1, 1, At, B1); PG8_BAR; PG8_SCHED;
	s_add_i32 s16, s72, s26
	v_lshl_add_u64 v[222:223], v[222:223], 0, s[36:37]
	s_mov_b32 m0, s16
	ds_read_b128 v[160:163], v220 offset:49152
	ds_read_b128 v[164:167], v220 offset:50176
	ds_read_b128 v[168:171], v220 offset:51200
	ds_read_b128 v[172:175], v220 offset:52224
	ds_read_b128 v[196:199], v220 offset:53248
	ds_read_b128 v[202:205], v220 offset:54272
	ds_read_b128 v[206:209], v220 offset:55296
	ds_read_b128 v[232:235], v220 offset:56320
	global_load_lds_dwordx4 v[222:223], off
	s_add_i32 m0, s16, 0x2000
	s_add_u32 s14, s14, 0x80080
	v_lshl_add_u64 v[222:223], v[228:229], 0, s[36:37]
	s_addc_u32 s15, s15, 0
	s_add_i32 s16, s73, s26
	global_load_lds_dwordx4 v[222:223], off
	v_lshl_add_u64 v[222:223], s[14:15], 0, v[182:183]
	s_mov_b32 m0, s16
	s_nop 0
	global_load_lds_dwordx4 v[222:223], off
	v_lshl_add_u64 v[222:223], s[14:15], 0, v[186:187]
	s_add_i32 m0, s16, 0x2000
	s_nop 0
	global_load_lds_dwordx4 v[222:223], off
	v_lshl_add_u64 v[222:223], v[236:237], 0, s[36:37]
	s_mov_b32 m0, s44
	s_nop 0
	global_load_lds_dwordx4 v[222:223], off
	v_lshl_add_u64 v[222:223], v[238:239], 0, s[36:37]
	s_mov_b32 m0, s45
	s_nop 0
	global_load_lds_dwordx4 v[222:223], off
	s_waitcnt vmcnt(8)
	s_waitcnt lgkmcnt(0)
	s_barrier
	s_setprio 1
	s_waitcnt lgkmcnt(0)
	v_mfma_f32_16x16x32_bf16 v[60:63], v[128:131], v[160:163], v[60:63]
	v_mfma_f32_16x16x32_bf16 v[56:59], v[136:139], v[160:163], v[56:59]
	v_mfma_f32_16x16x32_bf16 v[44:47], v[128:131], v[168:171], v[44:47]
	v_mfma_f32_16x16x32_bf16 v[40:43], v[136:139], v[168:171], v[40:43]
	v_mfma_f32_16x16x32_bf16 v[28:31], v[128:131], v[196:199], v[28:31]
	v_mfma_f32_16x16x32_bf16 v[24:27], v[136:139], v[196:199], v[24:27]
	v_mfma_f32_16x16x32_bf16 v[12:15], v[128:131], v[206:209], v[12:15]
	v_mfma_f32_16x16x32_bf16 v[8:11], v[136:139], v[206:209], v[8:11]
	v_mfma_f32_16x16x32_bf16 v[60:63], v[132:135], v[164:167], v[60:63]
	v_mfma_f32_16x16x32_bf16 v[56:59], v[140:143], v[164:167], v[56:59]
	v_mfma_f32_16x16x32_bf16 v[44:47], v[132:135], v[172:175], v[44:47]
	v_mfma_f32_16x16x32_bf16 v[40:43], v[140:143], v[172:175], v[40:43]
	v_mfma_f32_16x16x32_bf16 v[28:31], v[132:135], v[202:205], v[28:31]
	v_mfma_f32_16x16x32_bf16 v[24:27], v[140:143], v[202:205], v[24:27]
	v_mfma_f32_16x16x32_bf16 v[12:15], v[132:135], v[232:235], v[12:15]
	v_mfma_f32_16x16x32_bf16 v[8:11], v[140:143], v[232:235], v[8:11]
	s_setprio 0
	s_setprio 1
	v_mfma_f32_16x16x32_bf16 v[52:55], v[144:147], v[160:163], v[52:55]
	v_mfma_f32_16x16x32_bf16 v[48:51], v[152:155], v[160:163], v[48:51]
	v_mfma_f32_16x16x32_bf16 v[36:39], v[144:147], v[168:171], v[36:39]
	v_mfma_f32_16x16x32_bf16 v[32:35], v[152:155], v[168:171], v[32:35]
	v_mfma_f32_16x16x32_bf16 v[20:23], v[144:147], v[196:199], v[20:23]
	v_mfma_f32_16x16x32_bf16 v[16:19], v[152:155], v[196:199], v[16:19]
	v_mfma_f32_16x16x32_bf16 v[4:7], v[144:147], v[206:209], v[4:7]
	v_mfma_f32_16x16x32_bf16 v[0:3], v[152:155], v[206:209], v[0:3]
	v_mfma_f32_16x16x32_bf16 v[52:55], v[148:151], v[164:167], v[52:55]
	v_mfma_f32_16x16x32_bf16 v[48:51], v[156:159], v[164:167], v[48:51]
	v_mfma_f32_16x16x32_bf16 v[36:39], v[148:151], v[172:175], v[36:39]
	v_mfma_f32_16x16x32_bf16 v[32:35], v[156:159], v[172:175], v[32:35]
	v_mfma_f32_16x16x32_bf16 v[20:23], v[148:151], v[202:205], v[20:23]
	v_mfma_f32_16x16x32_bf16 v[16:19], v[156:159], v[202:205], v[16:19]
	v_mfma_f32_16x16x32_bf16 v[4:7], v[148:151], v[232:235], v[4:7]
	v_mfma_f32_16x16x32_bf16 v[0:3], v[156:159], v[232:235], v[0:3]
	s_setprio 0
	s_barrier
	s_add_i32 s71, s71, 2
	s_add_u32 s68, s68, 0x100
	s_addc_u32 s69, s69, 0
	s_add_u32 s67, s67, 0x100
	s_addc_u32 s70, s70, 0
.LBB0_896:
	ds_read_b128 v[128:131], v218
	ds_read_b128 v[132:135], v218 offset:1024
	ds_read_b128 v[136:139], v218 offset:2048
	ds_read_b128 v[140:143], v218 offset:3072
	ds_read_b128 v[144:147], v219
	ds_read_b128 v[148:151], v219 offset:1024
	ds_read_b128 v[152:155], v219 offset:2048
	ds_read_b128 v[156:159], v219 offset:3072
	s_add_u32 s14, s68, 0xfff80080
	s_addc_u32 s15, s69, -1
	s_cmp_eq_u32 s71, 28
	s_cselect_b32 s17, s18, s15
	s_cselect_b32 s16, s19, s14
	s_cselect_b32 s15, s41, s70
	s_cselect_b32 s14, s61, s67
	v_lshl_add_u64 v[222:223], s[68:69], 0, v[188:189]
	s_add_i32 m0, s27, 0xc000
	ds_read_b128 v[160:163], v220
	ds_read_b128 v[164:167], v220 offset:1024
	ds_read_b128 v[168:171], v220 offset:2048
	ds_read_b128 v[172:175], v220 offset:3072
	ds_read_b128 v[196:199], v220 offset:4096
	ds_read_b128 v[202:205], v220 offset:5120
	ds_read_b128 v[206:209], v220 offset:6144
	ds_read_b128 v[232:235], v220 offset:7168
	global_load_lds_dwordx4 v[222:223], off
	v_lshl_add_u64 v[222:223], s[68:69], 0, v[190:191]
	s_add_i32 m0, s27, 0xe000
	s_nop 0
	global_load_lds_dwordx4 v[222:223], off
	s_waitcnt vmcnt(8)
	s_waitcnt lgkmcnt(0)
	s_barrier
; #define PG8_STAGE(bufoff, gbase, voff) do { _Pragma("unroll") for (int _i = 0; _i < 2; ++_i) \
;         __builtin_amdgcn_global_load_lds((const unsigned*)((const char*)(gbase) + (voff)[_i]), (PG8_LAS unsigned*)(lds + (bufoff) + ldsw + _i * 8192), 16, 0, 0); } while (0)
; #define PG8_LDA(dst, b, h) do { _Pragma("unroll") for (int m = 0; m < 4; ++m) _Pragma("unroll") for (int k = 0; k < 2; ++k) dst[m][k] = *(const PG8_LAS bf16x8*)(lds + PG8_SA(b, h) + aoff + m * 2048 + k * 1024); } while (0)
; #define PG8_MMA(ai, bj, At, Bt) do { __builtin_amdgcn_s_setprio(1); _Pragma("unroll") for (int m = 0; m < 4; ++m) _Pragma("unroll") for (int n = 0; n < 2; ++n) _Pragma("unroll") for (int k = 0; k < 2; ++k) \
;         acc[ai][bj][m][n] = __builtin_amdgcn_mfma_f32_16x16x32_bf16(Bt[n][k], At[m][k], acc[ai][bj][m][n], 0, 0, 0); __builtin_amdgcn_s_setprio(0); } while (0)
; #define PG8_WAIT_V(n) asm volatile("s_waitcnt vmcnt(" #n ")" ::: "memory")
; #define PG8_WAIT_L(n) asm volatile("s_waitcnt lgkmcnt(" #n ")" ::: "memory")
; #define PG8_BAR __builtin_amdgcn_s_barrier()
; #define PG8_SCHED __builtin_amdgcn_sched_barrier(0)
; template <class Epi, class Sched, bool ALIGN_EPI = false, bool SP2 = false, bool DUAL = false>
; __device__ __forceinline__ void gemm_phase(PG8_LAS unsigned char* lds, const Gemm g, const Sched& S, const Epi& E) {
;     ...
;             PG8_WAIT_V(8); PG8_WAIT_L(0); PG8_BAR; PG8_MMA(0, 0, At, B0); PG8_MMA(0, 1, At, B1); PG8_BAR; PG8_SCHED;
;             PG8_LDA(At, 0, 1); PG8_STAGE(PG8_SB(0, 0), b2, voffB); PG8_STAGE(PG8_SB(0, 1), b2 + hstep, voffB); PG8_STAGE(PG8_SA(0, 0), a2, voffA);
;             PG8_WAIT_V(8); PG8_WAIT_L(0); PG8_BAR; PG8_MMA(1, 0, At, B0); PG8_MMA(1, 1, At, B1); PG8_BAR; PG8_SCHED;
	s_setprio 1
	s_waitcnt lgkmcnt(0)
	v_mfma_f32_16x16x32_bf16 v[124:127], v[128:131], v[160:163], v[124:127]
	v_mfma_f32_16x16x32_bf16 v[120:123], v[136:139], v[160:163], v[120:123]
	v_mfma_f32_16x16x32_bf16 v[108:111], v[128:131], v[168:171], v[108:111]
	v_mfma_f32_16x16x32_bf16 v[104:107], v[136:139], v[168:171], v[104:107]
	v_mfma_f32_16x16x32_bf16 v[92:95], v[128:131], v[196:199], v[92:95]
	v_mfma_f32_16x16x32_bf16 v[88:91], v[136:139], v[196:199], v[88:91]
	v_mfma_f32_16x16x32_bf16 v[76:79], v[128:131], v[206:209], v[76:79]
	v_mfma_f32_16x16x32_bf16 v[72:75], v[136:139], v[206:209], v[72:75]
	v_mfma_f32_16x16x32_bf16 v[124:127], v[132:135], v[164:167], v[124:127]
	v_mfma_f32_16x16x32_bf16 v[120:123], v[140:143], v[164:167], v[120:123]
	v_mfma_f32_16x16x32_bf16 v[108:111], v[132:135], v[172:175], v[108:111]
	v_mfma_f32_16x16x32_bf16 v[104:107], v[140:143], v[172:175], v[104:107]
	v_mfma_f32_16x16x32_bf16 v[92:95], v[132:135], v[202:205], v[92:95]
	v_mfma_f32_16x16x32_bf16 v[88:91], v[140:143], v[202:205], v[88:91]
	v_mfma_f32_16x16x32_bf16 v[76:79], v[132:135], v[232:235], v[76:79]
	v_mfma_f32_16x16x32_bf16 v[72:75], v[140:143], v[232:235], v[72:75]
	s_setprio 0
	s_setprio 1
	v_mfma_f32_16x16x32_bf16 v[116:119], v[144:147], v[160:163], v[116:119]
	v_mfma_f32_16x16x32_bf16 v[112:115], v[152:155], v[160:163], v[112:115]
	v_mfma_f32_16x16x32_bf16 v[100:103], v[144:147], v[168:171], v[100:103]
	v_mfma_f32_16x16x32_bf16 v[96:99], v[152:155], v[168:171], v[96:99]
	v_mfma_f32_16x16x32_bf16 v[84:87], v[144:147], v[196:199], v[84:87]
	v_mfma_f32_16x16x32_bf16 v[80:83], v[152:155], v[196:199], v[80:83]
	v_mfma_f32_16x16x32_bf16 v[68:71], v[144:147], v[206:209], v[68:71]
	v_mfma_f32_16x16x32_bf16 v[64:67], v[152:155], v[206:209], v[64:67]
	v_mfma_f32_16x16x32_bf16 v[116:119], v[148:151], v[164:167], v[116:119]
	v_mfma_f32_16x16x32_bf16 v[112:115], v[156:159], v[164:167], v[112:115]
	v_mfma_f32_16x16x32_bf16 v[100:103], v[148:151], v[172:175], v[100:103]
	v_mfma_f32_16x16x32_bf16 v[96:99], v[156:159], v[172:175], v[96:99]
	v_mfma_f32_16x16x32_bf16 v[84:87], v[148:151], v[202:205], v[84:87]
	v_mfma_f32_16x16x32_bf16 v[80:83], v[156:159], v[202:205], v[80:83]
	v_mfma_f32_16x16x32_bf16 v[68:71], v[148:151], v[232:235], v[68:71]
	v_mfma_f32_16x16x32_bf16 v[64:67], v[156:159], v[232:235], v[64:67]
	s_setprio 0
	s_barrier
	s_add_i32 s72, s48, s26
	v_lshl_add_u64 v[222:223], s[14:15], 0, v[182:183]
	s_mov_b32 m0, s72
	ds_read_b128 v[160:163], v220 offset:16384
	ds_read_b128 v[164:167], v220 offset:17408
	ds_read_b128 v[168:171], v220 offset:18432
	ds_read_b128 v[172:175], v220 offset:19456
	ds_read_b128 v[196:199], v220 offset:20480
	ds_read_b128 v[202:205], v220 offset:21504
	ds_read_b128 v[206:209], v220 offset:22528
	ds_read_b128 v[232:235], v220 offset:23552
	global_load_lds_dwordx4 v[222:223], off
	s_add_i32 m0, s72, 0x2000
	s_add_u32 s72, s14, 0x80000
	v_lshl_add_u64 v[228:229], s[14:15], 0, v[186:187]
	s_addc_u32 s73, s15, 0
	s_add_i32 s74, s49, s26
	global_load_lds_dwordx4 v[228:229], off
	v_lshl_add_u64 v[236:237], s[72:73], 0, v[182:183]
	s_mov_b32 m0, s74
	v_lshl_add_u64 v[238:239], s[16:17], 0, v[184:185]
	global_load_lds_dwordx4 v[236:237], off
	v_lshl_add_u64 v[236:237], s[72:73], 0, v[186:187]
	s_add_i32 m0, s74, 0x2000
	s_nop 0
	global_load_lds_dwordx4 v[236:237], off
	v_lshl_add_u64 v[236:237], s[16:17], 0, v[180:181]
	s_mov_b32 m0, s27
	s_nop 0
	global_load_lds_dwordx4 v[236:237], off
	s_mov_b32 m0, s28
	s_nop 0
	global_load_lds_dwordx4 v[238:239], off
	s_waitcnt vmcnt(8)
	s_waitcnt lgkmcnt(0)
	s_barrier
	s_setprio 1
	s_waitcnt lgkmcnt(0)
	v_mfma_f32_16x16x32_bf16 v[60:63], v[128:131], v[160:163], v[60:63]
	v_mfma_f32_16x16x32_bf16 v[56:59], v[136:139], v[160:163], v[56:59]
	v_mfma_f32_16x16x32_bf16 v[44:47], v[128:131], v[168:171], v[44:47]
	v_mfma_f32_16x16x32_bf16 v[40:43], v[136:139], v[168:171], v[40:43]
	v_mfma_f32_16x16x32_bf16 v[28:31], v[128:131], v[196:199], v[28:31]
	v_mfma_f32_16x16x32_bf16 v[24:27], v[136:139], v[196:199], v[24:27]
	v_mfma_f32_16x16x32_bf16 v[12:15], v[128:131], v[206:209], v[12:15]
	v_mfma_f32_16x16x32_bf16 v[8:11], v[136:139], v[206:209], v[8:11]
	v_mfma_f32_16x16x32_bf16 v[60:63], v[132:135], v[164:167], v[60:63]
	v_mfma_f32_16x16x32_bf16 v[56:59], v[140:143], v[164:167], v[56:59]
	v_mfma_f32_16x16x32_bf16 v[44:47], v[132:135], v[172:175], v[44:47]
	v_mfma_f32_16x16x32_bf16 v[40:43], v[140:143], v[172:175], v[40:43]
	v_mfma_f32_16x16x32_bf16 v[28:31], v[132:135], v[202:205], v[28:31]
	v_mfma_f32_16x16x32_bf16 v[24:27], v[140:143], v[202:205], v[24:27]
	v_mfma_f32_16x16x32_bf16 v[12:15], v[132:135], v[232:235], v[12:15]
	v_mfma_f32_16x16x32_bf16 v[8:11], v[140:143], v[232:235], v[8:11]
	s_setprio 0
	s_setprio 1
	v_mfma_f32_16x16x32_bf16 v[52:55], v[144:147], v[160:163], v[52:55]
	v_mfma_f32_16x16x32_bf16 v[48:51], v[152:155], v[160:163], v[48:51]
	v_mfma_f32_16x16x32_bf16 v[36:39], v[144:147], v[168:171], v[36:39]
	v_mfma_f32_16x16x32_bf16 v[32:35], v[152:155], v[168:171], v[32:35]
	v_mfma_f32_16x16x32_bf16 v[20:23], v[144:147], v[196:199], v[20:23]
	v_mfma_f32_16x16x32_bf16 v[16:19], v[152:155], v[196:199], v[16:19]
	v_mfma_f32_16x16x32_bf16 v[4:7], v[144:147], v[206:209], v[4:7]
	v_mfma_f32_16x16x32_bf16 v[0:3], v[152:155], v[206:209], v[0:3]
	v_mfma_f32_16x16x32_bf16 v[52:55], v[148:151], v[164:167], v[52:55]
	v_mfma_f32_16x16x32_bf16 v[48:51], v[156:159], v[164:167], v[48:51]
	v_mfma_f32_16x16x32_bf16 v[36:39], v[148:151], v[172:175], v[36:39]
	v_mfma_f32_16x16x32_bf16 v[32:35], v[156:159], v[172:175], v[32:35]
	v_mfma_f32_16x16x32_bf16 v[20:23], v[148:151], v[202:205], v[20:23]
	v_mfma_f32_16x16x32_bf16 v[16:19], v[156:159], v[202:205], v[16:19]
	v_mfma_f32_16x16x32_bf16 v[4:7], v[148:151], v[232:235], v[4:7]
	v_mfma_f32_16x16x32_bf16 v[0:3], v[156:159], v[232:235], v[0:3]
	s_setprio 0
	s_barrier
; #define PG8_STAGE(bufoff, gbase, voff) do { _Pragma("unroll") for (int _i = 0; _i < 2; ++_i) \
;         __builtin_amdgcn_global_load_lds((const unsigned*)((const char*)(gbase) + (voff)[_i]), (PG8_LAS unsigned*)(lds + (bufoff) + ldsw + _i * 8192), 16, 0, 0); } while (0)
; #define PG8_LDA(dst, b, h) do { _Pragma("unroll") for (int m = 0; m < 4; ++m) _Pragma("unroll") for (int k = 0; k < 2; ++k) dst[m][k] = *(const PG8_LAS bf16x8*)(lds + PG8_SA(b, h) + aoff + m * 2048 + k * 1024); } while (0)
; #define PG8_LDB(dst, b, h) do { _Pragma("unroll") for (int n = 0; n < 2; ++n) _Pragma("unroll") for (int k = 0; k < 2; ++k) dst[n][k] = *(const PG8_LAS bf16x8*)(lds + PG8_SB(b, h) + boff + n * 2048 + k * 1024); } while (0)
; #define PG8_MMA(ai, bj, At, Bt) do { __builtin_amdgcn_s_setprio(1); _Pragma("unroll") for (int m = 0; m < 4; ++m) _Pragma("unroll") for (int n = 0; n < 2; ++n) _Pragma("unroll") for (int k = 0; k < 2; ++k) \
;         acc[ai][bj][m][n] = __builtin_amdgcn_mfma_f32_16x16x32_bf16(Bt[n][k], At[m][k], acc[ai][bj][m][n], 0, 0, 0); __builtin_amdgcn_s_setprio(0); } while (0)
; #define PG8_WAIT_V(n) asm volatile("s_waitcnt vmcnt(" #n ")" ::: "memory")
; #define PG8_WAIT_L(n) asm volatile("s_waitcnt lgkmcnt(" #n ")" ::: "memory")
; #define PG8_BAR __builtin_amdgcn_s_barrier()
; #define PG8_SCHED __builtin_amdgcn_sched_barrier(0)
; template <class Epi, class Sched, bool ALIGN_EPI = false, bool SP2 = false, bool DUAL = false>
; __device__ __forceinline__ void gemm_phase(PG8_LAS unsigned char* lds, const Gemm g, const Sched& S, const Epi& E) {
;     ...
;             PG8_LDB(B0, 1, 0); PG8_LDB(B1, 1, 1); PG8_SCHED; PG8_LDA(At, 1, 0); PG8_STAGE(PG8_SA(0, 1), a2 + hstep, voffA);
;             PG8_WAIT_V(8); PG8_WAIT_L(0); PG8_BAR; PG8_MMA(0, 0, At, B0); PG8_MMA(0, 1, At, B1); PG8_BAR; PG8_SCHED;
	s_add_i32 s72, 0, 0x18000
	s_add_i32 s73, 0, 0x1c000
	v_add_u32_e32 v140, s72, v216
	v_add_u32_e32 v156, s73, v216
	ds_read_b128 v[128:131], v140
	ds_read_b128 v[132:135], v140 offset:1024
	ds_read_b128 v[136:139], v140 offset:2048
	ds_read_b128 v[140:143], v140 offset:3072
	ds_read_b128 v[144:147], v156
	ds_read_b128 v[148:151], v156 offset:1024
	ds_read_b128 v[152:155], v156 offset:2048
	ds_read_b128 v[156:159], v156 offset:3072
	s_add_u32 s16, s16, 0x80000
	s_addc_u32 s17, s17, 0
	s_mov_b32 m0, s29
	v_lshl_add_u64 v[240:241], s[16:17], 0, v[180:181]
	ds_read_b128 v[160:163], v220 offset:32768
	ds_read_b128 v[164:167], v220 offset:33792
	ds_read_b128 v[168:171], v220 offset:34816
	ds_read_b128 v[172:175], v220 offset:35840
	ds_read_b128 v[196:199], v220 offset:36864
	ds_read_b128 v[202:205], v220 offset:37888
	ds_read_b128 v[206:209], v220 offset:38912
	ds_read_b128 v[232:235], v220 offset:39936
	global_load_lds_dwordx4 v[240:241], off
	v_lshl_add_u64 v[240:241], s[16:17], 0, v[184:185]
	s_mov_b32 m0, s34
	s_nop 0
	global_load_lds_dwordx4 v[240:241], off
	s_waitcnt vmcnt(8)
	s_waitcnt lgkmcnt(0)
	s_barrier
	s_setprio 1
	s_waitcnt lgkmcnt(0)
	v_mfma_f32_16x16x32_bf16 v[124:127], v[128:131], v[160:163], v[124:127]
	v_mfma_f32_16x16x32_bf16 v[120:123], v[136:139], v[160:163], v[120:123]
	v_mfma_f32_16x16x32_bf16 v[108:111], v[128:131], v[168:171], v[108:111]
	v_mfma_f32_16x16x32_bf16 v[104:107], v[136:139], v[168:171], v[104:107]
	v_mfma_f32_16x16x32_bf16 v[92:95], v[128:131], v[196:199], v[92:95]
	v_mfma_f32_16x16x32_bf16 v[88:91], v[136:139], v[196:199], v[88:91]
	v_mfma_f32_16x16x32_bf16 v[76:79], v[128:131], v[206:209], v[76:79]
	v_mfma_f32_16x16x32_bf16 v[72:75], v[136:139], v[206:209], v[72:75]
	v_mfma_f32_16x16x32_bf16 v[124:127], v[132:135], v[164:167], v[124:127]
	v_mfma_f32_16x16x32_bf16 v[120:123], v[140:143], v[164:167], v[120:123]
	v_mfma_f32_16x16x32_bf16 v[108:111], v[132:135], v[172:175], v[108:111]
	v_mfma_f32_16x16x32_bf16 v[104:107], v[140:143], v[172:175], v[104:107]
	v_mfma_f32_16x16x32_bf16 v[92:95], v[132:135], v[202:205], v[92:95]
	v_mfma_f32_16x16x32_bf16 v[88:91], v[140:143], v[202:205], v[88:91]
	v_mfma_f32_16x16x32_bf16 v[76:79], v[132:135], v[232:235], v[76:79]
	v_mfma_f32_16x16x32_bf16 v[72:75], v[140:143], v[232:235], v[72:75]
	s_setprio 0
	s_setprio 1
	v_mfma_f32_16x16x32_bf16 v[116:119], v[144:147], v[160:163], v[116:119]
	v_mfma_f32_16x16x32_bf16 v[112:115], v[152:155], v[160:163], v[112:115]
	v_mfma_f32_16x16x32_bf16 v[100:103], v[144:147], v[168:171], v[100:103]
	v_mfma_f32_16x16x32_bf16 v[96:99], v[152:155], v[168:171], v[96:99]
	v_mfma_f32_16x16x32_bf16 v[84:87], v[144:147], v[196:199], v[84:87]
	v_mfma_f32_16x16x32_bf16 v[80:83], v[152:155], v[196:199], v[80:83]
	v_mfma_f32_16x16x32_bf16 v[68:71], v[144:147], v[206:209], v[68:71]
	v_mfma_f32_16x16x32_bf16 v[64:67], v[152:155], v[206:209], v[64:67]
	v_mfma_f32_16x16x32_bf16 v[116:119], v[148:151], v[164:167], v[116:119]
	v_mfma_f32_16x16x32_bf16 v[112:115], v[156:159], v[164:167], v[112:115]
	v_mfma_f32_16x16x32_bf16 v[100:103], v[148:151], v[172:175], v[100:103]
	v_mfma_f32_16x16x32_bf16 v[96:99], v[156:159], v[172:175], v[96:99]
	v_mfma_f32_16x16x32_bf16 v[84:87], v[148:151], v[202:205], v[84:87]
	v_mfma_f32_16x16x32_bf16 v[80:83], v[156:159], v[202:205], v[80:83]
	v_mfma_f32_16x16x32_bf16 v[68:71], v[148:151], v[232:235], v[68:71]
	v_mfma_f32_16x16x32_bf16 v[64:67], v[156:159], v[232:235], v[64:67]
	s_setprio 0
	s_barrier
; #define PG8_STAGE(bufoff, gbase, voff) do { _Pragma("unroll") for (int _i = 0; _i < 2; ++_i) \
;         __builtin_amdgcn_global_load_lds((const unsigned*)((const char*)(gbase) + (voff)[_i]), (PG8_LAS unsigned*)(lds + (bufoff) + ldsw + _i * 8192), 16, 0, 0); } while (0)
; #define PG8_LDA(dst, b, h) do { _Pragma("unroll") for (int m = 0; m < 4; ++m) _Pragma("unroll") for (int k = 0; k < 2; ++k) dst[m][k] = *(const PG8_LAS bf16x8*)(lds + PG8_SA(b, h) + aoff + m * 2048 + k * 1024); } while (0)
; #define PG8_MMA(ai, bj, At, Bt) do { __builtin_amdgcn_s_setprio(1); _Pragma("unroll") for (int m = 0; m < 4; ++m) _Pragma("unroll") for (int n = 0; n < 2; ++n) _Pragma("unroll") for (int k = 0; k < 2; ++k) \
;         acc[ai][bj][m][n] = __builtin_amdgcn_mfma_f32_16x16x32_bf16(Bt[n][k], At[m][k], acc[ai][bj][m][n], 0, 0, 0); __builtin_amdgcn_s_setprio(0); } while (0)
; #define PG8_WAIT_V(n) asm volatile("s_waitcnt vmcnt(" #n ")" ::: "memory")
; #define PG8_WAIT_L(n) asm volatile("s_waitcnt lgkmcnt(" #n ")" ::: "memory")
; #define PG8_BAR __builtin_amdgcn_s_barrier()
; #define PG8_SCHED __builtin_amdgcn_sched_barrier(0)
; template <class Epi, class Sched, bool ALIGN_EPI = false, bool SP2 = false, bool DUAL = false>
; __device__ __forceinline__ void gemm_phase(PG8_LAS unsigned char* lds, const Gemm g, const Sched& S, const Epi& E) {
;     ...
;             PG8_LDA(At, 1, 1); PG8_STAGE(PG8_SB(1, 0), b3, voffB); PG8_STAGE(PG8_SB(1, 1), b3 + hstep, voffB); PG8_STAGE(PG8_SA(1, 0), a3, voffA);
;             PG8_WAIT_V(8); PG8_WAIT_L(0); PG8_BAR; PG8_MMA(1, 0, At, B0); PG8_MMA(1, 1, At, B1); PG8_BAR; PG8_SCHED;
;     ...
;         if constexpr (ALIGN_EPI) { if (wr == 0) PG8_BAR; }
	s_add_i32 s16, s72, s26
	v_lshl_add_u64 v[222:223], v[222:223], 0, s[36:37]
	s_mov_b32 m0, s16
	ds_read_b128 v[160:163], v220 offset:49152
	ds_read_b128 v[164:167], v220 offset:50176
	ds_read_b128 v[168:171], v220 offset:51200
	ds_read_b128 v[172:175], v220 offset:52224
	ds_read_b128 v[196:199], v220 offset:53248
	ds_read_b128 v[202:205], v220 offset:54272
	ds_read_b128 v[206:209], v220 offset:55296
	ds_read_b128 v[232:235], v220 offset:56320
	global_load_lds_dwordx4 v[222:223], off
	s_add_i32 m0, s16, 0x2000
	s_add_u32 s14, s14, 0x80080
	v_lshl_add_u64 v[222:223], v[228:229], 0, s[36:37]
	s_addc_u32 s15, s15, 0
	s_add_i32 s16, s73, s26
	global_load_lds_dwordx4 v[222:223], off
	v_lshl_add_u64 v[222:223], s[14:15], 0, v[182:183]
	s_mov_b32 m0, s16
	s_nop 0
	global_load_lds_dwordx4 v[222:223], off
	v_lshl_add_u64 v[222:223], s[14:15], 0, v[186:187]
	s_add_i32 m0, s16, 0x2000
	s_nop 0
	global_load_lds_dwordx4 v[222:223], off
	v_lshl_add_u64 v[222:223], v[236:237], 0, s[36:37]
	s_mov_b32 m0, s44
	s_nop 0
	global_load_lds_dwordx4 v[222:223], off
	v_lshl_add_u64 v[222:223], v[238:239], 0, s[36:37]
	s_mov_b32 m0, s45
	s_nop 0
	global_load_lds_dwordx4 v[222:223], off
	s_waitcnt vmcnt(8)
	s_waitcnt lgkmcnt(0)
	s_barrier
	s_setprio 1
	s_waitcnt lgkmcnt(0)
	v_mfma_f32_16x16x32_bf16 v[60:63], v[128:131], v[160:163], v[60:63]
	v_mfma_f32_16x16x32_bf16 v[56:59], v[136:139], v[160:163], v[56:59]
	v_mfma_f32_16x16x32_bf16 v[44:47], v[128:131], v[168:171], v[44:47]
	v_mfma_f32_16x16x32_bf16 v[40:43], v[136:139], v[168:171], v[40:43]
	v_mfma_f32_16x16x32_bf16 v[28:31], v[128:131], v[196:199], v[28:31]
	v_mfma_f32_16x16x32_bf16 v[24:27], v[136:139], v[196:199], v[24:27]
	v_mfma_f32_16x16x32_bf16 v[12:15], v[128:131], v[206:209], v[12:15]
	v_mfma_f32_16x16x32_bf16 v[8:11], v[136:139], v[206:209], v[8:11]
	v_mfma_f32_16x16x32_bf16 v[60:63], v[132:135], v[164:167], v[60:63]
	v_mfma_f32_16x16x32_bf16 v[56:59], v[140:143], v[164:167], v[56:59]
	v_mfma_f32_16x16x32_bf16 v[44:47], v[132:135], v[172:175], v[44:47]
	v_mfma_f32_16x16x32_bf16 v[40:43], v[140:143], v[172:175], v[40:43]
	v_mfma_f32_16x16x32_bf16 v[28:31], v[132:135], v[202:205], v[28:31]
	v_mfma_f32_16x16x32_bf16 v[24:27], v[140:143], v[202:205], v[24:27]
	v_mfma_f32_16x16x32_bf16 v[12:15], v[132:135], v[232:235], v[12:15]
	v_mfma_f32_16x16x32_bf16 v[8:11], v[140:143], v[232:235], v[8:11]
	s_setprio 0
	s_setprio 1
	v_mfma_f32_16x16x32_bf16 v[52:55], v[144:147], v[160:163], v[52:55]
	v_mfma_f32_16x16x32_bf16 v[48:51], v[152:155], v[160:163], v[48:51]
	v_mfma_f32_16x16x32_bf16 v[36:39], v[144:147], v[168:171], v[36:39]
	v_mfma_f32_16x16x32_bf16 v[32:35], v[152:155], v[168:171], v[32:35]
	v_mfma_f32_16x16x32_bf16 v[20:23], v[144:147], v[196:199], v[20:23]
	v_mfma_f32_16x16x32_bf16 v[16:19], v[152:155], v[196:199], v[16:19]
	v_mfma_f32_16x16x32_bf16 v[4:7], v[144:147], v[206:209], v[4:7]
	v_mfma_f32_16x16x32_bf16 v[0:3], v[152:155], v[206:209], v[0:3]
	v_mfma_f32_16x16x32_bf16 v[52:55], v[148:151], v[164:167], v[52:55]
	v_mfma_f32_16x16x32_bf16 v[48:51], v[156:159], v[164:167], v[48:51]
	v_mfma_f32_16x16x32_bf16 v[36:39], v[148:151], v[172:175], v[36:39]
	v_mfma_f32_16x16x32_bf16 v[32:35], v[156:159], v[172:175], v[32:35]
	v_mfma_f32_16x16x32_bf16 v[20:23], v[148:151], v[202:205], v[20:23]
	v_mfma_f32_16x16x32_bf16 v[16:19], v[156:159], v[202:205], v[16:19]
	v_mfma_f32_16x16x32_bf16 v[4:7], v[148:151], v[232:235], v[4:7]
	v_mfma_f32_16x16x32_bf16 v[0:3], v[156:159], v[232:235], v[0:3]
	s_setprio 0
	s_barrier
	s_add_i32 s71, s71, 2
	s_add_u32 s68, s68, 0x100
	s_addc_u32 s69, s69, 0
	s_add_u32 s67, s67, 0x100
	s_addc_u32 s70, s70, 0
	s_cmp_gt_u32 s71, 29
	s_cbranch_scc0 .LBB0_896
	s_and_b64 vcc, exec, s[38:39]
	s_cbranch_vccz .LBB0_899
	s_barrier

; #define PG8_STAGE(bufoff, gbase, voff) do { _Pragma("unroll") for (int _i = 0; _i < 2; ++_i) \
;         __builtin_amdgcn_global_load_lds((const unsigned*)((const char*)(gbase) + (voff)[_i]), (PG8_LAS unsigned*)(lds + (bufoff) + ldsw + _i * 8192), 16, 0, 0); } while (0)
; #define PG8_WAIT_V(n) asm volatile("s_waitcnt vmcnt(" #n ")" ::: "memory")
; #define PG8_BAR __builtin_amdgcn_s_barrier()
; template <class Epi, class Sched, bool ALIGN_EPI = false, bool SP2 = false, bool DUAL = false>
; __device__ __forceinline__ void gemm_phase(PG8_LAS unsigned char* lds, const Gemm g, const Sched& S, const Epi& E) {
;     ...
;     if constexpr (SP2) {
;         PG8_STAGE(PG8_SB(0, 0), cB, voffB); PG8_STAGE(PG8_SB(0, 1), cB + hstep, voffB); PG8_STAGE(PG8_SA(0, 0), cA, voffA); PG8_STAGE(PG8_SA(0, 1), cA + hstep, voffA);
;         if (wr == 1) PG8_BAR;
;         PG8_WAIT_V(2); PG8_BAR;
;         PG8_STAGE(PG8_SB(1, 0), cB + kstep, voffB); PG8_STAGE(PG8_SA(1, 0), cA + kstep, voffA); PG8_STAGE(PG8_SB(1, 1), cB + hstep + kstep, voffB);
;         PG8_WAIT_V(6); PG8_BAR;
.LBB0_982:
	s_add_u32 s10, s58, 0x8100000
	s_addc_u32 s11, s59, 0
	s_lshl_b32 s12, s12, 5
	s_and_b32 s18, s12, 0x60
	s_mov_b64 s[12:13], 0x80
	s_add_i32 m0, s39, 0x18000
	v_lshl_add_u64 v[6:7], v[6:7], 0, s[12:13]
	s_ashr_i32 s46, s92, 31
	s_lshl_b32 s17, s16, 13
	s_lshl_b32 s20, s18, 7
	s_waitcnt vmcnt(2)
	s_barrier
	global_load_lds_dwordx4 v[6:7], off
	v_lshl_add_u64 v[4:5], v[4:5], 0, s[12:13]
	s_add_i32 m0, s39, 0x1a000
	s_add_i32 s47, s39, 0x8000
	s_add_i32 s48, s39, 0xa000
	global_load_lds_dwordx4 v[4:5], off
	v_lshl_add_u64 v[0:1], v[0:1], 0, s[12:13]
	s_mov_b32 m0, s47
	s_add_u32 s22, s14, 0x80080
	global_load_lds_dwordx4 v[0:1], off
	v_lshl_add_u64 v[0:1], v[2:3], 0, s[12:13]
	s_mov_b32 m0, s48
	s_addc_u32 s23, s15, 0
	global_load_lds_dwordx4 v[0:1], off
	s_add_i32 m0, s39, 0x1c000
	v_lshl_add_u64 v[0:1], s[22:23], 0, v[170:171]
	global_load_lds_dwordx4 v[0:1], off
	v_lshl_add_u64 v[0:1], s[22:23], 0, v[174:175]
	s_add_i32 m0, s39, 0x1e000
	s_sext_i32_i16 s62, s4
	global_load_lds_dwordx4 v[0:1], off
	v_lshlrev_b32_e32 v3, 1, v11
	v_lshlrev_b32_e32 v0, 6, v200
	s_movk_i32 s4, 0x3c0
	v_and_or_b32 v4, v0, s4, v3
	v_lshlrev_b32_e32 v0, 2, v11
	v_mov_b32_e32 v1, v171
	v_lshl_add_u64 v[0:1], s[58:59], 0, v[0:1]
	s_mov_b64 s[22:23], 0x3b260400
	v_and_b32_e32 v2, 15, v200
	v_lshl_add_u64 v[178:179], v[0:1], 0, s[22:23]
	v_lshlrev_b32_e32 v1, 9, v200
	v_lshl_or_b32 v212, s16, 6, v2
	v_lshl_or_b32 v0, v2, 6, v3
	v_and_b32_e32 v1, 0x70000, v1
	v_lshlrev_b32_e32 v2, 12, v10
	v_or3_b32 v1, v8, v1, v2
	v_and_b32_e32 v5, 32, v211
	v_add_u32_e32 v180, v1, v9
	v_lshlrev_b32_e32 v1, 5, v12
	v_bitop3_b32 v0, v0, s17, v5 bitop3:0xde
	s_waitcnt vmcnt(6)
	s_cmpk_lt_u32 s5, 0x100
	v_and_b32_e32 v1, 0xf0000, v1
	v_bitop3_b32 v213, s20, v4, v5 bitop3:0xf6
	s_cselect_b64 s[16:17], -1, 0
	v_or3_b32 v1, v8, v1, v2
	s_add_i32 s50, 0, 0x10000
	s_add_i32 s51, 0, 0x14000
	v_add_u32_e32 v217, 0, v0
	v_mbcnt_lo_u32_b32 v0, -1, 0
	s_mov_b32 s49, s92
	v_or_b32_e32 v214, s18, v11
	v_mov_b32_e32 v181, v171
	v_add_u32_e32 v182, v1, v9
	v_mov_b32_e32 v183, v171
	v_mov_b64_e32 v[184:185], 0x162c
	v_mov_b64_e32 v[186:187], 0x162b
	v_add_u32_e32 v215, s50, v213
	v_add_u32_e32 v216, s51, v213
	v_mbcnt_hi_u32_b32 v218, -1, v0
	s_movk_i32 s60, 0x2c00
	s_mov_b32 s18, 0x3a000000
	s_mov_b32 s20, 0x358637bd
	s_mov_b32 s61, 0x800000
	s_barrier
	s_branch .LBB0_985

;     __device__ bool next(int i, Unit& u) const { if (!base.next(i >> 1, u)) return false; u.sub = i & 1; return true; }
; #define PG8_STAGE(bufoff, gbase, voff) do { _Pragma("unroll") for (int _i = 0; _i < 2; ++_i) \
;         __builtin_amdgcn_global_load_lds((const unsigned*)((const char*)(gbase) + (voff)[_i]), (PG8_LAS unsigned*)(lds + (bufoff) + ldsw + _i * 8192), 16, 0, 0); } while (0)
; #define PG8_LDA(dst, b, h) do { _Pragma("unroll") for (int m = 0; m < 4; ++m) _Pragma("unroll") for (int k = 0; k < 2; ++k) dst[m][k] = *(const PG8_LAS bf16x8*)(lds + PG8_SA(b, h) + aoff + m * 2048 + k * 1024); } while (0)
; #define PG8_LDB(dst, b, h) do { _Pragma("unroll") for (int n = 0; n < 2; ++n) _Pragma("unroll") for (int k = 0; k < 2; ++k) dst[n][k] = *(const PG8_LAS bf16x8*)(lds + PG8_SB(b, h) + boff + n * 2048 + k * 1024); } while (0)
; #define PG8_WAIT_V(n) asm volatile("s_waitcnt vmcnt(" #n ")" ::: "memory")
; template <class Epi, class Sched, bool ALIGN_EPI = false, bool SP2 = false, bool DUAL = false>
; __device__ __forceinline__ void gemm_phase(PG8_LAS unsigned char* lds, const Gemm g, const Sched& S, const Epi& E) {
;     ...
;         const bool has_next = S.next(ui + 1, nxt);
;         const char* nA = has_next ? (const char*)((DUAL && nxt.sub) ? g.A2 : g.A) + (size_t)nxt.pm * tstep : cA; const char* nB = has_next ? (const char*)((DUAL && nxt.sub) ? g.Bt2 : g.Bt) + (size_t)nxt.pn * tstep : cB;
;         for (int t = 0; t < nt; t += 2) {
;             const bool last = (t == nt - 2);
;             const char* a1 = cA + (size_t)(t + 1) * kstep;
;             const char* a2 = last ? nA : cA + (size_t)(t + 2) * kstep; const char* b2 = last ? nB : cB + (size_t)(t + 2) * kstep;
;             const char* a3 = a2 + kstep; const char* b3 = b2 + kstep;
;             if (last && has_next) S.a_ready(nxt);
;             if constexpr (SP2) {
;             PG8_LDB(B0, 0, 0); PG8_LDB(B1, 0, 1); PG8_SCHED; PG8_LDA(At, 0, 0); PG8_STAGE(PG8_SA(1, 1), a1 + hstep, voffA);
;             PG8_WAIT_V(8); PG8_WAIT_L(0); PG8_BAR; PG8_MMA(0, 0, At, B0); PG8_MMA(0, 1, At, B1); PG8_BAR; PG8_SCHED;
;             PG8_LDA(At, 0, 1); PG8_STAGE(PG8_SB(0, 0), b2, voffB); PG8_STAGE(PG8_SB(0, 1), b2 + hstep, voffB); PG8_STAGE(PG8_SA(0, 0), a2, voffA);
;             PG8_WAIT_V(8); PG8_WAIT_L(0); PG8_BAR; PG8_MMA(1, 0, At, B0); PG8_MMA(1, 1, At, B1); PG8_BAR; PG8_SCHED;
.LBB0_991:
	s_ashr_i32 s25, s24, 31
	s_lshl_b64 s[28:29], s[24:25], 20
	s_add_u32 s30, s19, s28
	s_addc_u32 s31, s21, s29
	s_and_b64 s[28:29], s[4:5], exec
	s_cselect_b32 s25, s31, s27
	s_cselect_b32 s28, s30, s26
	s_ashr_i32 s23, s22, 31
	s_lshl_b64 s[36:37], s[22:23], 20
	s_add_u32 s36, s8, s36
	s_addc_u32 s37, s9, s37
	s_and_b64 s[40:41], s[4:5], exec
	s_cselect_b32 s23, s37, s15
	s_cselect_b32 s29, s36, s14
	s_add_u32 s40, s26, 0x80080
	s_addc_u32 s41, s27, 0
	s_add_u32 s63, s14, 0x100
	s_addc_u32 s64, s15, 0
	s_mov_b32 s65, -2
	ds_read_b128 v[128:131], v215
	ds_read_b128 v[132:135], v215 offset:1024
	ds_read_b128 v[136:139], v215 offset:2048
	ds_read_b128 v[140:143], v215 offset:3072
	ds_read_b128 v[144:147], v216
	ds_read_b128 v[148:151], v216 offset:1024
	ds_read_b128 v[152:155], v216 offset:2048
	ds_read_b128 v[156:159], v216 offset:3072
	s_add_u32 s14, s40, 0xfff80080
	s_addc_u32 s15, s41, -1
	s_cmp_eq_u32 s65, 28
	s_cselect_b32 s27, s25, s15
	s_cselect_b32 s26, s28, s14
	s_cselect_b32 s15, s23, s64
	s_cselect_b32 s14, s29, s63
	v_lshl_add_u64 v[228:229], s[40:41], 0, v[180:181]
	s_add_i32 m0, s39, 0xc000
	ds_read_b128 v[160:163], v217
	ds_read_b128 v[164:167], v217 offset:1024
	ds_read_b128 v[188:191], v217 offset:2048
	ds_read_b128 v[192:195], v217 offset:3072
	ds_read_b128 v[196:199], v217 offset:4096
	ds_read_b128 v[202:205], v217 offset:5120
	ds_read_b128 v[206:209], v217 offset:6144
	ds_read_b128 v[220:223], v217 offset:7168
	global_load_lds_dwordx4 v[228:229], off
	v_lshl_add_u64 v[228:229], s[40:41], 0, v[182:183]
	s_add_i32 m0, s39, 0xe000
	s_nop 0
	global_load_lds_dwordx4 v[228:229], off
	s_waitcnt vmcnt(8)
	s_waitcnt lgkmcnt(0)
	s_barrier
	s_setprio 1
	s_waitcnt lgkmcnt(0)
	v_mfma_f32_16x16x32_bf16 v[124:127], v[128:131], v[160:163], 0
	v_mfma_f32_16x16x32_bf16 v[120:123], v[136:139], v[160:163], 0
	v_mfma_f32_16x16x32_bf16 v[108:111], v[128:131], v[188:191], 0
	v_mfma_f32_16x16x32_bf16 v[104:107], v[136:139], v[188:191], 0
	v_mfma_f32_16x16x32_bf16 v[92:95], v[128:131], v[196:199], 0
	v_mfma_f32_16x16x32_bf16 v[88:91], v[136:139], v[196:199], 0
	v_mfma_f32_16x16x32_bf16 v[76:79], v[128:131], v[206:209], 0
	v_mfma_f32_16x16x32_bf16 v[72:75], v[136:139], v[206:209], 0
	v_mfma_f32_16x16x32_bf16 v[124:127], v[132:135], v[164:167], v[124:127]
	v_mfma_f32_16x16x32_bf16 v[120:123], v[140:143], v[164:167], v[120:123]
	v_mfma_f32_16x16x32_bf16 v[108:111], v[132:135], v[192:195], v[108:111]
	v_mfma_f32_16x16x32_bf16 v[104:107], v[140:143], v[192:195], v[104:107]
	v_mfma_f32_16x16x32_bf16 v[92:95], v[132:135], v[202:205], v[92:95]
	v_mfma_f32_16x16x32_bf16 v[88:91], v[140:143], v[202:205], v[88:91]
	v_mfma_f32_16x16x32_bf16 v[76:79], v[132:135], v[220:223], v[76:79]
	v_mfma_f32_16x16x32_bf16 v[72:75], v[140:143], v[220:223], v[72:75]
	s_setprio 0
	s_setprio 1
	v_mfma_f32_16x16x32_bf16 v[116:119], v[144:147], v[160:163], 0
	v_mfma_f32_16x16x32_bf16 v[112:115], v[152:155], v[160:163], 0
	v_mfma_f32_16x16x32_bf16 v[100:103], v[144:147], v[188:191], 0
	v_mfma_f32_16x16x32_bf16 v[96:99], v[152:155], v[188:191], 0
	v_mfma_f32_16x16x32_bf16 v[84:87], v[144:147], v[196:199], 0
	v_mfma_f32_16x16x32_bf16 v[80:83], v[152:155], v[196:199], 0
	v_mfma_f32_16x16x32_bf16 v[68:71], v[144:147], v[206:209], 0
	v_mfma_f32_16x16x32_bf16 v[64:67], v[152:155], v[206:209], 0
	v_mfma_f32_16x16x32_bf16 v[116:119], v[148:151], v[164:167], v[116:119]
	v_mfma_f32_16x16x32_bf16 v[112:115], v[156:159], v[164:167], v[112:115]
	v_mfma_f32_16x16x32_bf16 v[100:103], v[148:151], v[192:195], v[100:103]
	v_mfma_f32_16x16x32_bf16 v[96:99], v[156:159], v[192:195], v[96:99]
	v_mfma_f32_16x16x32_bf16 v[84:87], v[148:151], v[202:205], v[84:87]
	v_mfma_f32_16x16x32_bf16 v[80:83], v[156:159], v[202:205], v[80:83]
	v_mfma_f32_16x16x32_bf16 v[68:71], v[148:151], v[220:223], v[68:71]
	v_mfma_f32_16x16x32_bf16 v[64:67], v[156:159], v[220:223], v[64:67]
	s_setprio 0
	s_barrier
	s_add_i32 s66, s50, s34
	v_lshl_add_u64 v[228:229], s[14:15], 0, v[170:171]
	s_mov_b32 m0, s66
	ds_read_b128 v[160:163], v217 offset:16384
	ds_read_b128 v[164:167], v217 offset:17408
	ds_read_b128 v[188:191], v217 offset:18432
	ds_read_b128 v[192:195], v217 offset:19456
	ds_read_b128 v[196:199], v217 offset:20480
	ds_read_b128 v[202:205], v217 offset:21504
	ds_read_b128 v[206:209], v217 offset:22528
	ds_read_b128 v[220:223], v217 offset:23552
	global_load_lds_dwordx4 v[228:229], off
	s_add_i32 m0, s66, 0x2000
	s_add_u32 s66, s14, 0x80000
	v_lshl_add_u64 v[232:233], s[14:15], 0, v[174:175]
	s_addc_u32 s67, s15, 0
	s_add_i32 s68, s51, s34
	global_load_lds_dwordx4 v[232:233], off
	v_lshl_add_u64 v[234:235], s[66:67], 0, v[170:171]
	s_mov_b32 m0, s68
	v_lshl_add_u64 v[236:237], s[26:27], 0, v[172:173]
	global_load_lds_dwordx4 v[234:235], off
	v_lshl_add_u64 v[234:235], s[66:67], 0, v[174:175]
	s_add_i32 m0, s68, 0x2000
	s_nop 0
	global_load_lds_dwordx4 v[234:235], off
	v_lshl_add_u64 v[234:235], s[26:27], 0, v[168:169]
	s_mov_b32 m0, s39
	s_nop 0
	global_load_lds_dwordx4 v[234:235], off
	s_mov_b32 m0, s42
	s_nop 0
	global_load_lds_dwordx4 v[236:237], off
	s_waitcnt vmcnt(8)
	s_waitcnt lgkmcnt(0)
	s_barrier
; #define PG8_STAGE(bufoff, gbase, voff) do { _Pragma("unroll") for (int _i = 0; _i < 2; ++_i) \
;         __builtin_amdgcn_global_load_lds((const unsigned*)((const char*)(gbase) + (voff)[_i]), (PG8_LAS unsigned*)(lds + (bufoff) + ldsw + _i * 8192), 16, 0, 0); } while (0)
; #define PG8_LDA(dst, b, h) do { _Pragma("unroll") for (int m = 0; m < 4; ++m) _Pragma("unroll") for (int k = 0; k < 2; ++k) dst[m][k] = *(const PG8_LAS bf16x8*)(lds + PG8_SA(b, h) + aoff + m * 2048 + k * 1024); } while (0)
; #define PG8_LDB(dst, b, h) do { _Pragma("unroll") for (int n = 0; n < 2; ++n) _Pragma("unroll") for (int k = 0; k < 2; ++k) dst[n][k] = *(const PG8_LAS bf16x8*)(lds + PG8_SB(b, h) + boff + n * 2048 + k * 1024); } while (0)
; #define PG8_MMA(ai, bj, At, Bt) do { __builtin_amdgcn_s_setprio(1); _Pragma("unroll") for (int m = 0; m < 4; ++m) _Pragma("unroll") for (int n = 0; n < 2; ++n) _Pragma("unroll") for (int k = 0; k < 2; ++k) \
;         acc[ai][bj][m][n] = __builtin_amdgcn_mfma_f32_16x16x32_bf16(Bt[n][k], At[m][k], acc[ai][bj][m][n], 0, 0, 0); __builtin_amdgcn_s_setprio(0); } while (0)
; #define PG8_WAIT_V(n) asm volatile("s_waitcnt vmcnt(" #n ")" ::: "memory")
; #define PG8_WAIT_L(n) asm volatile("s_waitcnt lgkmcnt(" #n ")" ::: "memory")
; #define PG8_BAR __builtin_amdgcn_s_barrier()
; #define PG8_SCHED __builtin_amdgcn_sched_barrier(0)
; template <class Epi, class Sched, bool ALIGN_EPI = false, bool SP2 = false, bool DUAL = false>
; __device__ __forceinline__ void gemm_phase(PG8_LAS unsigned char* lds, const Gemm g, const Sched& S, const Epi& E) {
;     ...
;             PG8_WAIT_V(8); PG8_WAIT_L(0); PG8_BAR; PG8_MMA(1, 0, At, B0); PG8_MMA(1, 1, At, B1); PG8_BAR; PG8_SCHED;
;             PG8_LDB(B0, 1, 0); PG8_LDB(B1, 1, 1); PG8_SCHED; PG8_LDA(At, 1, 0); PG8_STAGE(PG8_SA(0, 1), a2 + hstep, voffA);
;             PG8_WAIT_V(8); PG8_WAIT_L(0); PG8_BAR; PG8_MMA(0, 0, At, B0); PG8_MMA(0, 1, At, B1); PG8_BAR; PG8_SCHED;
	s_setprio 1
	s_waitcnt lgkmcnt(0)
	v_mfma_f32_16x16x32_bf16 v[60:63], v[128:131], v[160:163], 0
	v_mfma_f32_16x16x32_bf16 v[56:59], v[136:139], v[160:163], 0
	v_mfma_f32_16x16x32_bf16 v[44:47], v[128:131], v[188:191], 0
	v_mfma_f32_16x16x32_bf16 v[40:43], v[136:139], v[188:191], 0
	v_mfma_f32_16x16x32_bf16 v[28:31], v[128:131], v[196:199], 0
	v_mfma_f32_16x16x32_bf16 v[24:27], v[136:139], v[196:199], 0
	v_mfma_f32_16x16x32_bf16 v[12:15], v[128:131], v[206:209], 0
	v_mfma_f32_16x16x32_bf16 v[8:11], v[136:139], v[206:209], 0
	v_mfma_f32_16x16x32_bf16 v[60:63], v[132:135], v[164:167], v[60:63]
	v_mfma_f32_16x16x32_bf16 v[56:59], v[140:143], v[164:167], v[56:59]
	v_mfma_f32_16x16x32_bf16 v[44:47], v[132:135], v[192:195], v[44:47]
	v_mfma_f32_16x16x32_bf16 v[40:43], v[140:143], v[192:195], v[40:43]
	v_mfma_f32_16x16x32_bf16 v[28:31], v[132:135], v[202:205], v[28:31]
	v_mfma_f32_16x16x32_bf16 v[24:27], v[140:143], v[202:205], v[24:27]
	v_mfma_f32_16x16x32_bf16 v[12:15], v[132:135], v[220:223], v[12:15]
	v_mfma_f32_16x16x32_bf16 v[8:11], v[140:143], v[220:223], v[8:11]
	s_setprio 0
	s_setprio 1
	v_mfma_f32_16x16x32_bf16 v[52:55], v[144:147], v[160:163], 0
	v_mfma_f32_16x16x32_bf16 v[48:51], v[152:155], v[160:163], 0
	v_mfma_f32_16x16x32_bf16 v[36:39], v[144:147], v[188:191], 0
	v_mfma_f32_16x16x32_bf16 v[32:35], v[152:155], v[188:191], 0
	v_mfma_f32_16x16x32_bf16 v[20:23], v[144:147], v[196:199], 0
	v_mfma_f32_16x16x32_bf16 v[16:19], v[152:155], v[196:199], 0
	v_mfma_f32_16x16x32_bf16 v[4:7], v[144:147], v[206:209], 0
	v_mfma_f32_16x16x32_bf16 v[0:3], v[152:155], v[206:209], 0
	v_mfma_f32_16x16x32_bf16 v[52:55], v[148:151], v[164:167], v[52:55]
	v_mfma_f32_16x16x32_bf16 v[48:51], v[156:159], v[164:167], v[48:51]
	v_mfma_f32_16x16x32_bf16 v[36:39], v[148:151], v[192:195], v[36:39]
	v_mfma_f32_16x16x32_bf16 v[32:35], v[156:159], v[192:195], v[32:35]
	v_mfma_f32_16x16x32_bf16 v[20:23], v[148:151], v[202:205], v[20:23]
	v_mfma_f32_16x16x32_bf16 v[16:19], v[156:159], v[202:205], v[16:19]
	v_mfma_f32_16x16x32_bf16 v[4:7], v[148:151], v[220:223], v[4:7]
	v_mfma_f32_16x16x32_bf16 v[0:3], v[156:159], v[220:223], v[0:3]
	s_setprio 0
	s_barrier
	s_add_i32 s66, 0, 0x18000
	s_add_i32 s67, 0, 0x1c000
	v_add_u32_e32 v140, s66, v213
	v_add_u32_e32 v156, s67, v213
	ds_read_b128 v[128:131], v140
	ds_read_b128 v[132:135], v140 offset:1024
	ds_read_b128 v[136:139], v140 offset:2048
	ds_read_b128 v[140:143], v140 offset:3072
	ds_read_b128 v[144:147], v156
	ds_read_b128 v[148:151], v156 offset:1024
	ds_read_b128 v[152:155], v156 offset:2048
	ds_read_b128 v[156:159], v156 offset:3072
	s_add_u32 s26, s26, 0x80000
	s_addc_u32 s27, s27, 0
	s_mov_b32 m0, s43
	v_lshl_add_u64 v[238:239], s[26:27], 0, v[168:169]
	ds_read_b128 v[160:163], v217 offset:32768
	ds_read_b128 v[164:167], v217 offset:33792
	ds_read_b128 v[188:191], v217 offset:34816
	ds_read_b128 v[192:195], v217 offset:35840
	ds_read_b128 v[196:199], v217 offset:36864
	ds_read_b128 v[202:205], v217 offset:37888
	ds_read_b128 v[206:209], v217 offset:38912
	ds_read_b128 v[220:223], v217 offset:39936
	global_load_lds_dwordx4 v[238:239], off
	v_lshl_add_u64 v[238:239], s[26:27], 0, v[172:173]
	s_mov_b32 m0, s44
	s_nop 0
	global_load_lds_dwordx4 v[238:239], off
	s_waitcnt vmcnt(8)
	s_waitcnt lgkmcnt(0)
	s_barrier
	s_setprio 1
	s_waitcnt lgkmcnt(0)
	v_mfma_f32_16x16x32_bf16 v[124:127], v[128:131], v[160:163], v[124:127]
	v_mfma_f32_16x16x32_bf16 v[120:123], v[136:139], v[160:163], v[120:123]
	v_mfma_f32_16x16x32_bf16 v[108:111], v[128:131], v[188:191], v[108:111]
	v_mfma_f32_16x16x32_bf16 v[104:107], v[136:139], v[188:191], v[104:107]
	v_mfma_f32_16x16x32_bf16 v[92:95], v[128:131], v[196:199], v[92:95]
	v_mfma_f32_16x16x32_bf16 v[88:91], v[136:139], v[196:199], v[88:91]
	v_mfma_f32_16x16x32_bf16 v[76:79], v[128:131], v[206:209], v[76:79]
	v_mfma_f32_16x16x32_bf16 v[72:75], v[136:139], v[206:209], v[72:75]
	v_mfma_f32_16x16x32_bf16 v[124:127], v[132:135], v[164:167], v[124:127]
	v_mfma_f32_16x16x32_bf16 v[120:123], v[140:143], v[164:167], v[120:123]
	v_mfma_f32_16x16x32_bf16 v[108:111], v[132:135], v[192:195], v[108:111]
	v_mfma_f32_16x16x32_bf16 v[104:107], v[140:143], v[192:195], v[104:107]
	v_mfma_f32_16x16x32_bf16 v[92:95], v[132:135], v[202:205], v[92:95]
	v_mfma_f32_16x16x32_bf16 v[88:91], v[140:143], v[202:205], v[88:91]
	v_mfma_f32_16x16x32_bf16 v[76:79], v[132:135], v[220:223], v[76:79]
	v_mfma_f32_16x16x32_bf16 v[72:75], v[140:143], v[220:223], v[72:75]
	s_setprio 0
	s_setprio 1
	v_mfma_f32_16x16x32_bf16 v[116:119], v[144:147], v[160:163], v[116:119]
	v_mfma_f32_16x16x32_bf16 v[112:115], v[152:155], v[160:163], v[112:115]
	v_mfma_f32_16x16x32_bf16 v[100:103], v[144:147], v[188:191], v[100:103]
	v_mfma_f32_16x16x32_bf16 v[96:99], v[152:155], v[188:191], v[96:99]
	v_mfma_f32_16x16x32_bf16 v[84:87], v[144:147], v[196:199], v[84:87]
	v_mfma_f32_16x16x32_bf16 v[80:83], v[152:155], v[196:199], v[80:83]
	v_mfma_f32_16x16x32_bf16 v[68:71], v[144:147], v[206:209], v[68:71]
	v_mfma_f32_16x16x32_bf16 v[64:67], v[152:155], v[206:209], v[64:67]
	v_mfma_f32_16x16x32_bf16 v[116:119], v[148:151], v[164:167], v[116:119]
	v_mfma_f32_16x16x32_bf16 v[112:115], v[156:159], v[164:167], v[112:115]
	v_mfma_f32_16x16x32_bf16 v[100:103], v[148:151], v[192:195], v[100:103]
	v_mfma_f32_16x16x32_bf16 v[96:99], v[156:159], v[192:195], v[96:99]
	v_mfma_f32_16x16x32_bf16 v[84:87], v[148:151], v[202:205], v[84:87]
	v_mfma_f32_16x16x32_bf16 v[80:83], v[156:159], v[202:205], v[80:83]
	v_mfma_f32_16x16x32_bf16 v[68:71], v[148:151], v[220:223], v[68:71]
	v_mfma_f32_16x16x32_bf16 v[64:67], v[156:159], v[220:223], v[64:67]
	s_setprio 0
	s_barrier
; #define PG8_STAGE(bufoff, gbase, voff) do { _Pragma("unroll") for (int _i = 0; _i < 2; ++_i) \
;         __builtin_amdgcn_global_load_lds((const unsigned*)((const char*)(gbase) + (voff)[_i]), (PG8_LAS unsigned*)(lds + (bufoff) + ldsw + _i * 8192), 16, 0, 0); } while (0)
; #define PG8_LDA(dst, b, h) do { _Pragma("unroll") for (int m = 0; m < 4; ++m) _Pragma("unroll") for (int k = 0; k < 2; ++k) dst[m][k] = *(const PG8_LAS bf16x8*)(lds + PG8_SA(b, h) + aoff + m * 2048 + k * 1024); } while (0)
; #define PG8_LDB(dst, b, h) do { _Pragma("unroll") for (int n = 0; n < 2; ++n) _Pragma("unroll") for (int k = 0; k < 2; ++k) dst[n][k] = *(const PG8_LAS bf16x8*)(lds + PG8_SB(b, h) + boff + n * 2048 + k * 1024); } while (0)
; #define PG8_MMA(ai, bj, At, Bt) do { __builtin_amdgcn_s_setprio(1); _Pragma("unroll") for (int m = 0; m < 4; ++m) _Pragma("unroll") for (int n = 0; n < 2; ++n) _Pragma("unroll") for (int k = 0; k < 2; ++k) \
;         acc[ai][bj][m][n] = __builtin_amdgcn_mfma_f32_16x16x32_bf16(Bt[n][k], At[m][k], acc[ai][bj][m][n], 0, 0, 0); __builtin_amdgcn_s_setprio(0); } while (0)
; #define PG8_BAR __builtin_amdgcn_s_barrier()
; template <class Epi, class Sched, bool ALIGN_EPI = false, bool SP2 = false, bool DUAL = false>
; __device__ __forceinline__ void gemm_phase(PG8_LAS unsigned char* lds, const Gemm g, const Sched& S, const Epi& E) {
;     ...
;             PG8_LDB(B0, 0, 0); PG8_LDB(B1, 0, 1); PG8_SCHED; PG8_LDA(At, 0, 0); PG8_STAGE(PG8_SA(1, 1), a1 + hstep, voffA);
;             PG8_WAIT_V(8); PG8_WAIT_L(0); PG8_BAR; PG8_MMA(0, 0, At, B0); PG8_MMA(0, 1, At, B1); PG8_BAR; PG8_SCHED;
;             PG8_LDA(At, 0, 1); PG8_STAGE(PG8_SB(0, 0), b2, voffB); PG8_STAGE(PG8_SB(0, 1), b2 + hstep, voffB); PG8_STAGE(PG8_SA(0, 0), a2, voffA);
;             PG8_WAIT_V(8); PG8_WAIT_L(0); PG8_BAR; PG8_MMA(1, 0, At, B0); PG8_MMA(1, 1, At, B1); PG8_BAR; PG8_SCHED;
;             PG8_LDB(B0, 1, 0); PG8_LDB(B1, 1, 1); PG8_SCHED; PG8_LDA(At, 1, 0); PG8_STAGE(PG8_SA(0, 1), a2 + hstep, voffA);
;             PG8_WAIT_V(8); PG8_WAIT_L(0); PG8_BAR; PG8_MMA(0, 0, At, B0); PG8_MMA(0, 1, At, B1); PG8_BAR; PG8_SCHED;
;             PG8_LDA(At, 1, 1); PG8_STAGE(PG8_SB(1, 0), b3, voffB); PG8_STAGE(PG8_SB(1, 1), b3 + hstep, voffB); PG8_STAGE(PG8_SA(1, 0), a3, voffA);
;             PG8_WAIT_V(8); PG8_WAIT_L(0); PG8_BAR; PG8_MMA(1, 0, At, B0); PG8_MMA(1, 1, At, B1); PG8_BAR; PG8_SCHED;
	s_add_i32 s26, s66, s34
	v_lshl_add_u64 v[228:229], v[228:229], 0, s[12:13]
	s_mov_b32 m0, s26
	ds_read_b128 v[160:163], v217 offset:49152
	ds_read_b128 v[164:167], v217 offset:50176
	ds_read_b128 v[188:191], v217 offset:51200
	ds_read_b128 v[192:195], v217 offset:52224
	ds_read_b128 v[196:199], v217 offset:53248
	ds_read_b128 v[202:205], v217 offset:54272
	ds_read_b128 v[206:209], v217 offset:55296
	ds_read_b128 v[220:223], v217 offset:56320
	global_load_lds_dwordx4 v[228:229], off
	s_add_i32 m0, s26, 0x2000
	s_add_u32 s14, s14, 0x80080
	v_lshl_add_u64 v[228:229], v[232:233], 0, s[12:13]
	s_addc_u32 s15, s15, 0
	s_add_i32 s26, s67, s34
	global_load_lds_dwordx4 v[228:229], off
	v_lshl_add_u64 v[228:229], s[14:15], 0, v[170:171]
	s_mov_b32 m0, s26
	s_nop 0
	global_load_lds_dwordx4 v[228:229], off
	v_lshl_add_u64 v[228:229], s[14:15], 0, v[174:175]
	s_add_i32 m0, s26, 0x2000
	s_nop 0
	global_load_lds_dwordx4 v[228:229], off
	v_lshl_add_u64 v[228:229], v[234:235], 0, s[12:13]
	s_mov_b32 m0, s47
	s_nop 0
	global_load_lds_dwordx4 v[228:229], off
	v_lshl_add_u64 v[228:229], v[236:237], 0, s[12:13]
	s_mov_b32 m0, s48
	s_nop 0
	global_load_lds_dwordx4 v[228:229], off
	s_waitcnt vmcnt(8)
	s_waitcnt lgkmcnt(0)
	s_barrier
	s_setprio 1
	s_waitcnt lgkmcnt(0)
	v_mfma_f32_16x16x32_bf16 v[60:63], v[128:131], v[160:163], v[60:63]
	v_mfma_f32_16x16x32_bf16 v[56:59], v[136:139], v[160:163], v[56:59]
	v_mfma_f32_16x16x32_bf16 v[44:47], v[128:131], v[188:191], v[44:47]
	v_mfma_f32_16x16x32_bf16 v[40:43], v[136:139], v[188:191], v[40:43]
	v_mfma_f32_16x16x32_bf16 v[28:31], v[128:131], v[196:199], v[28:31]
	v_mfma_f32_16x16x32_bf16 v[24:27], v[136:139], v[196:199], v[24:27]
	v_mfma_f32_16x16x32_bf16 v[12:15], v[128:131], v[206:209], v[12:15]
	v_mfma_f32_16x16x32_bf16 v[8:11], v[136:139], v[206:209], v[8:11]
	v_mfma_f32_16x16x32_bf16 v[60:63], v[132:135], v[164:167], v[60:63]
	v_mfma_f32_16x16x32_bf16 v[56:59], v[140:143], v[164:167], v[56:59]
	v_mfma_f32_16x16x32_bf16 v[44:47], v[132:135], v[192:195], v[44:47]
	v_mfma_f32_16x16x32_bf16 v[40:43], v[140:143], v[192:195], v[40:43]
	v_mfma_f32_16x16x32_bf16 v[28:31], v[132:135], v[202:205], v[28:31]
	v_mfma_f32_16x16x32_bf16 v[24:27], v[140:143], v[202:205], v[24:27]
	v_mfma_f32_16x16x32_bf16 v[12:15], v[132:135], v[220:223], v[12:15]
	v_mfma_f32_16x16x32_bf16 v[8:11], v[140:143], v[220:223], v[8:11]
	s_setprio 0
	s_setprio 1
	v_mfma_f32_16x16x32_bf16 v[52:55], v[144:147], v[160:163], v[52:55]
	v_mfma_f32_16x16x32_bf16 v[48:51], v[152:155], v[160:163], v[48:51]
	v_mfma_f32_16x16x32_bf16 v[36:39], v[144:147], v[188:191], v[36:39]
	v_mfma_f32_16x16x32_bf16 v[32:35], v[152:155], v[188:191], v[32:35]
	v_mfma_f32_16x16x32_bf16 v[20:23], v[144:147], v[196:199], v[20:23]
	v_mfma_f32_16x16x32_bf16 v[16:19], v[152:155], v[196:199], v[16:19]
	v_mfma_f32_16x16x32_bf16 v[4:7], v[144:147], v[206:209], v[4:7]
	v_mfma_f32_16x16x32_bf16 v[0:3], v[152:155], v[206:209], v[0:3]
	v_mfma_f32_16x16x32_bf16 v[52:55], v[148:151], v[164:167], v[52:55]
	v_mfma_f32_16x16x32_bf16 v[48:51], v[156:159], v[164:167], v[48:51]
	v_mfma_f32_16x16x32_bf16 v[36:39], v[148:151], v[192:195], v[36:39]
	v_mfma_f32_16x16x32_bf16 v[32:35], v[156:159], v[192:195], v[32:35]
	v_mfma_f32_16x16x32_bf16 v[20:23], v[148:151], v[202:205], v[20:23]
	v_mfma_f32_16x16x32_bf16 v[16:19], v[156:159], v[202:205], v[16:19]
	v_mfma_f32_16x16x32_bf16 v[4:7], v[148:151], v[220:223], v[4:7]
	v_mfma_f32_16x16x32_bf16 v[0:3], v[156:159], v[220:223], v[0:3]
	s_setprio 0
	s_barrier
	s_add_i32 s65, s65, 2
	s_add_u32 s40, s40, 0x100
	s_addc_u32 s41, s41, 0
	s_add_u32 s63, s63, 0x100
	s_addc_u32 s64, s64, 0
.LBB0_992:
	ds_read_b128 v[128:131], v215
	ds_read_b128 v[132:135], v215 offset:1024
	ds_read_b128 v[136:139], v215 offset:2048
	ds_read_b128 v[140:143], v215 offset:3072
	ds_read_b128 v[144:147], v216
	ds_read_b128 v[148:151], v216 offset:1024
	ds_read_b128 v[152:155], v216 offset:2048
	ds_read_b128 v[156:159], v216 offset:3072
	s_add_u32 s14, s40, 0xfff80080
	s_addc_u32 s15, s41, -1
	s_cmp_eq_u32 s65, 28
	s_cselect_b32 s27, s25, s15
	s_cselect_b32 s26, s28, s14
	s_cselect_b32 s15, s23, s64
	s_cselect_b32 s14, s29, s63
	v_lshl_add_u64 v[228:229], s[40:41], 0, v[180:181]
	s_add_i32 m0, s39, 0xc000
	ds_read_b128 v[160:163], v217
	ds_read_b128 v[164:167], v217 offset:1024
	ds_read_b128 v[188:191], v217 offset:2048
	ds_read_b128 v[192:195], v217 offset:3072
	ds_read_b128 v[196:199], v217 offset:4096
	ds_read_b128 v[202:205], v217 offset:5120
	ds_read_b128 v[206:209], v217 offset:6144
	ds_read_b128 v[220:223], v217 offset:7168
	global_load_lds_dwordx4 v[228:229], off
	v_lshl_add_u64 v[228:229], s[40:41], 0, v[182:183]
	s_add_i32 m0, s39, 0xe000
	s_nop 0
	global_load_lds_dwordx4 v[228:229], off
	s_waitcnt vmcnt(8)
	s_waitcnt lgkmcnt(0)
	s_barrier
; #define PG8_STAGE(bufoff, gbase, voff) do { _Pragma("unroll") for (int _i = 0; _i < 2; ++_i) \
;         __builtin_amdgcn_global_load_lds((const unsigned*)((const char*)(gbase) + (voff)[_i]), (PG8_LAS unsigned*)(lds + (bufoff) + ldsw + _i * 8192), 16, 0, 0); } while (0)
; #define PG8_LDA(dst, b, h) do { _Pragma("unroll") for (int m = 0; m < 4; ++m) _Pragma("unroll") for (int k = 0; k < 2; ++k) dst[m][k] = *(const PG8_LAS bf16x8*)(lds + PG8_SA(b, h) + aoff + m * 2048 + k * 1024); } while (0)
; #define PG8_MMA(ai, bj, At, Bt) do { __builtin_amdgcn_s_setprio(1); _Pragma("unroll") for (int m = 0; m < 4; ++m) _Pragma("unroll") for (int n = 0; n < 2; ++n) _Pragma("unroll") for (int k = 0; k < 2; ++k) \
;         acc[ai][bj][m][n] = __builtin_amdgcn_mfma_f32_16x16x32_bf16(Bt[n][k], At[m][k], acc[ai][bj][m][n], 0, 0, 0); __builtin_amdgcn_s_setprio(0); } while (0)
; #define PG8_WAIT_V(n) asm volatile("s_waitcnt vmcnt(" #n ")" ::: "memory")
; #define PG8_WAIT_L(n) asm volatile("s_waitcnt lgkmcnt(" #n ")" ::: "memory")
; #define PG8_BAR __builtin_amdgcn_s_barrier()
; #define PG8_SCHED __builtin_amdgcn_sched_barrier(0)
; template <class Epi, class Sched, bool ALIGN_EPI = false, bool SP2 = false, bool DUAL = false>
; __device__ __forceinline__ void gemm_phase(PG8_LAS unsigned char* lds, const Gemm g, const Sched& S, const Epi& E) {
;     ...
;             PG8_WAIT_V(8); PG8_WAIT_L(0); PG8_BAR; PG8_MMA(0, 0, At, B0); PG8_MMA(0, 1, At, B1); PG8_BAR; PG8_SCHED;
;             PG8_LDA(At, 0, 1); PG8_STAGE(PG8_SB(0, 0), b2, voffB); PG8_STAGE(PG8_SB(0, 1), b2 + hstep, voffB); PG8_STAGE(PG8_SA(0, 0), a2, voffA);
;             PG8_WAIT_V(8); PG8_WAIT_L(0); PG8_BAR; PG8_MMA(1, 0, At, B0); PG8_MMA(1, 1, At, B1); PG8_BAR; PG8_SCHED;
	s_setprio 1
	s_waitcnt lgkmcnt(0)
	v_mfma_f32_16x16x32_bf16 v[124:127], v[128:131], v[160:163], v[124:127]
	v_mfma_f32_16x16x32_bf16 v[120:123], v[136:139], v[160:163], v[120:123]
	v_mfma_f32_16x16x32_bf16 v[108:111], v[128:131], v[188:191], v[108:111]
	v_mfma_f32_16x16x32_bf16 v[104:107], v[136:139], v[188:191], v[104:107]
	v_mfma_f32_16x16x32_bf16 v[92:95], v[128:131], v[196:199], v[92:95]
	v_mfma_f32_16x16x32_bf16 v[88:91], v[136:139], v[196:199], v[88:91]
	v_mfma_f32_16x16x32_bf16 v[76:79], v[128:131], v[206:209], v[76:79]
	v_mfma_f32_16x16x32_bf16 v[72:75], v[136:139], v[206:209], v[72:75]
	v_mfma_f32_16x16x32_bf16 v[124:127], v[132:135], v[164:167], v[124:127]
	v_mfma_f32_16x16x32_bf16 v[120:123], v[140:143], v[164:167], v[120:123]
	v_mfma_f32_16x16x32_bf16 v[108:111], v[132:135], v[192:195], v[108:111]
	v_mfma_f32_16x16x32_bf16 v[104:107], v[140:143], v[192:195], v[104:107]
	v_mfma_f32_16x16x32_bf16 v[92:95], v[132:135], v[202:205], v[92:95]
	v_mfma_f32_16x16x32_bf16 v[88:91], v[140:143], v[202:205], v[88:91]
	v_mfma_f32_16x16x32_bf16 v[76:79], v[132:135], v[220:223], v[76:79]
	v_mfma_f32_16x16x32_bf16 v[72:75], v[140:143], v[220:223], v[72:75]
	s_setprio 0
	s_setprio 1
	v_mfma_f32_16x16x32_bf16 v[116:119], v[144:147], v[160:163], v[116:119]
	v_mfma_f32_16x16x32_bf16 v[112:115], v[152:155], v[160:163], v[112:115]
	v_mfma_f32_16x16x32_bf16 v[100:103], v[144:147], v[188:191], v[100:103]
	v_mfma_f32_16x16x32_bf16 v[96:99], v[152:155], v[188:191], v[96:99]
	v_mfma_f32_16x16x32_bf16 v[84:87], v[144:147], v[196:199], v[84:87]
	v_mfma_f32_16x16x32_bf16 v[80:83], v[152:155], v[196:199], v[80:83]
	v_mfma_f32_16x16x32_bf16 v[68:71], v[144:147], v[206:209], v[68:71]
	v_mfma_f32_16x16x32_bf16 v[64:67], v[152:155], v[206:209], v[64:67]
	v_mfma_f32_16x16x32_bf16 v[116:119], v[148:151], v[164:167], v[116:119]
	v_mfma_f32_16x16x32_bf16 v[112:115], v[156:159], v[164:167], v[112:115]
	v_mfma_f32_16x16x32_bf16 v[100:103], v[148:151], v[192:195], v[100:103]
	v_mfma_f32_16x16x32_bf16 v[96:99], v[156:159], v[192:195], v[96:99]
	v_mfma_f32_16x16x32_bf16 v[84:87], v[148:151], v[202:205], v[84:87]
	v_mfma_f32_16x16x32_bf16 v[80:83], v[156:159], v[202:205], v[80:83]
	v_mfma_f32_16x16x32_bf16 v[68:71], v[148:151], v[220:223], v[68:71]
	v_mfma_f32_16x16x32_bf16 v[64:67], v[156:159], v[220:223], v[64:67]
	s_setprio 0
	s_barrier
	s_add_i32 s66, s50, s34
	v_lshl_add_u64 v[228:229], s[14:15], 0, v[170:171]
	s_mov_b32 m0, s66
	ds_read_b128 v[160:163], v217 offset:16384
	ds_read_b128 v[164:167], v217 offset:17408
	ds_read_b128 v[188:191], v217 offset:18432
	ds_read_b128 v[192:195], v217 offset:19456
	ds_read_b128 v[196:199], v217 offset:20480
	ds_read_b128 v[202:205], v217 offset:21504
	ds_read_b128 v[206:209], v217 offset:22528
	ds_read_b128 v[220:223], v217 offset:23552
	global_load_lds_dwordx4 v[228:229], off
	s_add_i32 m0, s66, 0x2000
	s_add_u32 s66, s14, 0x80000
	v_lshl_add_u64 v[232:233], s[14:15], 0, v[174:175]
	s_addc_u32 s67, s15, 0
	s_add_i32 s68, s51, s34
	global_load_lds_dwordx4 v[232:233], off
	v_lshl_add_u64 v[234:235], s[66:67], 0, v[170:171]
	s_mov_b32 m0, s68
	v_lshl_add_u64 v[236:237], s[26:27], 0, v[172:173]
	global_load_lds_dwordx4 v[234:235], off
	v_lshl_add_u64 v[234:235], s[66:67], 0, v[174:175]
	s_add_i32 m0, s68, 0x2000
	s_nop 0
	global_load_lds_dwordx4 v[234:235], off
	v_lshl_add_u64 v[234:235], s[26:27], 0, v[168:169]
	s_mov_b32 m0, s39
	s_nop 0
	global_load_lds_dwordx4 v[234:235], off
	s_mov_b32 m0, s42
	s_nop 0
	global_load_lds_dwordx4 v[236:237], off
	s_waitcnt vmcnt(8)
	s_waitcnt lgkmcnt(0)
	s_barrier
	s_setprio 1
	s_waitcnt lgkmcnt(0)
	v_mfma_f32_16x16x32_bf16 v[60:63], v[128:131], v[160:163], v[60:63]
	v_mfma_f32_16x16x32_bf16 v[56:59], v[136:139], v[160:163], v[56:59]
	v_mfma_f32_16x16x32_bf16 v[44:47], v[128:131], v[188:191], v[44:47]
	v_mfma_f32_16x16x32_bf16 v[40:43], v[136:139], v[188:191], v[40:43]
	v_mfma_f32_16x16x32_bf16 v[28:31], v[128:131], v[196:199], v[28:31]
	v_mfma_f32_16x16x32_bf16 v[24:27], v[136:139], v[196:199], v[24:27]
	v_mfma_f32_16x16x32_bf16 v[12:15], v[128:131], v[206:209], v[12:15]
	v_mfma_f32_16x16x32_bf16 v[8:11], v[136:139], v[206:209], v[8:11]
	v_mfma_f32_16x16x32_bf16 v[60:63], v[132:135], v[164:167], v[60:63]
	v_mfma_f32_16x16x32_bf16 v[56:59], v[140:143], v[164:167], v[56:59]
	v_mfma_f32_16x16x32_bf16 v[44:47], v[132:135], v[192:195], v[44:47]
	v_mfma_f32_16x16x32_bf16 v[40:43], v[140:143], v[192:195], v[40:43]
	v_mfma_f32_16x16x32_bf16 v[28:31], v[132:135], v[202:205], v[28:31]
	v_mfma_f32_16x16x32_bf16 v[24:27], v[140:143], v[202:205], v[24:27]
	v_mfma_f32_16x16x32_bf16 v[12:15], v[132:135], v[220:223], v[12:15]
	v_mfma_f32_16x16x32_bf16 v[8:11], v[140:143], v[220:223], v[8:11]
	s_setprio 0
	s_setprio 1
	v_mfma_f32_16x16x32_bf16 v[52:55], v[144:147], v[160:163], v[52:55]
	v_mfma_f32_16x16x32_bf16 v[48:51], v[152:155], v[160:163], v[48:51]
	v_mfma_f32_16x16x32_bf16 v[36:39], v[144:147], v[188:191], v[36:39]
	v_mfma_f32_16x16x32_bf16 v[32:35], v[152:155], v[188:191], v[32:35]
	v_mfma_f32_16x16x32_bf16 v[20:23], v[144:147], v[196:199], v[20:23]
	v_mfma_f32_16x16x32_bf16 v[16:19], v[152:155], v[196:199], v[16:19]
	v_mfma_f32_16x16x32_bf16 v[4:7], v[144:147], v[206:209], v[4:7]
	v_mfma_f32_16x16x32_bf16 v[0:3], v[152:155], v[206:209], v[0:3]
	v_mfma_f32_16x16x32_bf16 v[52:55], v[148:151], v[164:167], v[52:55]
	v_mfma_f32_16x16x32_bf16 v[48:51], v[156:159], v[164:167], v[48:51]
	v_mfma_f32_16x16x32_bf16 v[36:39], v[148:151], v[192:195], v[36:39]
	v_mfma_f32_16x16x32_bf16 v[32:35], v[156:159], v[192:195], v[32:35]
	v_mfma_f32_16x16x32_bf16 v[20:23], v[148:151], v[202:205], v[20:23]
	v_mfma_f32_16x16x32_bf16 v[16:19], v[156:159], v[202:205], v[16:19]
	v_mfma_f32_16x16x32_bf16 v[4:7], v[148:151], v[220:223], v[4:7]
	v_mfma_f32_16x16x32_bf16 v[0:3], v[156:159], v[220:223], v[0:3]
	s_setprio 0
	s_barrier
; #define PG8_STAGE(bufoff, gbase, voff) do { _Pragma("unroll") for (int _i = 0; _i < 2; ++_i) \
;         __builtin_amdgcn_global_load_lds((const unsigned*)((const char*)(gbase) + (voff)[_i]), (PG8_LAS unsigned*)(lds + (bufoff) + ldsw + _i * 8192), 16, 0, 0); } while (0)
; #define PG8_LDA(dst, b, h) do { _Pragma("unroll") for (int m = 0; m < 4; ++m) _Pragma("unroll") for (int k = 0; k < 2; ++k) dst[m][k] = *(const PG8_LAS bf16x8*)(lds + PG8_SA(b, h) + aoff + m * 2048 + k * 1024); } while (0)
; #define PG8_LDB(dst, b, h) do { _Pragma("unroll") for (int n = 0; n < 2; ++n) _Pragma("unroll") for (int k = 0; k < 2; ++k) dst[n][k] = *(const PG8_LAS bf16x8*)(lds + PG8_SB(b, h) + boff + n * 2048 + k * 1024); } while (0)
; #define PG8_MMA(ai, bj, At, Bt) do { __builtin_amdgcn_s_setprio(1); _Pragma("unroll") for (int m = 0; m < 4; ++m) _Pragma("unroll") for (int n = 0; n < 2; ++n) _Pragma("unroll") for (int k = 0; k < 2; ++k) \
;         acc[ai][bj][m][n] = __builtin_amdgcn_mfma_f32_16x16x32_bf16(Bt[n][k], At[m][k], acc[ai][bj][m][n], 0, 0, 0); __builtin_amdgcn_s_setprio(0); } while (0)
; #define PG8_WAIT_V(n) asm volatile("s_waitcnt vmcnt(" #n ")" ::: "memory")
; #define PG8_WAIT_L(n) asm volatile("s_waitcnt lgkmcnt(" #n ")" ::: "memory")
; #define PG8_BAR __builtin_amdgcn_s_barrier()
; #define PG8_SCHED __builtin_amdgcn_sched_barrier(0)
; template <class Epi, class Sched, bool ALIGN_EPI = false, bool SP2 = false, bool DUAL = false>
; __device__ __forceinline__ void gemm_phase(PG8_LAS unsigned char* lds, const Gemm g, const Sched& S, const Epi& E) {
;     ...
;             PG8_LDB(B0, 1, 0); PG8_LDB(B1, 1, 1); PG8_SCHED; PG8_LDA(At, 1, 0); PG8_STAGE(PG8_SA(0, 1), a2 + hstep, voffA);
;             PG8_WAIT_V(8); PG8_WAIT_L(0); PG8_BAR; PG8_MMA(0, 0, At, B0); PG8_MMA(0, 1, At, B1); PG8_BAR; PG8_SCHED;
	s_add_i32 s66, 0, 0x18000
	s_add_i32 s67, 0, 0x1c000
	v_add_u32_e32 v140, s66, v213
	v_add_u32_e32 v156, s67, v213
	ds_read_b128 v[128:131], v140
	ds_read_b128 v[132:135], v140 offset:1024
	ds_read_b128 v[136:139], v140 offset:2048
	ds_read_b128 v[140:143], v140 offset:3072
	ds_read_b128 v[144:147], v156
	ds_read_b128 v[148:151], v156 offset:1024
	ds_read_b128 v[152:155], v156 offset:2048
	ds_read_b128 v[156:159], v156 offset:3072
	s_add_u32 s26, s26, 0x80000
	s_addc_u32 s27, s27, 0
	s_mov_b32 m0, s43
	v_lshl_add_u64 v[238:239], s[26:27], 0, v[168:169]
	ds_read_b128 v[160:163], v217 offset:32768
	ds_read_b128 v[164:167], v217 offset:33792
	ds_read_b128 v[188:191], v217 offset:34816
	ds_read_b128 v[192:195], v217 offset:35840
	ds_read_b128 v[196:199], v217 offset:36864
	ds_read_b128 v[202:205], v217 offset:37888
	ds_read_b128 v[206:209], v217 offset:38912
	ds_read_b128 v[220:223], v217 offset:39936
	global_load_lds_dwordx4 v[238:239], off
	v_lshl_add_u64 v[238:239], s[26:27], 0, v[172:173]
	s_mov_b32 m0, s44
	s_nop 0
	global_load_lds_dwordx4 v[238:239], off
	s_waitcnt vmcnt(8)
	s_waitcnt lgkmcnt(0)
	s_barrier
	s_setprio 1
	s_waitcnt lgkmcnt(0)
	v_mfma_f32_16x16x32_bf16 v[124:127], v[128:131], v[160:163], v[124:127]
	v_mfma_f32_16x16x32_bf16 v[120:123], v[136:139], v[160:163], v[120:123]
	v_mfma_f32_16x16x32_bf16 v[108:111], v[128:131], v[188:191], v[108:111]
	v_mfma_f32_16x16x32_bf16 v[104:107], v[136:139], v[188:191], v[104:107]
	v_mfma_f32_16x16x32_bf16 v[92:95], v[128:131], v[196:199], v[92:95]
	v_mfma_f32_16x16x32_bf16 v[88:91], v[136:139], v[196:199], v[88:91]
	v_mfma_f32_16x16x32_bf16 v[76:79], v[128:131], v[206:209], v[76:79]
	v_mfma_f32_16x16x32_bf16 v[72:75], v[136:139], v[206:209], v[72:75]
	v_mfma_f32_16x16x32_bf16 v[124:127], v[132:135], v[164:167], v[124:127]
	v_mfma_f32_16x16x32_bf16 v[120:123], v[140:143], v[164:167], v[120:123]
	v_mfma_f32_16x16x32_bf16 v[108:111], v[132:135], v[192:195], v[108:111]
	v_mfma_f32_16x16x32_bf16 v[104:107], v[140:143], v[192:195], v[104:107]
	v_mfma_f32_16x16x32_bf16 v[92:95], v[132:135], v[202:205], v[92:95]
	v_mfma_f32_16x16x32_bf16 v[88:91], v[140:143], v[202:205], v[88:91]
	v_mfma_f32_16x16x32_bf16 v[76:79], v[132:135], v[220:223], v[76:79]
	v_mfma_f32_16x16x32_bf16 v[72:75], v[140:143], v[220:223], v[72:75]
	s_setprio 0
	s_setprio 1
	v_mfma_f32_16x16x32_bf16 v[116:119], v[144:147], v[160:163], v[116:119]
	v_mfma_f32_16x16x32_bf16 v[112:115], v[152:155], v[160:163], v[112:115]
	v_mfma_f32_16x16x32_bf16 v[100:103], v[144:147], v[188:191], v[100:103]
	v_mfma_f32_16x16x32_bf16 v[96:99], v[152:155], v[188:191], v[96:99]
	v_mfma_f32_16x16x32_bf16 v[84:87], v[144:147], v[196:199], v[84:87]
	v_mfma_f32_16x16x32_bf16 v[80:83], v[152:155], v[196:199], v[80:83]
	v_mfma_f32_16x16x32_bf16 v[68:71], v[144:147], v[206:209], v[68:71]
	v_mfma_f32_16x16x32_bf16 v[64:67], v[152:155], v[206:209], v[64:67]
	v_mfma_f32_16x16x32_bf16 v[116:119], v[148:151], v[164:167], v[116:119]
	v_mfma_f32_16x16x32_bf16 v[112:115], v[156:159], v[164:167], v[112:115]
	v_mfma_f32_16x16x32_bf16 v[100:103], v[148:151], v[192:195], v[100:103]
	v_mfma_f32_16x16x32_bf16 v[96:99], v[156:159], v[192:195], v[96:99]
	v_mfma_f32_16x16x32_bf16 v[84:87], v[148:151], v[202:205], v[84:87]
	v_mfma_f32_16x16x32_bf16 v[80:83], v[156:159], v[202:205], v[80:83]
	v_mfma_f32_16x16x32_bf16 v[68:71], v[148:151], v[220:223], v[68:71]
	v_mfma_f32_16x16x32_bf16 v[64:67], v[156:159], v[220:223], v[64:67]
	s_setprio 0
	s_barrier
; #define PG8_STAGE(bufoff, gbase, voff) do { _Pragma("unroll") for (int _i = 0; _i < 2; ++_i) \
;         __builtin_amdgcn_global_load_lds((const unsigned*)((const char*)(gbase) + (voff)[_i]), (PG8_LAS unsigned*)(lds + (bufoff) + ldsw + _i * 8192), 16, 0, 0); } while (0)
; #define PG8_LDA(dst, b, h) do { _Pragma("unroll") for (int m = 0; m < 4; ++m) _Pragma("unroll") for (int k = 0; k < 2; ++k) dst[m][k] = *(const PG8_LAS bf16x8*)(lds + PG8_SA(b, h) + aoff + m * 2048 + k * 1024); } while (0)
; #define PG8_MMA(ai, bj, At, Bt) do { __builtin_amdgcn_s_setprio(1); _Pragma("unroll") for (int m = 0; m < 4; ++m) _Pragma("unroll") for (int n = 0; n < 2; ++n) _Pragma("unroll") for (int k = 0; k < 2; ++k) \
;         acc[ai][bj][m][n] = __builtin_amdgcn_mfma_f32_16x16x32_bf16(Bt[n][k], At[m][k], acc[ai][bj][m][n], 0, 0, 0); __builtin_amdgcn_s_setprio(0); } while (0)
; #define PG8_WAIT_V(n) asm volatile("s_waitcnt vmcnt(" #n ")" ::: "memory")
; #define PG8_WAIT_L(n) asm volatile("s_waitcnt lgkmcnt(" #n ")" ::: "memory")
; #define PG8_BAR __builtin_amdgcn_s_barrier()
; #define PG8_SCHED __builtin_amdgcn_sched_barrier(0)
; template <class Epi, class Sched, bool ALIGN_EPI = false, bool SP2 = false, bool DUAL = false>
; __device__ __forceinline__ void gemm_phase(PG8_LAS unsigned char* lds, const Gemm g, const Sched& S, const Epi& E) {
;     ...
;             PG8_LDA(At, 1, 1); PG8_STAGE(PG8_SB(1, 0), b3, voffB); PG8_STAGE(PG8_SB(1, 1), b3 + hstep, voffB); PG8_STAGE(PG8_SA(1, 0), a3, voffA);
;             PG8_WAIT_V(8); PG8_WAIT_L(0); PG8_BAR; PG8_MMA(1, 0, At, B0); PG8_MMA(1, 1, At, B1); PG8_BAR; PG8_SCHED;
;     ...
;         if constexpr (ALIGN_EPI) { if (wr == 0) PG8_BAR; }
	s_add_i32 s26, s66, s34
	v_lshl_add_u64 v[228:229], v[228:229], 0, s[12:13]
	s_mov_b32 m0, s26
	ds_read_b128 v[160:163], v217 offset:49152
	ds_read_b128 v[164:167], v217 offset:50176
	ds_read_b128 v[188:191], v217 offset:51200
	ds_read_b128 v[192:195], v217 offset:52224
	ds_read_b128 v[196:199], v217 offset:53248
	ds_read_b128 v[202:205], v217 offset:54272
	ds_read_b128 v[206:209], v217 offset:55296
	ds_read_b128 v[220:223], v217 offset:56320
	global_load_lds_dwordx4 v[228:229], off
	s_add_i32 m0, s26, 0x2000
	s_add_u32 s14, s14, 0x80080
	v_lshl_add_u64 v[228:229], v[232:233], 0, s[12:13]
	s_addc_u32 s15, s15, 0
	s_add_i32 s26, s67, s34
	global_load_lds_dwordx4 v[228:229], off
	v_lshl_add_u64 v[228:229], s[14:15], 0, v[170:171]
	s_mov_b32 m0, s26
	s_nop 0
	global_load_lds_dwordx4 v[228:229], off
	v_lshl_add_u64 v[228:229], s[14:15], 0, v[174:175]
	s_add_i32 m0, s26, 0x2000
	s_nop 0
	global_load_lds_dwordx4 v[228:229], off
	v_lshl_add_u64 v[228:229], v[234:235], 0, s[12:13]
	s_mov_b32 m0, s47
	s_nop 0
	global_load_lds_dwordx4 v[228:229], off
	v_lshl_add_u64 v[228:229], v[236:237], 0, s[12:13]
	s_mov_b32 m0, s48
	s_nop 0
	global_load_lds_dwordx4 v[228:229], off
	s_waitcnt vmcnt(8)
	s_waitcnt lgkmcnt(0)
	s_barrier
	s_setprio 1
	s_waitcnt lgkmcnt(0)
	v_mfma_f32_16x16x32_bf16 v[60:63], v[128:131], v[160:163], v[60:63]
	v_mfma_f32_16x16x32_bf16 v[56:59], v[136:139], v[160:163], v[56:59]
	v_mfma_f32_16x16x32_bf16 v[44:47], v[128:131], v[188:191], v[44:47]
	v_mfma_f32_16x16x32_bf16 v[40:43], v[136:139], v[188:191], v[40:43]
	v_mfma_f32_16x16x32_bf16 v[28:31], v[128:131], v[196:199], v[28:31]
	v_mfma_f32_16x16x32_bf16 v[24:27], v[136:139], v[196:199], v[24:27]
	v_mfma_f32_16x16x32_bf16 v[12:15], v[128:131], v[206:209], v[12:15]
	v_mfma_f32_16x16x32_bf16 v[8:11], v[136:139], v[206:209], v[8:11]
	v_mfma_f32_16x16x32_bf16 v[60:63], v[132:135], v[164:167], v[60:63]
	v_mfma_f32_16x16x32_bf16 v[56:59], v[140:143], v[164:167], v[56:59]
	v_mfma_f32_16x16x32_bf16 v[44:47], v[132:135], v[192:195], v[44:47]
	v_mfma_f32_16x16x32_bf16 v[40:43], v[140:143], v[192:195], v[40:43]
	v_mfma_f32_16x16x32_bf16 v[28:31], v[132:135], v[202:205], v[28:31]
	v_mfma_f32_16x16x32_bf16 v[24:27], v[140:143], v[202:205], v[24:27]
	v_mfma_f32_16x16x32_bf16 v[12:15], v[132:135], v[220:223], v[12:15]
	v_mfma_f32_16x16x32_bf16 v[8:11], v[140:143], v[220:223], v[8:11]
	s_setprio 0
	s_setprio 1
	v_mfma_f32_16x16x32_bf16 v[52:55], v[144:147], v[160:163], v[52:55]
	v_mfma_f32_16x16x32_bf16 v[48:51], v[152:155], v[160:163], v[48:51]
	v_mfma_f32_16x16x32_bf16 v[36:39], v[144:147], v[188:191], v[36:39]
	v_mfma_f32_16x16x32_bf16 v[32:35], v[152:155], v[188:191], v[32:35]
	v_mfma_f32_16x16x32_bf16 v[20:23], v[144:147], v[196:199], v[20:23]
	v_mfma_f32_16x16x32_bf16 v[16:19], v[152:155], v[196:199], v[16:19]
	v_mfma_f32_16x16x32_bf16 v[4:7], v[144:147], v[206:209], v[4:7]
	v_mfma_f32_16x16x32_bf16 v[0:3], v[152:155], v[206:209], v[0:3]
	v_mfma_f32_16x16x32_bf16 v[52:55], v[148:151], v[164:167], v[52:55]
	v_mfma_f32_16x16x32_bf16 v[48:51], v[156:159], v[164:167], v[48:51]
	v_mfma_f32_16x16x32_bf16 v[36:39], v[148:151], v[192:195], v[36:39]
	v_mfma_f32_16x16x32_bf16 v[32:35], v[156:159], v[192:195], v[32:35]
	v_mfma_f32_16x16x32_bf16 v[20:23], v[148:151], v[202:205], v[20:23]
	v_mfma_f32_16x16x32_bf16 v[16:19], v[156:159], v[202:205], v[16:19]
	v_mfma_f32_16x16x32_bf16 v[4:7], v[148:151], v[220:223], v[4:7]
	v_mfma_f32_16x16x32_bf16 v[0:3], v[156:159], v[220:223], v[0:3]
	s_setprio 0
	s_barrier
	s_add_i32 s65, s65, 2
	s_add_u32 s40, s40, 0x100
	s_addc_u32 s41, s41, 0
	s_add_u32 s63, s63, 0x100
	s_addc_u32 s64, s64, 0
	s_cmp_gt_u32 s65, 29
	s_cbranch_scc0 .LBB0_992
	v_readlane_b32 s64, v254, 20
	v_readlane_b32 s70, v254, 26
	v_readlane_b32 s71, v254, 27
	v_readlane_b32 s72, v254, 28
	v_readlane_b32 s73, v254, 29
	v_readlane_b32 s74, v254, 30
	v_readlane_b32 s75, v254, 31
	v_readlane_b32 s76, v254, 32
	v_readlane_b32 s77, v254, 33
	s_and_b64 vcc, exec, s[16:17]
	s_mov_b64 s[70:71], s[74:75]
	s_mov_b64 s[72:73], s[76:77]
	v_readlane_b32 s65, v254, 21
	v_readlane_b32 s66, v254, 22
	v_readlane_b32 s67, v254, 23
	v_readlane_b32 s68, v254, 24
	v_readlane_b32 s69, v254, 25
	v_readlane_b32 s78, v254, 34
	v_readlane_b32 s79, v254, 35
	s_cbranch_vccz .LBB0_995
	s_barrier

; #define PG8_STAGE(bufoff, gbase, voff) do { _Pragma("unroll") for (int _i = 0; _i < 2; ++_i) \
;         __builtin_amdgcn_global_load_lds((const unsigned*)((const char*)(gbase) + (voff)[_i]), (PG8_LAS unsigned*)(lds + (bufoff) + ldsw + _i * 8192), 16, 0, 0); } while (0)
; #define PG8_WAIT_V(n) asm volatile("s_waitcnt vmcnt(" #n ")" ::: "memory")
; #define PG8_BAR __builtin_amdgcn_s_barrier()
; template <class Epi, class Sched, bool ALIGN_EPI = false, bool SP2 = false, bool DUAL = false>
; __device__ __forceinline__ void gemm_phase(PG8_LAS unsigned char* lds, const Gemm g, const Sched& S, const Epi& E) {
;     ...
;     if constexpr (SP2) {
;         PG8_STAGE(PG8_SB(0, 0), cB, voffB); PG8_STAGE(PG8_SB(0, 1), cB + hstep, voffB); PG8_STAGE(PG8_SA(0, 0), cA, voffA); PG8_STAGE(PG8_SA(0, 1), cA + hstep, voffA);
;         if (wr == 1) PG8_BAR;
;         PG8_WAIT_V(2); PG8_BAR;
;         PG8_STAGE(PG8_SB(1, 0), cB + kstep, voffB); PG8_STAGE(PG8_SA(1, 0), cA + kstep, voffA); PG8_STAGE(PG8_SB(1, 1), cB + hstep + kstep, voffB);
;         PG8_WAIT_V(6); PG8_BAR;
.LBB0_1179:
	s_lshl_b32 s5, s5, 5
	s_mov_b64 s[18:19], 0x80
	s_and_b32 s5, s5, 0x60
	s_add_i32 m0, s31, 0x18000
	v_lshl_add_u64 v[6:7], v[6:7], 0, s[18:19]
	s_lshl_b32 s22, s0, 13
	s_lshl_b32 s23, s5, 7
	s_waitcnt vmcnt(2)
	s_barrier
	global_load_lds_dwordx4 v[6:7], off
	v_lshl_add_u64 v[4:5], v[4:5], 0, s[18:19]
	s_add_i32 m0, s31, 0x1a000
	s_add_i32 s37, s31, 0x8000
	s_add_i32 s38, s31, 0xa000
	global_load_lds_dwordx4 v[4:5], off
	v_lshl_add_u64 v[0:1], v[0:1], 0, s[18:19]
	s_mov_b32 m0, s37
	s_add_u32 s20, s14, 0x160080
	global_load_lds_dwordx4 v[0:1], off
	v_lshl_add_u64 v[0:1], v[2:3], 0, s[18:19]
	s_mov_b32 m0, s38
	s_addc_u32 s21, s15, 0
	global_load_lds_dwordx4 v[0:1], off
	s_add_i32 m0, s31, 0x1c000
	v_lshl_add_u64 v[0:1], s[20:21], 0, v[166:167]
	global_load_lds_dwordx4 v[0:1], off
	v_lshl_add_u64 v[0:1], s[20:21], 0, v[170:171]
	s_add_i32 m0, s31, 0x1e000
	v_lshl_or_b32 v177, s0, 6, v195
	global_load_lds_dwordx4 v[0:1], off
	v_lshlrev_b32_e32 v0, 6, v195
	v_lshlrev_b32_e32 v1, 1, v10
	s_movk_i32 s0, 0x3c0
	v_lshlrev_b32_e32 v2, 2, v195
	v_and_or_b32 v0, v0, s0, v1
	v_and_b32_e32 v2, 32, v2
	v_bitop3_b32 v0, v0, s22, v2 bitop3:0xde
	v_lshlrev_b32_e32 v2, 6, v200
	v_and_or_b32 v1, v2, s0, v1
	v_and_b32_e32 v2, 32, v197
	v_bitop3_b32 v198, s23, v1, v2 bitop3:0xf6
	s_waitcnt vmcnt(6)
	s_cmpk_lt_u32 s4, 0x100
	v_add_u16_e32 v1, v8, v9
	s_cselect_b64 s[20:21], -1, 0
	v_lshrrev_b16_e32 v1, 1, v1
	s_add_i32 s40, 0, 0x10000
	s_add_i32 s41, 0, 0x14000
	s_sext_i32_i8 s45, s1
	s_ashr_i32 s39, s92, 31
	v_or_b32_e32 v199, s5, v10
	v_add_lshl_u32 v172, v11, v1, 1
	v_mov_b32_e32 v173, v167
	v_add_lshl_u32 v174, v12, v1, 1
	v_mov_b32_e32 v175, v167
	v_mov_b64_e32 v[178:179], 0x400
	v_mov_b64_e32 v[180:181], 0x3ff
	v_add_u32_e32 v201, s40, v198
	v_add_u32_e32 v202, s41, v198
	v_add_u32_e32 v203, 0, v0
	s_barrier
	s_branch .LBB0_1182

; #define PG8_STAGE(bufoff, gbase, voff) do { _Pragma("unroll") for (int _i = 0; _i < 2; ++_i) \
;         __builtin_amdgcn_global_load_lds((const unsigned*)((const char*)(gbase) + (voff)[_i]), (PG8_LAS unsigned*)(lds + (bufoff) + ldsw + _i * 8192), 16, 0, 0); } while (0)
; #define PG8_LDA(dst, b, h) do { _Pragma("unroll") for (int m = 0; m < 4; ++m) _Pragma("unroll") for (int k = 0; k < 2; ++k) dst[m][k] = *(const PG8_LAS bf16x8*)(lds + PG8_SA(b, h) + aoff + m * 2048 + k * 1024); } while (0)
; #define PG8_LDB(dst, b, h) do { _Pragma("unroll") for (int n = 0; n < 2; ++n) _Pragma("unroll") for (int k = 0; k < 2; ++k) dst[n][k] = *(const PG8_LAS bf16x8*)(lds + PG8_SB(b, h) + boff + n * 2048 + k * 1024); } while (0)
; #define PG8_MMA(ai, bj, At, Bt) do { __builtin_amdgcn_s_setprio(1); _Pragma("unroll") for (int m = 0; m < 4; ++m) _Pragma("unroll") for (int n = 0; n < 2; ++n) _Pragma("unroll") for (int k = 0; k < 2; ++k) \
;         acc[ai][bj][m][n] = __builtin_amdgcn_mfma_f32_16x16x32_bf16(Bt[n][k], At[m][k], acc[ai][bj][m][n], 0, 0, 0); __builtin_amdgcn_s_setprio(0); } while (0)
; template <class Epi, class Sched, bool ALIGN_EPI = false, bool SP2 = false, bool DUAL = false>
; __device__ __forceinline__ void gemm_phase(PG8_LAS unsigned char* lds, const Gemm g, const Sched& S, const Epi& E) {
;     ...
;         const char* nA = has_next ? (const char*)((DUAL && nxt.sub) ? g.A2 : g.A) + (size_t)nxt.pm * tstep : cA; const char* nB = has_next ? (const char*)((DUAL && nxt.sub) ? g.Bt2 : g.Bt) + (size_t)nxt.pn * tstep : cB;
;         for (int t = 0; t < nt; t += 2) {
;             const bool last = (t == nt - 2);
;             const char* a1 = cA + (size_t)(t + 1) * kstep;
;             const char* a2 = last ? nA : cA + (size_t)(t + 2) * kstep; const char* b2 = last ? nB : cB + (size_t)(t + 2) * kstep;
;             const char* a3 = a2 + kstep; const char* b3 = b2 + kstep;
;             if (last && has_next) S.a_ready(nxt);
;             if constexpr (SP2) {
;             PG8_LDB(B0, 0, 0); PG8_LDB(B1, 0, 1); PG8_SCHED; PG8_LDA(At, 0, 0); PG8_STAGE(PG8_SA(1, 1), a1 + hstep, voffA);
;             PG8_WAIT_V(8); PG8_WAIT_L(0); PG8_BAR; PG8_MMA(0, 0, At, B0); PG8_MMA(0, 1, At, B1); PG8_BAR; PG8_SCHED;
;             PG8_LDA(At, 0, 1); PG8_STAGE(PG8_SB(0, 0), b2, voffB); PG8_STAGE(PG8_SB(0, 1), b2 + hstep, voffB); PG8_STAGE(PG8_SA(0, 0), a2, voffA);
.LBB0_1192:
	s_add_u32 s24, s24, 0x160080
	s_addc_u32 s25, s25, 0
	s_add_u32 s46, s14, 0x100
	s_addc_u32 s47, s15, 0
	s_mov_b32 s48, -2
	ds_read_b128 v[128:131], v201
	ds_read_b128 v[132:135], v201 offset:1024
	ds_read_b128 v[136:139], v201 offset:2048
	ds_read_b128 v[140:143], v201 offset:3072
	ds_read_b128 v[144:147], v202
	ds_read_b128 v[148:151], v202 offset:1024
	ds_read_b128 v[152:155], v202 offset:2048
	ds_read_b128 v[156:159], v202 offset:3072
	s_add_u32 s14, s24, 0xffea0080
	s_addc_u32 s15, s25, -1
	s_cmpk_eq_i32 s48, 0x54
	s_cselect_b32 s27, s5, s15
	s_cselect_b32 s26, s4, s14
	s_cselect_b32 s15, s23, s47
	s_cselect_b32 s14, s22, s46
	v_lshl_add_u64 v[220:221], s[24:25], 0, v[172:173]
	s_add_i32 m0, s31, 0xc000
	ds_read_b128 v[160:163], v203
	ds_read_b128 v[182:185], v203 offset:1024
	ds_read_b128 v[186:189], v203 offset:2048
	ds_read_b128 v[190:193], v203 offset:3072
	ds_read_b128 v[204:207], v203 offset:4096
	ds_read_b128 v[208:211], v203 offset:5120
	ds_read_b128 v[212:215], v203 offset:6144
	ds_read_b128 v[216:219], v203 offset:7168
	global_load_lds_dwordx4 v[220:221], off
	v_lshl_add_u64 v[220:221], s[24:25], 0, v[174:175]
	s_add_i32 m0, s31, 0xe000
	s_nop 0
	global_load_lds_dwordx4 v[220:221], off
	s_waitcnt vmcnt(8)
	s_waitcnt lgkmcnt(0)
	s_barrier
	s_setprio 1
	s_waitcnt lgkmcnt(0)
	v_mfma_f32_16x16x32_bf16 v[124:127], v[128:131], v[160:163], 0
	v_mfma_f32_16x16x32_bf16 v[120:123], v[136:139], v[160:163], 0
	v_mfma_f32_16x16x32_bf16 v[112:115], v[128:131], v[186:189], 0
	v_mfma_f32_16x16x32_bf16 v[104:107], v[136:139], v[186:189], 0
	v_mfma_f32_16x16x32_bf16 v[96:99], v[128:131], v[204:207], 0
	v_mfma_f32_16x16x32_bf16 v[88:91], v[136:139], v[204:207], 0
	v_mfma_f32_16x16x32_bf16 v[80:83], v[128:131], v[212:215], 0
	v_mfma_f32_16x16x32_bf16 v[72:75], v[136:139], v[212:215], 0
	v_mfma_f32_16x16x32_bf16 v[124:127], v[132:135], v[182:185], v[124:127]
	v_mfma_f32_16x16x32_bf16 v[120:123], v[140:143], v[182:185], v[120:123]
	v_mfma_f32_16x16x32_bf16 v[112:115], v[132:135], v[190:193], v[112:115]
	v_mfma_f32_16x16x32_bf16 v[104:107], v[140:143], v[190:193], v[104:107]
	v_mfma_f32_16x16x32_bf16 v[96:99], v[132:135], v[208:211], v[96:99]
	v_mfma_f32_16x16x32_bf16 v[88:91], v[140:143], v[208:211], v[88:91]
	v_mfma_f32_16x16x32_bf16 v[80:83], v[132:135], v[216:219], v[80:83]
	v_mfma_f32_16x16x32_bf16 v[72:75], v[140:143], v[216:219], v[72:75]
	s_setprio 0
	s_setprio 1
	v_mfma_f32_16x16x32_bf16 v[116:119], v[144:147], v[160:163], 0
	v_mfma_f32_16x16x32_bf16 v[108:111], v[152:155], v[160:163], 0
	v_mfma_f32_16x16x32_bf16 v[100:103], v[144:147], v[186:189], 0
	v_mfma_f32_16x16x32_bf16 v[92:95], v[152:155], v[186:189], 0
	v_mfma_f32_16x16x32_bf16 v[84:87], v[144:147], v[204:207], 0
	v_mfma_f32_16x16x32_bf16 v[76:79], v[152:155], v[204:207], 0
	v_mfma_f32_16x16x32_bf16 v[68:71], v[144:147], v[212:215], 0
	v_mfma_f32_16x16x32_bf16 v[64:67], v[152:155], v[212:215], 0
	v_mfma_f32_16x16x32_bf16 v[116:119], v[148:151], v[182:185], v[116:119]
	v_mfma_f32_16x16x32_bf16 v[108:111], v[156:159], v[182:185], v[108:111]
	v_mfma_f32_16x16x32_bf16 v[100:103], v[148:151], v[190:193], v[100:103]
	v_mfma_f32_16x16x32_bf16 v[92:95], v[156:159], v[190:193], v[92:95]
	v_mfma_f32_16x16x32_bf16 v[84:87], v[148:151], v[208:211], v[84:87]
	v_mfma_f32_16x16x32_bf16 v[76:79], v[156:159], v[208:211], v[76:79]
	v_mfma_f32_16x16x32_bf16 v[68:71], v[148:151], v[216:219], v[68:71]
	v_mfma_f32_16x16x32_bf16 v[64:67], v[156:159], v[216:219], v[64:67]
	s_setprio 0
	s_barrier
	s_add_i32 s49, s40, s30
	v_lshl_add_u64 v[220:221], s[14:15], 0, v[166:167]
	s_mov_b32 m0, s49
	ds_read_b128 v[160:163], v203 offset:16384
	ds_read_b128 v[182:185], v203 offset:17408
	ds_read_b128 v[186:189], v203 offset:18432
	ds_read_b128 v[190:193], v203 offset:19456
	ds_read_b128 v[204:207], v203 offset:20480
	ds_read_b128 v[208:211], v203 offset:21504
	ds_read_b128 v[212:215], v203 offset:22528
	ds_read_b128 v[216:219], v203 offset:23552
	global_load_lds_dwordx4 v[220:221], off
	s_add_i32 m0, s49, 0x2000
	s_add_u32 s50, s14, 0x160000
	v_lshl_add_u64 v[222:223], s[14:15], 0, v[170:171]
	s_addc_u32 s51, s15, 0
	s_add_i32 s49, s41, s30
	global_load_lds_dwordx4 v[222:223], off
	v_lshl_add_u64 v[224:225], s[50:51], 0, v[166:167]
	s_mov_b32 m0, s49
	v_lshl_add_u64 v[226:227], s[26:27], 0, v[168:169]
	global_load_lds_dwordx4 v[224:225], off
	v_lshl_add_u64 v[224:225], s[50:51], 0, v[170:171]
	s_add_i32 m0, s49, 0x2000
	s_nop 0
	global_load_lds_dwordx4 v[224:225], off
	v_lshl_add_u64 v[224:225], s[26:27], 0, v[164:165]
	s_mov_b32 m0, s31
	s_nop 0
	global_load_lds_dwordx4 v[224:225], off
	s_mov_b32 m0, s33
	s_nop 0
	global_load_lds_dwordx4 v[226:227], off
	s_waitcnt vmcnt(8)
	s_waitcnt lgkmcnt(0)
	s_barrier
; #define PG8_STAGE(bufoff, gbase, voff) do { _Pragma("unroll") for (int _i = 0; _i < 2; ++_i) \
;         __builtin_amdgcn_global_load_lds((const unsigned*)((const char*)(gbase) + (voff)[_i]), (PG8_LAS unsigned*)(lds + (bufoff) + ldsw + _i * 8192), 16, 0, 0); } while (0)
; #define PG8_LDA(dst, b, h) do { _Pragma("unroll") for (int m = 0; m < 4; ++m) _Pragma("unroll") for (int k = 0; k < 2; ++k) dst[m][k] = *(const PG8_LAS bf16x8*)(lds + PG8_SA(b, h) + aoff + m * 2048 + k * 1024); } while (0)
; #define PG8_LDB(dst, b, h) do { _Pragma("unroll") for (int n = 0; n < 2; ++n) _Pragma("unroll") for (int k = 0; k < 2; ++k) dst[n][k] = *(const PG8_LAS bf16x8*)(lds + PG8_SB(b, h) + boff + n * 2048 + k * 1024); } while (0)
; #define PG8_MMA(ai, bj, At, Bt) do { __builtin_amdgcn_s_setprio(1); _Pragma("unroll") for (int m = 0; m < 4; ++m) _Pragma("unroll") for (int n = 0; n < 2; ++n) _Pragma("unroll") for (int k = 0; k < 2; ++k) \
;         acc[ai][bj][m][n] = __builtin_amdgcn_mfma_f32_16x16x32_bf16(Bt[n][k], At[m][k], acc[ai][bj][m][n], 0, 0, 0); __builtin_amdgcn_s_setprio(0); } while (0)
; #define PG8_WAIT_V(n) asm volatile("s_waitcnt vmcnt(" #n ")" ::: "memory")
; #define PG8_WAIT_L(n) asm volatile("s_waitcnt lgkmcnt(" #n ")" ::: "memory")
; #define PG8_BAR __builtin_amdgcn_s_barrier()
; #define PG8_SCHED __builtin_amdgcn_sched_barrier(0)
; template <class Epi, class Sched, bool ALIGN_EPI = false, bool SP2 = false, bool DUAL = false>
; __device__ __forceinline__ void gemm_phase(PG8_LAS unsigned char* lds, const Gemm g, const Sched& S, const Epi& E) {
;     ...
;             PG8_WAIT_V(8); PG8_WAIT_L(0); PG8_BAR; PG8_MMA(1, 0, At, B0); PG8_MMA(1, 1, At, B1); PG8_BAR; PG8_SCHED;
;             PG8_LDB(B0, 1, 0); PG8_LDB(B1, 1, 1); PG8_SCHED; PG8_LDA(At, 1, 0); PG8_STAGE(PG8_SA(0, 1), a2 + hstep, voffA);
;             PG8_WAIT_V(8); PG8_WAIT_L(0); PG8_BAR; PG8_MMA(0, 0, At, B0); PG8_MMA(0, 1, At, B1); PG8_BAR; PG8_SCHED;
	s_setprio 1
	s_waitcnt lgkmcnt(0)
	v_mfma_f32_16x16x32_bf16 v[60:63], v[128:131], v[160:163], 0
	v_mfma_f32_16x16x32_bf16 v[56:59], v[136:139], v[160:163], 0
	v_mfma_f32_16x16x32_bf16 v[48:51], v[128:131], v[186:189], 0
	v_mfma_f32_16x16x32_bf16 v[40:43], v[136:139], v[186:189], 0
	v_mfma_f32_16x16x32_bf16 v[32:35], v[128:131], v[204:207], 0
	v_mfma_f32_16x16x32_bf16 v[24:27], v[136:139], v[204:207], 0
	v_mfma_f32_16x16x32_bf16 v[16:19], v[128:131], v[212:215], 0
	v_mfma_f32_16x16x32_bf16 v[8:11], v[136:139], v[212:215], 0
	v_mfma_f32_16x16x32_bf16 v[60:63], v[132:135], v[182:185], v[60:63]
	v_mfma_f32_16x16x32_bf16 v[56:59], v[140:143], v[182:185], v[56:59]
	v_mfma_f32_16x16x32_bf16 v[48:51], v[132:135], v[190:193], v[48:51]
	v_mfma_f32_16x16x32_bf16 v[40:43], v[140:143], v[190:193], v[40:43]
	v_mfma_f32_16x16x32_bf16 v[32:35], v[132:135], v[208:211], v[32:35]
	v_mfma_f32_16x16x32_bf16 v[24:27], v[140:143], v[208:211], v[24:27]
	v_mfma_f32_16x16x32_bf16 v[16:19], v[132:135], v[216:219], v[16:19]
	v_mfma_f32_16x16x32_bf16 v[8:11], v[140:143], v[216:219], v[8:11]
	s_setprio 0
	s_setprio 1
	v_mfma_f32_16x16x32_bf16 v[52:55], v[144:147], v[160:163], 0
	v_mfma_f32_16x16x32_bf16 v[44:47], v[152:155], v[160:163], 0
	v_mfma_f32_16x16x32_bf16 v[36:39], v[144:147], v[186:189], 0
	v_mfma_f32_16x16x32_bf16 v[28:31], v[152:155], v[186:189], 0
	v_mfma_f32_16x16x32_bf16 v[20:23], v[144:147], v[204:207], 0
	v_mfma_f32_16x16x32_bf16 v[12:15], v[152:155], v[204:207], 0
	v_mfma_f32_16x16x32_bf16 v[4:7], v[144:147], v[212:215], 0
	v_mfma_f32_16x16x32_bf16 v[0:3], v[152:155], v[212:215], 0
	v_mfma_f32_16x16x32_bf16 v[52:55], v[148:151], v[182:185], v[52:55]
	v_mfma_f32_16x16x32_bf16 v[44:47], v[156:159], v[182:185], v[44:47]
	v_mfma_f32_16x16x32_bf16 v[36:39], v[148:151], v[190:193], v[36:39]
	v_mfma_f32_16x16x32_bf16 v[28:31], v[156:159], v[190:193], v[28:31]
	v_mfma_f32_16x16x32_bf16 v[20:23], v[148:151], v[208:211], v[20:23]
	v_mfma_f32_16x16x32_bf16 v[12:15], v[156:159], v[208:211], v[12:15]
	v_mfma_f32_16x16x32_bf16 v[4:7], v[148:151], v[216:219], v[4:7]
	v_mfma_f32_16x16x32_bf16 v[0:3], v[156:159], v[216:219], v[0:3]
	s_setprio 0
	s_barrier
	s_add_i32 s49, 0, 0x18000
	s_add_i32 s50, 0, 0x1c000
	v_add_u32_e32 v140, s49, v198
	v_add_u32_e32 v156, s50, v198
	ds_read_b128 v[128:131], v140
	ds_read_b128 v[132:135], v140 offset:1024
	ds_read_b128 v[136:139], v140 offset:2048
	ds_read_b128 v[140:143], v140 offset:3072
	ds_read_b128 v[144:147], v156
	ds_read_b128 v[148:151], v156 offset:1024
	ds_read_b128 v[152:155], v156 offset:2048
	ds_read_b128 v[156:159], v156 offset:3072
	s_add_u32 s26, s26, 0x160000
	s_addc_u32 s27, s27, 0
	s_mov_b32 m0, s34
	v_lshl_add_u64 v[228:229], s[26:27], 0, v[164:165]
	ds_read_b128 v[160:163], v203 offset:32768
	ds_read_b128 v[182:185], v203 offset:33792
	ds_read_b128 v[186:189], v203 offset:34816
	ds_read_b128 v[190:193], v203 offset:35840
	ds_read_b128 v[204:207], v203 offset:36864
	ds_read_b128 v[208:211], v203 offset:37888
	ds_read_b128 v[212:215], v203 offset:38912
	ds_read_b128 v[216:219], v203 offset:39936
	global_load_lds_dwordx4 v[228:229], off
	v_lshl_add_u64 v[228:229], s[26:27], 0, v[168:169]
	s_mov_b32 m0, s35
	s_nop 0
	global_load_lds_dwordx4 v[228:229], off
	s_waitcnt vmcnt(8)
	s_waitcnt lgkmcnt(0)
	s_barrier
	s_setprio 1
	s_waitcnt lgkmcnt(0)
	v_mfma_f32_16x16x32_bf16 v[124:127], v[128:131], v[160:163], v[124:127]
	v_mfma_f32_16x16x32_bf16 v[120:123], v[136:139], v[160:163], v[120:123]
	v_mfma_f32_16x16x32_bf16 v[112:115], v[128:131], v[186:189], v[112:115]
	v_mfma_f32_16x16x32_bf16 v[104:107], v[136:139], v[186:189], v[104:107]
	v_mfma_f32_16x16x32_bf16 v[96:99], v[128:131], v[204:207], v[96:99]
	v_mfma_f32_16x16x32_bf16 v[88:91], v[136:139], v[204:207], v[88:91]
	v_mfma_f32_16x16x32_bf16 v[80:83], v[128:131], v[212:215], v[80:83]
	v_mfma_f32_16x16x32_bf16 v[72:75], v[136:139], v[212:215], v[72:75]
	v_mfma_f32_16x16x32_bf16 v[124:127], v[132:135], v[182:185], v[124:127]
	v_mfma_f32_16x16x32_bf16 v[120:123], v[140:143], v[182:185], v[120:123]
	v_mfma_f32_16x16x32_bf16 v[112:115], v[132:135], v[190:193], v[112:115]
	v_mfma_f32_16x16x32_bf16 v[104:107], v[140:143], v[190:193], v[104:107]
	v_mfma_f32_16x16x32_bf16 v[96:99], v[132:135], v[208:211], v[96:99]
	v_mfma_f32_16x16x32_bf16 v[88:91], v[140:143], v[208:211], v[88:91]
	v_mfma_f32_16x16x32_bf16 v[80:83], v[132:135], v[216:219], v[80:83]
	v_mfma_f32_16x16x32_bf16 v[72:75], v[140:143], v[216:219], v[72:75]
	s_setprio 0
	s_setprio 1
	v_mfma_f32_16x16x32_bf16 v[116:119], v[144:147], v[160:163], v[116:119]
	v_mfma_f32_16x16x32_bf16 v[108:111], v[152:155], v[160:163], v[108:111]
	v_mfma_f32_16x16x32_bf16 v[100:103], v[144:147], v[186:189], v[100:103]
	v_mfma_f32_16x16x32_bf16 v[92:95], v[152:155], v[186:189], v[92:95]
	v_mfma_f32_16x16x32_bf16 v[84:87], v[144:147], v[204:207], v[84:87]
	v_mfma_f32_16x16x32_bf16 v[76:79], v[152:155], v[204:207], v[76:79]
	v_mfma_f32_16x16x32_bf16 v[68:71], v[144:147], v[212:215], v[68:71]
	v_mfma_f32_16x16x32_bf16 v[64:67], v[152:155], v[212:215], v[64:67]
	v_mfma_f32_16x16x32_bf16 v[116:119], v[148:151], v[182:185], v[116:119]
	v_mfma_f32_16x16x32_bf16 v[108:111], v[156:159], v[182:185], v[108:111]
	v_mfma_f32_16x16x32_bf16 v[100:103], v[148:151], v[190:193], v[100:103]
	v_mfma_f32_16x16x32_bf16 v[92:95], v[156:159], v[190:193], v[92:95]
	v_mfma_f32_16x16x32_bf16 v[84:87], v[148:151], v[208:211], v[84:87]
	v_mfma_f32_16x16x32_bf16 v[76:79], v[156:159], v[208:211], v[76:79]
	v_mfma_f32_16x16x32_bf16 v[68:71], v[148:151], v[216:219], v[68:71]
	v_mfma_f32_16x16x32_bf16 v[64:67], v[156:159], v[216:219], v[64:67]
	s_setprio 0
	s_barrier
; #define PG8_STAGE(bufoff, gbase, voff) do { _Pragma("unroll") for (int _i = 0; _i < 2; ++_i) \
;         __builtin_amdgcn_global_load_lds((const unsigned*)((const char*)(gbase) + (voff)[_i]), (PG8_LAS unsigned*)(lds + (bufoff) + ldsw + _i * 8192), 16, 0, 0); } while (0)
; #define PG8_LDA(dst, b, h) do { _Pragma("unroll") for (int m = 0; m < 4; ++m) _Pragma("unroll") for (int k = 0; k < 2; ++k) dst[m][k] = *(const PG8_LAS bf16x8*)(lds + PG8_SA(b, h) + aoff + m * 2048 + k * 1024); } while (0)
; #define PG8_LDB(dst, b, h) do { _Pragma("unroll") for (int n = 0; n < 2; ++n) _Pragma("unroll") for (int k = 0; k < 2; ++k) dst[n][k] = *(const PG8_LAS bf16x8*)(lds + PG8_SB(b, h) + boff + n * 2048 + k * 1024); } while (0)
; #define PG8_MMA(ai, bj, At, Bt) do { __builtin_amdgcn_s_setprio(1); _Pragma("unroll") for (int m = 0; m < 4; ++m) _Pragma("unroll") for (int n = 0; n < 2; ++n) _Pragma("unroll") for (int k = 0; k < 2; ++k) \
;         acc[ai][bj][m][n] = __builtin_amdgcn_mfma_f32_16x16x32_bf16(Bt[n][k], At[m][k], acc[ai][bj][m][n], 0, 0, 0); __builtin_amdgcn_s_setprio(0); } while (0)
; #define PG8_WAIT_V(n) asm volatile("s_waitcnt vmcnt(" #n ")" ::: "memory")
; #define PG8_BAR __builtin_amdgcn_s_barrier()
; template <class Epi, class Sched, bool ALIGN_EPI = false, bool SP2 = false, bool DUAL = false>
; __device__ __forceinline__ void gemm_phase(PG8_LAS unsigned char* lds, const Gemm g, const Sched& S, const Epi& E) {
;     ...
;         for (int t = 0; t < nt; t += 2) {
;             const bool last = (t == nt - 2);
;             const char* a1 = cA + (size_t)(t + 1) * kstep;
;             const char* a2 = last ? nA : cA + (size_t)(t + 2) * kstep; const char* b2 = last ? nB : cB + (size_t)(t + 2) * kstep;
;             const char* a3 = a2 + kstep; const char* b3 = b2 + kstep;
;             if (last && has_next) S.a_ready(nxt);
;             if constexpr (SP2) {
;             PG8_LDB(B0, 0, 0); PG8_LDB(B1, 0, 1); PG8_SCHED; PG8_LDA(At, 0, 0); PG8_STAGE(PG8_SA(1, 1), a1 + hstep, voffA);
;             PG8_WAIT_V(8); PG8_WAIT_L(0); PG8_BAR; PG8_MMA(0, 0, At, B0); PG8_MMA(0, 1, At, B1); PG8_BAR; PG8_SCHED;
;     ...
;             PG8_LDA(At, 1, 1); PG8_STAGE(PG8_SB(1, 0), b3, voffB); PG8_STAGE(PG8_SB(1, 1), b3 + hstep, voffB); PG8_STAGE(PG8_SA(1, 0), a3, voffA);
;             PG8_WAIT_V(8); PG8_WAIT_L(0); PG8_BAR; PG8_MMA(1, 0, At, B0); PG8_MMA(1, 1, At, B1); PG8_BAR; PG8_SCHED;
	s_add_i32 s26, s49, s30
	v_lshl_add_u64 v[220:221], v[220:221], 0, s[18:19]
	s_mov_b32 m0, s26
	ds_read_b128 v[160:163], v203 offset:49152
	ds_read_b128 v[182:185], v203 offset:50176
	ds_read_b128 v[186:189], v203 offset:51200
	ds_read_b128 v[190:193], v203 offset:52224
	ds_read_b128 v[204:207], v203 offset:53248
	ds_read_b128 v[208:211], v203 offset:54272
	ds_read_b128 v[212:215], v203 offset:55296
	ds_read_b128 v[216:219], v203 offset:56320
	global_load_lds_dwordx4 v[220:221], off
	s_add_i32 m0, s26, 0x2000
	s_add_u32 s14, s14, 0x160080
	v_lshl_add_u64 v[220:221], v[222:223], 0, s[18:19]
	s_addc_u32 s15, s15, 0
	s_add_i32 s26, s50, s30
	global_load_lds_dwordx4 v[220:221], off
	v_lshl_add_u64 v[220:221], s[14:15], 0, v[166:167]
	s_mov_b32 m0, s26
	s_nop 0
	global_load_lds_dwordx4 v[220:221], off
	v_lshl_add_u64 v[220:221], s[14:15], 0, v[170:171]
	s_add_i32 m0, s26, 0x2000
	s_nop 0
	global_load_lds_dwordx4 v[220:221], off
	v_lshl_add_u64 v[220:221], v[224:225], 0, s[18:19]
	s_mov_b32 m0, s37
	s_nop 0
	global_load_lds_dwordx4 v[220:221], off
	v_lshl_add_u64 v[220:221], v[226:227], 0, s[18:19]
	s_mov_b32 m0, s38
	s_nop 0
	global_load_lds_dwordx4 v[220:221], off
	s_waitcnt vmcnt(8)
	s_waitcnt lgkmcnt(0)
	s_barrier
	s_setprio 1
	s_waitcnt lgkmcnt(0)
	v_mfma_f32_16x16x32_bf16 v[60:63], v[128:131], v[160:163], v[60:63]
	v_mfma_f32_16x16x32_bf16 v[56:59], v[136:139], v[160:163], v[56:59]
	v_mfma_f32_16x16x32_bf16 v[48:51], v[128:131], v[186:189], v[48:51]
	v_mfma_f32_16x16x32_bf16 v[40:43], v[136:139], v[186:189], v[40:43]
	v_mfma_f32_16x16x32_bf16 v[32:35], v[128:131], v[204:207], v[32:35]
	v_mfma_f32_16x16x32_bf16 v[24:27], v[136:139], v[204:207], v[24:27]
	v_mfma_f32_16x16x32_bf16 v[16:19], v[128:131], v[212:215], v[16:19]
	v_mfma_f32_16x16x32_bf16 v[8:11], v[136:139], v[212:215], v[8:11]
	v_mfma_f32_16x16x32_bf16 v[60:63], v[132:135], v[182:185], v[60:63]
	v_mfma_f32_16x16x32_bf16 v[56:59], v[140:143], v[182:185], v[56:59]
	v_mfma_f32_16x16x32_bf16 v[48:51], v[132:135], v[190:193], v[48:51]
	v_mfma_f32_16x16x32_bf16 v[40:43], v[140:143], v[190:193], v[40:43]
	v_mfma_f32_16x16x32_bf16 v[32:35], v[132:135], v[208:211], v[32:35]
	v_mfma_f32_16x16x32_bf16 v[24:27], v[140:143], v[208:211], v[24:27]
	v_mfma_f32_16x16x32_bf16 v[16:19], v[132:135], v[216:219], v[16:19]
	v_mfma_f32_16x16x32_bf16 v[8:11], v[140:143], v[216:219], v[8:11]
	s_setprio 0
	s_setprio 1
	v_mfma_f32_16x16x32_bf16 v[52:55], v[144:147], v[160:163], v[52:55]
	v_mfma_f32_16x16x32_bf16 v[44:47], v[152:155], v[160:163], v[44:47]
	v_mfma_f32_16x16x32_bf16 v[36:39], v[144:147], v[186:189], v[36:39]
	v_mfma_f32_16x16x32_bf16 v[28:31], v[152:155], v[186:189], v[28:31]
	v_mfma_f32_16x16x32_bf16 v[20:23], v[144:147], v[204:207], v[20:23]
	v_mfma_f32_16x16x32_bf16 v[12:15], v[152:155], v[204:207], v[12:15]
	v_mfma_f32_16x16x32_bf16 v[4:7], v[144:147], v[212:215], v[4:7]
	v_mfma_f32_16x16x32_bf16 v[0:3], v[152:155], v[212:215], v[0:3]
	v_mfma_f32_16x16x32_bf16 v[52:55], v[148:151], v[182:185], v[52:55]
	v_mfma_f32_16x16x32_bf16 v[44:47], v[156:159], v[182:185], v[44:47]
	v_mfma_f32_16x16x32_bf16 v[36:39], v[148:151], v[190:193], v[36:39]
	v_mfma_f32_16x16x32_bf16 v[28:31], v[156:159], v[190:193], v[28:31]
	v_mfma_f32_16x16x32_bf16 v[20:23], v[148:151], v[208:211], v[20:23]
	v_mfma_f32_16x16x32_bf16 v[12:15], v[156:159], v[208:211], v[12:15]
	v_mfma_f32_16x16x32_bf16 v[4:7], v[148:151], v[216:219], v[4:7]
	v_mfma_f32_16x16x32_bf16 v[0:3], v[156:159], v[216:219], v[0:3]
	s_setprio 0
	s_barrier
	s_add_i32 s48, s48, 2
	s_add_u32 s24, s24, 0x100
	s_addc_u32 s25, s25, 0
	s_add_u32 s46, s46, 0x100
	s_addc_u32 s47, s47, 0
.LBB0_1193:
	ds_read_b128 v[128:131], v201
	ds_read_b128 v[132:135], v201 offset:1024
	ds_read_b128 v[136:139], v201 offset:2048
	ds_read_b128 v[140:143], v201 offset:3072
	ds_read_b128 v[144:147], v202
	ds_read_b128 v[148:151], v202 offset:1024
	ds_read_b128 v[152:155], v202 offset:2048
	ds_read_b128 v[156:159], v202 offset:3072
	s_add_u32 s14, s24, 0xffea0080
	s_addc_u32 s15, s25, -1
	s_cmpk_eq_i32 s48, 0x54
	s_cselect_b32 s27, s5, s15
	s_cselect_b32 s26, s4, s14
	s_cselect_b32 s15, s23, s47
	s_cselect_b32 s14, s22, s46
	v_lshl_add_u64 v[220:221], s[24:25], 0, v[172:173]
	s_add_i32 m0, s31, 0xc000
	ds_read_b128 v[160:163], v203
	ds_read_b128 v[182:185], v203 offset:1024
	ds_read_b128 v[186:189], v203 offset:2048
	ds_read_b128 v[190:193], v203 offset:3072
	ds_read_b128 v[204:207], v203 offset:4096
	ds_read_b128 v[208:211], v203 offset:5120
	ds_read_b128 v[212:215], v203 offset:6144
	ds_read_b128 v[216:219], v203 offset:7168
	global_load_lds_dwordx4 v[220:221], off
	v_lshl_add_u64 v[220:221], s[24:25], 0, v[174:175]
	s_add_i32 m0, s31, 0xe000
	s_nop 0
	global_load_lds_dwordx4 v[220:221], off
	s_waitcnt vmcnt(8)
	s_waitcnt lgkmcnt(0)
	s_barrier
; #define PG8_STAGE(bufoff, gbase, voff) do { _Pragma("unroll") for (int _i = 0; _i < 2; ++_i) \
;         __builtin_amdgcn_global_load_lds((const unsigned*)((const char*)(gbase) + (voff)[_i]), (PG8_LAS unsigned*)(lds + (bufoff) + ldsw + _i * 8192), 16, 0, 0); } while (0)
; #define PG8_LDA(dst, b, h) do { _Pragma("unroll") for (int m = 0; m < 4; ++m) _Pragma("unroll") for (int k = 0; k < 2; ++k) dst[m][k] = *(const PG8_LAS bf16x8*)(lds + PG8_SA(b, h) + aoff + m * 2048 + k * 1024); } while (0)
; #define PG8_MMA(ai, bj, At, Bt) do { __builtin_amdgcn_s_setprio(1); _Pragma("unroll") for (int m = 0; m < 4; ++m) _Pragma("unroll") for (int n = 0; n < 2; ++n) _Pragma("unroll") for (int k = 0; k < 2; ++k) \
;         acc[ai][bj][m][n] = __builtin_amdgcn_mfma_f32_16x16x32_bf16(Bt[n][k], At[m][k], acc[ai][bj][m][n], 0, 0, 0); __builtin_amdgcn_s_setprio(0); } while (0)
; #define PG8_WAIT_V(n) asm volatile("s_waitcnt vmcnt(" #n ")" ::: "memory")
; #define PG8_WAIT_L(n) asm volatile("s_waitcnt lgkmcnt(" #n ")" ::: "memory")
; #define PG8_BAR __builtin_amdgcn_s_barrier()
; #define PG8_SCHED __builtin_amdgcn_sched_barrier(0)
; template <class Epi, class Sched, bool ALIGN_EPI = false, bool SP2 = false, bool DUAL = false>
; __device__ __forceinline__ void gemm_phase(PG8_LAS unsigned char* lds, const Gemm g, const Sched& S, const Epi& E) {
;     ...
;             PG8_WAIT_V(8); PG8_WAIT_L(0); PG8_BAR; PG8_MMA(0, 0, At, B0); PG8_MMA(0, 1, At, B1); PG8_BAR; PG8_SCHED;
;             PG8_LDA(At, 0, 1); PG8_STAGE(PG8_SB(0, 0), b2, voffB); PG8_STAGE(PG8_SB(0, 1), b2 + hstep, voffB); PG8_STAGE(PG8_SA(0, 0), a2, voffA);
;             PG8_WAIT_V(8); PG8_WAIT_L(0); PG8_BAR; PG8_MMA(1, 0, At, B0); PG8_MMA(1, 1, At, B1); PG8_BAR; PG8_SCHED;
	s_setprio 1
	s_waitcnt lgkmcnt(0)
	v_mfma_f32_16x16x32_bf16 v[124:127], v[128:131], v[160:163], v[124:127]
	v_mfma_f32_16x16x32_bf16 v[120:123], v[136:139], v[160:163], v[120:123]
	v_mfma_f32_16x16x32_bf16 v[112:115], v[128:131], v[186:189], v[112:115]
	v_mfma_f32_16x16x32_bf16 v[104:107], v[136:139], v[186:189], v[104:107]
	v_mfma_f32_16x16x32_bf16 v[96:99], v[128:131], v[204:207], v[96:99]
	v_mfma_f32_16x16x32_bf16 v[88:91], v[136:139], v[204:207], v[88:91]
	v_mfma_f32_16x16x32_bf16 v[80:83], v[128:131], v[212:215], v[80:83]
	v_mfma_f32_16x16x32_bf16 v[72:75], v[136:139], v[212:215], v[72:75]
	v_mfma_f32_16x16x32_bf16 v[124:127], v[132:135], v[182:185], v[124:127]
	v_mfma_f32_16x16x32_bf16 v[120:123], v[140:143], v[182:185], v[120:123]
	v_mfma_f32_16x16x32_bf16 v[112:115], v[132:135], v[190:193], v[112:115]
	v_mfma_f32_16x16x32_bf16 v[104:107], v[140:143], v[190:193], v[104:107]
	v_mfma_f32_16x16x32_bf16 v[96:99], v[132:135], v[208:211], v[96:99]
	v_mfma_f32_16x16x32_bf16 v[88:91], v[140:143], v[208:211], v[88:91]
	v_mfma_f32_16x16x32_bf16 v[80:83], v[132:135], v[216:219], v[80:83]
	v_mfma_f32_16x16x32_bf16 v[72:75], v[140:143], v[216:219], v[72:75]
	s_setprio 0
	s_setprio 1
	v_mfma_f32_16x16x32_bf16 v[116:119], v[144:147], v[160:163], v[116:119]
	v_mfma_f32_16x16x32_bf16 v[108:111], v[152:155], v[160:163], v[108:111]
	v_mfma_f32_16x16x32_bf16 v[100:103], v[144:147], v[186:189], v[100:103]
	v_mfma_f32_16x16x32_bf16 v[92:95], v[152:155], v[186:189], v[92:95]
	v_mfma_f32_16x16x32_bf16 v[84:87], v[144:147], v[204:207], v[84:87]
	v_mfma_f32_16x16x32_bf16 v[76:79], v[152:155], v[204:207], v[76:79]
	v_mfma_f32_16x16x32_bf16 v[68:71], v[144:147], v[212:215], v[68:71]
	v_mfma_f32_16x16x32_bf16 v[64:67], v[152:155], v[212:215], v[64:67]
	v_mfma_f32_16x16x32_bf16 v[116:119], v[148:151], v[182:185], v[116:119]
	v_mfma_f32_16x16x32_bf16 v[108:111], v[156:159], v[182:185], v[108:111]
	v_mfma_f32_16x16x32_bf16 v[100:103], v[148:151], v[190:193], v[100:103]
	v_mfma_f32_16x16x32_bf16 v[92:95], v[156:159], v[190:193], v[92:95]
	v_mfma_f32_16x16x32_bf16 v[84:87], v[148:151], v[208:211], v[84:87]
	v_mfma_f32_16x16x32_bf16 v[76:79], v[156:159], v[208:211], v[76:79]
	v_mfma_f32_16x16x32_bf16 v[68:71], v[148:151], v[216:219], v[68:71]
	v_mfma_f32_16x16x32_bf16 v[64:67], v[156:159], v[216:219], v[64:67]
	s_setprio 0
	s_barrier
	s_add_i32 s49, s40, s30
	v_lshl_add_u64 v[220:221], s[14:15], 0, v[166:167]
	s_mov_b32 m0, s49
	ds_read_b128 v[160:163], v203 offset:16384
	ds_read_b128 v[182:185], v203 offset:17408
	ds_read_b128 v[186:189], v203 offset:18432
	ds_read_b128 v[190:193], v203 offset:19456
	ds_read_b128 v[204:207], v203 offset:20480
	ds_read_b128 v[208:211], v203 offset:21504
	ds_read_b128 v[212:215], v203 offset:22528
	ds_read_b128 v[216:219], v203 offset:23552
	global_load_lds_dwordx4 v[220:221], off
	s_add_i32 m0, s49, 0x2000
	s_add_u32 s50, s14, 0x160000
	v_lshl_add_u64 v[222:223], s[14:15], 0, v[170:171]
	s_addc_u32 s51, s15, 0
	s_add_i32 s49, s41, s30
	global_load_lds_dwordx4 v[222:223], off
	v_lshl_add_u64 v[224:225], s[50:51], 0, v[166:167]
	s_mov_b32 m0, s49
	v_lshl_add_u64 v[226:227], s[26:27], 0, v[168:169]
	global_load_lds_dwordx4 v[224:225], off
	v_lshl_add_u64 v[224:225], s[50:51], 0, v[170:171]
	s_add_i32 m0, s49, 0x2000
	s_nop 0
	global_load_lds_dwordx4 v[224:225], off
	v_lshl_add_u64 v[224:225], s[26:27], 0, v[164:165]
	s_mov_b32 m0, s31
	s_nop 0
	global_load_lds_dwordx4 v[224:225], off
	s_mov_b32 m0, s33
	s_nop 0
	global_load_lds_dwordx4 v[226:227], off
	s_waitcnt vmcnt(8)
	s_waitcnt lgkmcnt(0)
	s_barrier
	s_setprio 1
	s_waitcnt lgkmcnt(0)
	v_mfma_f32_16x16x32_bf16 v[60:63], v[128:131], v[160:163], v[60:63]
	v_mfma_f32_16x16x32_bf16 v[56:59], v[136:139], v[160:163], v[56:59]
	v_mfma_f32_16x16x32_bf16 v[48:51], v[128:131], v[186:189], v[48:51]
	v_mfma_f32_16x16x32_bf16 v[40:43], v[136:139], v[186:189], v[40:43]
	v_mfma_f32_16x16x32_bf16 v[32:35], v[128:131], v[204:207], v[32:35]
	v_mfma_f32_16x16x32_bf16 v[24:27], v[136:139], v[204:207], v[24:27]
	v_mfma_f32_16x16x32_bf16 v[16:19], v[128:131], v[212:215], v[16:19]
	v_mfma_f32_16x16x32_bf16 v[8:11], v[136:139], v[212:215], v[8:11]
	v_mfma_f32_16x16x32_bf16 v[60:63], v[132:135], v[182:185], v[60:63]
	v_mfma_f32_16x16x32_bf16 v[56:59], v[140:143], v[182:185], v[56:59]
	v_mfma_f32_16x16x32_bf16 v[48:51], v[132:135], v[190:193], v[48:51]
	v_mfma_f32_16x16x32_bf16 v[40:43], v[140:143], v[190:193], v[40:43]
	v_mfma_f32_16x16x32_bf16 v[32:35], v[132:135], v[208:211], v[32:35]
	v_mfma_f32_16x16x32_bf16 v[24:27], v[140:143], v[208:211], v[24:27]
	v_mfma_f32_16x16x32_bf16 v[16:19], v[132:135], v[216:219], v[16:19]
	v_mfma_f32_16x16x32_bf16 v[8:11], v[140:143], v[216:219], v[8:11]
	s_setprio 0
	s_setprio 1
	v_mfma_f32_16x16x32_bf16 v[52:55], v[144:147], v[160:163], v[52:55]
	v_mfma_f32_16x16x32_bf16 v[44:47], v[152:155], v[160:163], v[44:47]
	v_mfma_f32_16x16x32_bf16 v[36:39], v[144:147], v[186:189], v[36:39]
	v_mfma_f32_16x16x32_bf16 v[28:31], v[152:155], v[186:189], v[28:31]
	v_mfma_f32_16x16x32_bf16 v[20:23], v[144:147], v[204:207], v[20:23]
	v_mfma_f32_16x16x32_bf16 v[12:15], v[152:155], v[204:207], v[12:15]
	v_mfma_f32_16x16x32_bf16 v[4:7], v[144:147], v[212:215], v[4:7]
	v_mfma_f32_16x16x32_bf16 v[0:3], v[152:155], v[212:215], v[0:3]
	v_mfma_f32_16x16x32_bf16 v[52:55], v[148:151], v[182:185], v[52:55]
	v_mfma_f32_16x16x32_bf16 v[44:47], v[156:159], v[182:185], v[44:47]
	v_mfma_f32_16x16x32_bf16 v[36:39], v[148:151], v[190:193], v[36:39]
	v_mfma_f32_16x16x32_bf16 v[28:31], v[156:159], v[190:193], v[28:31]
	v_mfma_f32_16x16x32_bf16 v[20:23], v[148:151], v[208:211], v[20:23]
	v_mfma_f32_16x16x32_bf16 v[12:15], v[156:159], v[208:211], v[12:15]
	v_mfma_f32_16x16x32_bf16 v[4:7], v[148:151], v[216:219], v[4:7]
	v_mfma_f32_16x16x32_bf16 v[0:3], v[156:159], v[216:219], v[0:3]
	s_setprio 0
	s_barrier
; #define PG8_STAGE(bufoff, gbase, voff) do { _Pragma("unroll") for (int _i = 0; _i < 2; ++_i) \
;         __builtin_amdgcn_global_load_lds((const unsigned*)((const char*)(gbase) + (voff)[_i]), (PG8_LAS unsigned*)(lds + (bufoff) + ldsw + _i * 8192), 16, 0, 0); } while (0)
; #define PG8_LDA(dst, b, h) do { _Pragma("unroll") for (int m = 0; m < 4; ++m) _Pragma("unroll") for (int k = 0; k < 2; ++k) dst[m][k] = *(const PG8_LAS bf16x8*)(lds + PG8_SA(b, h) + aoff + m * 2048 + k * 1024); } while (0)
; #define PG8_LDB(dst, b, h) do { _Pragma("unroll") for (int n = 0; n < 2; ++n) _Pragma("unroll") for (int k = 0; k < 2; ++k) dst[n][k] = *(const PG8_LAS bf16x8*)(lds + PG8_SB(b, h) + boff + n * 2048 + k * 1024); } while (0)
; #define PG8_MMA(ai, bj, At, Bt) do { __builtin_amdgcn_s_setprio(1); _Pragma("unroll") for (int m = 0; m < 4; ++m) _Pragma("unroll") for (int n = 0; n < 2; ++n) _Pragma("unroll") for (int k = 0; k < 2; ++k) \
;         acc[ai][bj][m][n] = __builtin_amdgcn_mfma_f32_16x16x32_bf16(Bt[n][k], At[m][k], acc[ai][bj][m][n], 0, 0, 0); __builtin_amdgcn_s_setprio(0); } while (0)
; #define PG8_WAIT_V(n) asm volatile("s_waitcnt vmcnt(" #n ")" ::: "memory")
; #define PG8_WAIT_L(n) asm volatile("s_waitcnt lgkmcnt(" #n ")" ::: "memory")
; #define PG8_BAR __builtin_amdgcn_s_barrier()
; #define PG8_SCHED __builtin_amdgcn_sched_barrier(0)
; template <class Epi, class Sched, bool ALIGN_EPI = false, bool SP2 = false, bool DUAL = false>
; __device__ __forceinline__ void gemm_phase(PG8_LAS unsigned char* lds, const Gemm g, const Sched& S, const Epi& E) {
;     ...
;             PG8_LDB(B0, 1, 0); PG8_LDB(B1, 1, 1); PG8_SCHED; PG8_LDA(At, 1, 0); PG8_STAGE(PG8_SA(0, 1), a2 + hstep, voffA);
;             PG8_WAIT_V(8); PG8_WAIT_L(0); PG8_BAR; PG8_MMA(0, 0, At, B0); PG8_MMA(0, 1, At, B1); PG8_BAR; PG8_SCHED;
	s_add_i32 s49, 0, 0x18000
	s_add_i32 s50, 0, 0x1c000
	v_add_u32_e32 v140, s49, v198
	v_add_u32_e32 v156, s50, v198
	ds_read_b128 v[128:131], v140
	ds_read_b128 v[132:135], v140 offset:1024
	ds_read_b128 v[136:139], v140 offset:2048
	ds_read_b128 v[140:143], v140 offset:3072
	ds_read_b128 v[144:147], v156
	ds_read_b128 v[148:151], v156 offset:1024
	ds_read_b128 v[152:155], v156 offset:2048
	ds_read_b128 v[156:159], v156 offset:3072
	s_add_u32 s26, s26, 0x160000
	s_addc_u32 s27, s27, 0
	s_mov_b32 m0, s34
	v_lshl_add_u64 v[228:229], s[26:27], 0, v[164:165]
	ds_read_b128 v[160:163], v203 offset:32768
	ds_read_b128 v[182:185], v203 offset:33792
	ds_read_b128 v[186:189], v203 offset:34816
	ds_read_b128 v[190:193], v203 offset:35840
	ds_read_b128 v[204:207], v203 offset:36864
	ds_read_b128 v[208:211], v203 offset:37888
	ds_read_b128 v[212:215], v203 offset:38912
	ds_read_b128 v[216:219], v203 offset:39936
	global_load_lds_dwordx4 v[228:229], off
	v_lshl_add_u64 v[228:229], s[26:27], 0, v[168:169]
	s_mov_b32 m0, s35
	s_nop 0
	global_load_lds_dwordx4 v[228:229], off
	s_waitcnt vmcnt(8)
	s_waitcnt lgkmcnt(0)
	s_barrier
	s_setprio 1
	s_waitcnt lgkmcnt(0)
	v_mfma_f32_16x16x32_bf16 v[124:127], v[128:131], v[160:163], v[124:127]
	v_mfma_f32_16x16x32_bf16 v[120:123], v[136:139], v[160:163], v[120:123]
	v_mfma_f32_16x16x32_bf16 v[112:115], v[128:131], v[186:189], v[112:115]
	v_mfma_f32_16x16x32_bf16 v[104:107], v[136:139], v[186:189], v[104:107]
	v_mfma_f32_16x16x32_bf16 v[96:99], v[128:131], v[204:207], v[96:99]
	v_mfma_f32_16x16x32_bf16 v[88:91], v[136:139], v[204:207], v[88:91]
	v_mfma_f32_16x16x32_bf16 v[80:83], v[128:131], v[212:215], v[80:83]
	v_mfma_f32_16x16x32_bf16 v[72:75], v[136:139], v[212:215], v[72:75]
	v_mfma_f32_16x16x32_bf16 v[124:127], v[132:135], v[182:185], v[124:127]
	v_mfma_f32_16x16x32_bf16 v[120:123], v[140:143], v[182:185], v[120:123]
	v_mfma_f32_16x16x32_bf16 v[112:115], v[132:135], v[190:193], v[112:115]
	v_mfma_f32_16x16x32_bf16 v[104:107], v[140:143], v[190:193], v[104:107]
	v_mfma_f32_16x16x32_bf16 v[96:99], v[132:135], v[208:211], v[96:99]
	v_mfma_f32_16x16x32_bf16 v[88:91], v[140:143], v[208:211], v[88:91]
	v_mfma_f32_16x16x32_bf16 v[80:83], v[132:135], v[216:219], v[80:83]
	v_mfma_f32_16x16x32_bf16 v[72:75], v[140:143], v[216:219], v[72:75]
	s_setprio 0
	s_setprio 1
	v_mfma_f32_16x16x32_bf16 v[116:119], v[144:147], v[160:163], v[116:119]
	v_mfma_f32_16x16x32_bf16 v[108:111], v[152:155], v[160:163], v[108:111]
	v_mfma_f32_16x16x32_bf16 v[100:103], v[144:147], v[186:189], v[100:103]
	v_mfma_f32_16x16x32_bf16 v[92:95], v[152:155], v[186:189], v[92:95]
	v_mfma_f32_16x16x32_bf16 v[84:87], v[144:147], v[204:207], v[84:87]
	v_mfma_f32_16x16x32_bf16 v[76:79], v[152:155], v[204:207], v[76:79]
	v_mfma_f32_16x16x32_bf16 v[68:71], v[144:147], v[212:215], v[68:71]
	v_mfma_f32_16x16x32_bf16 v[64:67], v[152:155], v[212:215], v[64:67]
	v_mfma_f32_16x16x32_bf16 v[116:119], v[148:151], v[182:185], v[116:119]
	v_mfma_f32_16x16x32_bf16 v[108:111], v[156:159], v[182:185], v[108:111]
	v_mfma_f32_16x16x32_bf16 v[100:103], v[148:151], v[190:193], v[100:103]
	v_mfma_f32_16x16x32_bf16 v[92:95], v[156:159], v[190:193], v[92:95]
	v_mfma_f32_16x16x32_bf16 v[84:87], v[148:151], v[208:211], v[84:87]
	v_mfma_f32_16x16x32_bf16 v[76:79], v[156:159], v[208:211], v[76:79]
	v_mfma_f32_16x16x32_bf16 v[68:71], v[148:151], v[216:219], v[68:71]
	v_mfma_f32_16x16x32_bf16 v[64:67], v[156:159], v[216:219], v[64:67]
	s_setprio 0
	s_barrier
; #define PG8_STAGE(bufoff, gbase, voff) do { _Pragma("unroll") for (int _i = 0; _i < 2; ++_i) \
;         __builtin_amdgcn_global_load_lds((const unsigned*)((const char*)(gbase) + (voff)[_i]), (PG8_LAS unsigned*)(lds + (bufoff) + ldsw + _i * 8192), 16, 0, 0); } while (0)
; #define PG8_LDA(dst, b, h) do { _Pragma("unroll") for (int m = 0; m < 4; ++m) _Pragma("unroll") for (int k = 0; k < 2; ++k) dst[m][k] = *(const PG8_LAS bf16x8*)(lds + PG8_SA(b, h) + aoff + m * 2048 + k * 1024); } while (0)
; #define PG8_MMA(ai, bj, At, Bt) do { __builtin_amdgcn_s_setprio(1); _Pragma("unroll") for (int m = 0; m < 4; ++m) _Pragma("unroll") for (int n = 0; n < 2; ++n) _Pragma("unroll") for (int k = 0; k < 2; ++k) \
;         acc[ai][bj][m][n] = __builtin_amdgcn_mfma_f32_16x16x32_bf16(Bt[n][k], At[m][k], acc[ai][bj][m][n], 0, 0, 0); __builtin_amdgcn_s_setprio(0); } while (0)
; #define PG8_WAIT_V(n) asm volatile("s_waitcnt vmcnt(" #n ")" ::: "memory")
; #define PG8_WAIT_L(n) asm volatile("s_waitcnt lgkmcnt(" #n ")" ::: "memory")
; #define PG8_BAR __builtin_amdgcn_s_barrier()
; #define PG8_SCHED __builtin_amdgcn_sched_barrier(0)
; template <class Epi, class Sched, bool ALIGN_EPI = false, bool SP2 = false, bool DUAL = false>
; __device__ __forceinline__ void gemm_phase(PG8_LAS unsigned char* lds, const Gemm g, const Sched& S, const Epi& E) {
;     ...
;             PG8_LDA(At, 1, 1); PG8_STAGE(PG8_SB(1, 0), b3, voffB); PG8_STAGE(PG8_SB(1, 1), b3 + hstep, voffB); PG8_STAGE(PG8_SA(1, 0), a3, voffA);
;             PG8_WAIT_V(8); PG8_WAIT_L(0); PG8_BAR; PG8_MMA(1, 0, At, B0); PG8_MMA(1, 1, At, B1); PG8_BAR; PG8_SCHED;
;     ...
;         }
;         if constexpr (ALIGN_EPI) { if (wr == 0) PG8_BAR; }
	s_add_i32 s26, s49, s30
	v_lshl_add_u64 v[220:221], v[220:221], 0, s[18:19]
	s_mov_b32 m0, s26
	ds_read_b128 v[160:163], v203 offset:49152
	ds_read_b128 v[182:185], v203 offset:50176
	ds_read_b128 v[186:189], v203 offset:51200
	ds_read_b128 v[190:193], v203 offset:52224
	ds_read_b128 v[204:207], v203 offset:53248
	ds_read_b128 v[208:211], v203 offset:54272
	ds_read_b128 v[212:215], v203 offset:55296
	ds_read_b128 v[216:219], v203 offset:56320
	global_load_lds_dwordx4 v[220:221], off
	s_add_i32 m0, s26, 0x2000
	s_add_u32 s14, s14, 0x160080
	v_lshl_add_u64 v[220:221], v[222:223], 0, s[18:19]
	s_addc_u32 s15, s15, 0
	s_add_i32 s26, s50, s30
	global_load_lds_dwordx4 v[220:221], off
	v_lshl_add_u64 v[220:221], s[14:15], 0, v[166:167]
	s_mov_b32 m0, s26
	s_nop 0
	global_load_lds_dwordx4 v[220:221], off
	v_lshl_add_u64 v[220:221], s[14:15], 0, v[170:171]
	s_add_i32 m0, s26, 0x2000
	s_nop 0
	global_load_lds_dwordx4 v[220:221], off
	v_lshl_add_u64 v[220:221], v[224:225], 0, s[18:19]
	s_mov_b32 m0, s37
	s_nop 0
	global_load_lds_dwordx4 v[220:221], off
	v_lshl_add_u64 v[220:221], v[226:227], 0, s[18:19]
	s_mov_b32 m0, s38
	s_nop 0
	global_load_lds_dwordx4 v[220:221], off
	s_waitcnt vmcnt(8)
	s_waitcnt lgkmcnt(0)
	s_barrier
	s_setprio 1
	s_waitcnt lgkmcnt(0)
	v_mfma_f32_16x16x32_bf16 v[60:63], v[128:131], v[160:163], v[60:63]
	v_mfma_f32_16x16x32_bf16 v[56:59], v[136:139], v[160:163], v[56:59]
	v_mfma_f32_16x16x32_bf16 v[48:51], v[128:131], v[186:189], v[48:51]
	v_mfma_f32_16x16x32_bf16 v[40:43], v[136:139], v[186:189], v[40:43]
	v_mfma_f32_16x16x32_bf16 v[32:35], v[128:131], v[204:207], v[32:35]
	v_mfma_f32_16x16x32_bf16 v[24:27], v[136:139], v[204:207], v[24:27]
	v_mfma_f32_16x16x32_bf16 v[16:19], v[128:131], v[212:215], v[16:19]
	v_mfma_f32_16x16x32_bf16 v[8:11], v[136:139], v[212:215], v[8:11]
	v_mfma_f32_16x16x32_bf16 v[60:63], v[132:135], v[182:185], v[60:63]
	v_mfma_f32_16x16x32_bf16 v[56:59], v[140:143], v[182:185], v[56:59]
	v_mfma_f32_16x16x32_bf16 v[48:51], v[132:135], v[190:193], v[48:51]
	v_mfma_f32_16x16x32_bf16 v[40:43], v[140:143], v[190:193], v[40:43]
	v_mfma_f32_16x16x32_bf16 v[32:35], v[132:135], v[208:211], v[32:35]
	v_mfma_f32_16x16x32_bf16 v[24:27], v[140:143], v[208:211], v[24:27]
	v_mfma_f32_16x16x32_bf16 v[16:19], v[132:135], v[216:219], v[16:19]
	v_mfma_f32_16x16x32_bf16 v[8:11], v[140:143], v[216:219], v[8:11]
	s_setprio 0
	s_setprio 1
	v_mfma_f32_16x16x32_bf16 v[52:55], v[144:147], v[160:163], v[52:55]
	v_mfma_f32_16x16x32_bf16 v[44:47], v[152:155], v[160:163], v[44:47]
	v_mfma_f32_16x16x32_bf16 v[36:39], v[144:147], v[186:189], v[36:39]
	v_mfma_f32_16x16x32_bf16 v[28:31], v[152:155], v[186:189], v[28:31]
	v_mfma_f32_16x16x32_bf16 v[20:23], v[144:147], v[204:207], v[20:23]
	v_mfma_f32_16x16x32_bf16 v[12:15], v[152:155], v[204:207], v[12:15]
	v_mfma_f32_16x16x32_bf16 v[4:7], v[144:147], v[212:215], v[4:7]
	v_mfma_f32_16x16x32_bf16 v[0:3], v[152:155], v[212:215], v[0:3]
	v_mfma_f32_16x16x32_bf16 v[52:55], v[148:151], v[182:185], v[52:55]
	v_mfma_f32_16x16x32_bf16 v[44:47], v[156:159], v[182:185], v[44:47]
	v_mfma_f32_16x16x32_bf16 v[36:39], v[148:151], v[190:193], v[36:39]
	v_mfma_f32_16x16x32_bf16 v[28:31], v[156:159], v[190:193], v[28:31]
	v_mfma_f32_16x16x32_bf16 v[20:23], v[148:151], v[208:211], v[20:23]
	v_mfma_f32_16x16x32_bf16 v[12:15], v[156:159], v[208:211], v[12:15]
	v_mfma_f32_16x16x32_bf16 v[4:7], v[148:151], v[216:219], v[4:7]
	v_mfma_f32_16x16x32_bf16 v[0:3], v[156:159], v[216:219], v[0:3]
	s_setprio 0
	s_barrier
	s_add_i32 s48, s48, 2
	s_add_u32 s24, s24, 0x100
	s_addc_u32 s25, s25, 0
	s_add_u32 s46, s46, 0x100
	s_addc_u32 s47, s47, 0
	s_cmpk_gt_u32 s48, 0x55
	s_cbranch_scc0 .LBB0_1193
	s_and_b64 vcc, exec, s[20:21]
	s_cbranch_vccz .LBB0_1196
	s_barrier
